# v45
# speedup vs baseline: 1.0573x; 1.0248x over previous
; #define WAIT_V(n) asm volatile("s_waitcnt vmcnt(" #n ")" ::: "memory")
; #define BAR __builtin_amdgcn_s_barrier()
; template <int EPI>
; __device__ __forceinline__ void gemm_tile(const Params& p, const bf16* __restrict__ A, const bf16* __restrict__ Bt, const int K,
;                                           const int nt, const int brow, const int bcol, int pm, int pn) {
;     ...
;   int tid;
;   asm volatile("v_mov_b32 %0, %1" : "=v"(tid) : "v"(threadIdx.x));
;   const int wid = __builtin_amdgcn_readfirstlane(tid >> 6), lane = tid & 63, wr = wid >> 2, wc = wid & 3, fr = lane & 15, fq = lane >> 4;
;   unsigned toff;
;   { int _r, _c; stage_rc(tid * 16, _r, _c); toff = (unsigned)(_r * K + _c) * 2u; }
;   f32x4 acc[2][2][4][2] = {};
;   float pre0 = 0.f, pre1 = 0.f, pre2 = 0.f;
;   if constexpr (EPI == EPI_GU) {
;     const int base = (pm == 65) ? SEQ : 254 * pm - 2;
;     if (tid < 256) pre0 = P_SSQ(p)[max(base + tid, 0)];
;     else if (tid < 384) { const int c = pn * 128 + tid - 256; pre0 = p.w_ffn_conv[c]; pre1 = p.w_ffn_conv[DFF + c]; pre2 = p.w_ffn_conv[2 * DFF + c]; }
;   }
;   bf16x8 At[4][2], B0[2][2], B1[2][2];
;   STAGE(SB(0, 0), Bt, bcol, 0); STAGE(SA(0, 0), A, brow, 0);
;   STAGE(SB(0, 1), Bt, bcol + HALF, 0); STAGE(SA(0, 1), A, brow + HALF, 0);
;   if (wr == 1) BAR;
;   WAIT_V(4); BAR;
;   STAGE(SB(1, 0), Bt, bcol, 1); STAGE(SA(1, 0), A, brow, 1); STAGE(SB(1, 1), Bt, bcol + HALF, 1);
;   WAIT_V(6); BAR;
.LBB0_414:
	s_add_u32 s36, s46, s36
	v_add_u32_e32 v151, s91, v4
	s_addc_u32 s37, s47, s37
	v_lshl_add_u64 v[6:7], s[36:37], 0, v[132:133]
	v_readfirstlane_b32 s31, v151
	s_add_u32 s40, s46, s40
	v_lshl_add_u64 v[6:7], v[6:7], 0, s[26:27]
	s_mov_b32 m0, s31
	s_addc_u32 s41, s47, s41
	v_add_u32_e32 v152, 0x2000, v151
	s_waitcnt vmcnt(4)
	s_barrier
	global_load_lds_dwordx4 v[6:7], off
	v_lshl_add_u64 v[6:7], s[40:41], 0, v[132:133]
	v_readfirstlane_b32 s31, v152
	s_add_u32 s40, s60, s38
	v_lshl_add_u64 v[6:7], v[6:7], 0, s[26:27]
	s_mov_b32 m0, s31
	s_addc_u32 s41, s61, s39
	v_add_u32_e32 v153, 0x8000, v138
	global_load_lds_dwordx4 v[6:7], off
	v_lshl_add_u64 v[6:7], s[40:41], 0, v[132:133]
	v_readfirstlane_b32 s31, v153
	s_add_u32 s40, s60, s42
	v_lshl_add_u64 v[6:7], v[6:7], 0, s[26:27]
	s_mov_b32 m0, s31
	s_addc_u32 s41, s61, s43
	global_load_lds_dwordx4 v[6:7], off
	v_lshl_add_u64 v[6:7], s[40:41], 0, v[132:133]
	v_add_u32_e32 v154, 0xa000, v138
	s_add_u32 s40, s46, s62
	v_readfirstlane_b32 s31, v154
	v_add_u32_e32 v155, s92, v4
	s_addc_u32 s41, s47, s63
	v_lshl_add_u64 v[6:7], v[6:7], 0, s[26:27]
	s_mov_b32 m0, s31
	v_lshl_add_u64 v[4:5], s[40:41], 0, v[132:133]
	v_readfirstlane_b32 s31, v155
	s_add_u32 s40, s46, s86
	global_load_lds_dwordx4 v[6:7], off
	v_lshl_add_u64 v[4:5], v[4:5], 0, s[26:27]
	s_mov_b32 m0, s31
	s_addc_u32 s41, s47, s87
	v_add_u32_e32 v157, 0x2000, v155
	global_load_lds_dwordx4 v[4:5], off
	v_lshl_add_u64 v[4:5], s[40:41], 0, v[132:133]
	v_readfirstlane_b32 s31, v157
	v_lshl_add_u64 v[4:5], v[4:5], 0, s[26:27]
	s_mov_b32 m0, s31
	v_and_b32_e32 v8, 15, v1
	global_load_lds_dwordx4 v[4:5], off
	v_and_b32_e32 v9, 48, v1
	v_lshlrev_b32_e32 v5, 2, v1
	s_lshl_b32 s40, s9, 13
	v_lshlrev_b32_e32 v1, 6, v1
	s_movk_i32 s9, 0x3c0
	v_lshlrev_b32_e32 v4, 6, v8
	v_and_b32_e32 v5, 32, v5
	v_and_or_b32 v1, v1, s9, v9
	v_bitop3_b32 v4, v4, v5, v9 bitop3:0x36
	v_xad_u32 v1, v1, v5, 16
	v_lshlrev_b32_e32 v5, 15, v0
	v_and_b32_e32 v5, 0xffff0000, v5
	s_lshl_b32 s31, s5, 6
	v_lshl_add_u32 v2, v2, 12, v5
	v_and_b32_e32 v0, 1, v0
	s_waitcnt vmcnt(6)
	s_and_b32 s31, s31, 0x3000
	s_or_b32 s41, s40, 0x800
	s_or_b32 s42, s40, 0x1000
	s_or_b32 s43, s40, 0x1800
	v_lshl_or_b32 v0, v0, 6, v2
	v_add_u32_e32 v6, s88, v4
	v_add_u32_e32 v7, s89, v4
	v_add_u32_e32 v8, s91, v4
	v_add_u32_e32 v10, s92, v4
	v_add_u32_e32 v4, 16, v4
	v_lshl_add_u32 v128, v3, 1, v0
	s_add_u32 s38, s46, s38
	v_mov_b32_e32 v0, 0
	v_mov_b32_e32 v129, v133
	s_addc_u32 s39, s47, s39
	s_mov_b32 s9, -2
	v_add_u32_e32 v160, s31, v6
	v_add_u32_e32 v136, s40, v4
	v_add_u32_e32 v135, s41, v1
	v_add_u32_e32 v131, s42, v1
	v_add_u32_e32 v130, s43, v1
	v_add_u32_e32 v159, 0xc000, v138
	v_add_u32_e32 v158, 0xe000, v138
	v_add_u32_e32 v156, s31, v7
	v_add_u32_e32 v149, s31, v8
	v_add_u32_e32 v139, s31, v10
	v_mov_b32_e32 v1, v0
	v_mov_b32_e32 v2, v0
	v_mov_b32_e32 v3, v0
	v_mov_b32_e32 v4, v0
	v_mov_b32_e32 v5, v0
	v_mov_b32_e32 v6, v0
	v_mov_b32_e32 v7, v0
	v_mov_b32_e32 v8, v0
	v_mov_b32_e32 v9, v0
	v_mov_b32_e32 v10, v0
	v_mov_b32_e32 v11, v0
	v_mov_b32_e32 v12, v0
	v_mov_b32_e32 v13, v0
	v_mov_b32_e32 v14, v0
	v_mov_b32_e32 v15, v0
	v_mov_b32_e32 v16, v0
	v_mov_b32_e32 v17, v0
	v_mov_b32_e32 v18, v0
	v_mov_b32_e32 v19, v0
	v_mov_b32_e32 v20, v0
	v_mov_b32_e32 v21, v0
	v_mov_b32_e32 v22, v0
	v_mov_b32_e32 v23, v0
	v_mov_b32_e32 v24, v0
	v_mov_b32_e32 v25, v0
	v_mov_b32_e32 v26, v0
	v_mov_b32_e32 v27, v0
	v_mov_b32_e32 v28, v0
	v_mov_b32_e32 v29, v0
	v_mov_b32_e32 v30, v0
	v_mov_b32_e32 v31, v0
	v_mov_b32_e32 v32, v0
	v_mov_b32_e32 v33, v0
	v_mov_b32_e32 v34, v0
	v_mov_b32_e32 v35, v0
	v_mov_b32_e32 v36, v0
	v_mov_b32_e32 v37, v0
	v_mov_b32_e32 v38, v0
	v_mov_b32_e32 v39, v0
	v_mov_b32_e32 v40, v0
	v_mov_b32_e32 v41, v0
	v_mov_b32_e32 v42, v0
	v_mov_b32_e32 v43, v0
	v_mov_b32_e32 v44, v0
	v_mov_b32_e32 v45, v0
	v_mov_b32_e32 v46, v0
	v_mov_b32_e32 v47, v0
	v_mov_b32_e32 v48, v0
	v_mov_b32_e32 v49, v0
	v_mov_b32_e32 v50, v0
	v_mov_b32_e32 v51, v0
	v_mov_b32_e32 v52, v0
	v_mov_b32_e32 v53, v0
	v_mov_b32_e32 v54, v0
	v_mov_b32_e32 v55, v0
	v_mov_b32_e32 v56, v0
	v_mov_b32_e32 v57, v0
	v_mov_b32_e32 v58, v0
	v_mov_b32_e32 v59, v0
	v_mov_b32_e32 v60, v0
	v_mov_b32_e32 v61, v0
	v_mov_b32_e32 v62, v0
	v_mov_b32_e32 v63, v0
	v_mov_b32_e32 v64, v0
	v_mov_b32_e32 v65, v0
	v_mov_b32_e32 v66, v0
	v_mov_b32_e32 v67, v0
	v_mov_b32_e32 v68, v0
	v_mov_b32_e32 v69, v0
	v_mov_b32_e32 v70, v0
	v_mov_b32_e32 v71, v0
	v_mov_b32_e32 v72, v0
	v_mov_b32_e32 v73, v0
	v_mov_b32_e32 v74, v0
	v_mov_b32_e32 v75, v0
	v_mov_b32_e32 v76, v0
	v_mov_b32_e32 v77, v0
	v_mov_b32_e32 v78, v0
	v_mov_b32_e32 v79, v0
	v_mov_b32_e32 v80, v0
	v_mov_b32_e32 v81, v0
	v_mov_b32_e32 v82, v0
	v_mov_b32_e32 v83, v0
	v_mov_b32_e32 v84, v0
	v_mov_b32_e32 v85, v0
	v_mov_b32_e32 v86, v0
	v_mov_b32_e32 v87, v0
	v_mov_b32_e32 v88, v0
	v_mov_b32_e32 v89, v0
	v_mov_b32_e32 v90, v0
	v_mov_b32_e32 v91, v0
	v_mov_b32_e32 v92, v0
	v_mov_b32_e32 v93, v0
	v_mov_b32_e32 v94, v0
	v_mov_b32_e32 v95, v0
	v_mov_b32_e32 v96, v0
	v_mov_b32_e32 v97, v0
	v_mov_b32_e32 v98, v0
	v_mov_b32_e32 v99, v0
	v_mov_b32_e32 v100, v0
	v_mov_b32_e32 v101, v0
	v_mov_b32_e32 v102, v0
	v_mov_b32_e32 v103, v0
	v_mov_b32_e32 v104, v0
	v_mov_b32_e32 v105, v0
	v_mov_b32_e32 v106, v0
	v_mov_b32_e32 v107, v0
	v_mov_b32_e32 v108, v0
	v_mov_b32_e32 v109, v0
	v_mov_b32_e32 v110, v0
	v_mov_b32_e32 v111, v0
	v_mov_b32_e32 v112, v0
	v_mov_b32_e32 v113, v0
	v_mov_b32_e32 v114, v0
	v_mov_b32_e32 v115, v0
	v_mov_b32_e32 v116, v0
	v_mov_b32_e32 v117, v0
	v_mov_b32_e32 v118, v0
	v_mov_b32_e32 v119, v0
	v_mov_b32_e32 v120, v0
	v_mov_b32_e32 v121, v0
	v_mov_b32_e32 v122, v0
	v_mov_b32_e32 v123, v0
	v_mov_b32_e32 v124, v0
	v_mov_b32_e32 v125, v0
	v_mov_b32_e32 v126, v0
	v_mov_b32_e32 v127, v0
	s_barrier
	v_lshl_add_u64 v[228:229], s[38:39], 0, v[128:129]
	s_mov_b64 s[40:41], 0x6282080
	v_lshl_add_u64 v[246:247], v[228:229], 0, s[40:41]
	s_mov_b64 s[40:41], 0x62c2080
	v_lshl_add_u64 v[244:245], v[228:229], 0, s[40:41]
	v_readfirstlane_b32 s99, v159
	v_readfirstlane_b32 s98, v158
	v_readfirstlane_b32 s100, v148
	v_readfirstlane_b32 s101, v150
; #define WAIT_L(n) asm volatile("s_waitcnt lgkmcnt(" #n ")" ::: "memory")
; #define BAR __builtin_amdgcn_s_barrier()
; #define SCHED __builtin_amdgcn_sched_barrier(0)
; template <int EPI>
; __device__ __forceinline__ void gemm_tile(const Params& p, const bf16* __restrict__ A, const bf16* __restrict__ Bt, const int K,
;                                           const int nt, const int brow, const int bcol, int pm, int pn) {
;     ...
;     LDB(B0, 0, 0); SCHED; LDA(At, 0, 0); STAGE(SA(1, 1), A, brow + HALF, t + 1);
;     WAIT_L(8); BAR; WAIT_L(0); MMA(0, 0, At, B0); BAR; SCHED;
;     LDB(B1, 0, 1); STAGE(SB(0, 0), Bt, bcol, t + 2);
;     BAR; WAIT_L(0); MMA(0, 1, At, B1); BAR;
;     LDA(At, 0, 1); STAGE(SA(0, 0), A, brow, t + 2);
;     BAR; WAIT_L(0); MMA(1, 0, At, B0); BAR; SCHED;
.LBB0_415:
	ds_read_b128 v[162:165], v160
	ds_read_b128 v[166:169], v160 offset:1024
	ds_read_b128 v[170:173], v160 offset:2048
	ds_read_b128 v[174:177], v160 offset:3072
	s_mov_b32 m0, s99
	ds_read_b128 v[178:181], v136
	ds_read_b128 v[182:185], v136 offset:1024
	ds_read_b128 v[186:189], v135
	ds_read_b128 v[190:193], v135 offset:1024
	ds_read_b128 v[194:197], v131
	ds_read_b128 v[198:201], v131 offset:1024
	ds_read_b128 v[202:205], v130
	ds_read_b128 v[208:211], v130 offset:1024
	global_load_lds_dwordx4 v[246:247], off
	s_mov_b32 m0, s98
	s_nop 0
	global_load_lds_dwordx4 v[244:245], off
	s_waitcnt lgkmcnt(8)
	s_setprio 1
	s_barrier
	s_waitcnt lgkmcnt(0)
	v_mfma_f32_16x16x32_bf16 v[124:127], v[178:181], v[162:165], v[124:127]
	v_mfma_f32_16x16x32_bf16 v[120:123], v[178:181], v[170:173], v[120:123]
	v_mfma_f32_16x16x32_bf16 v[116:119], v[186:189], v[162:165], v[116:119]
	v_mfma_f32_16x16x32_bf16 v[112:115], v[186:189], v[170:173], v[112:115]
	v_mfma_f32_16x16x32_bf16 v[108:111], v[194:197], v[162:165], v[108:111]
	v_mfma_f32_16x16x32_bf16 v[104:107], v[194:197], v[170:173], v[104:107]
	v_mfma_f32_16x16x32_bf16 v[100:103], v[202:205], v[162:165], v[100:103]
	v_mfma_f32_16x16x32_bf16 v[96:99], v[202:205], v[170:173], v[96:99]
	v_mfma_f32_16x16x32_bf16 v[124:127], v[182:185], v[166:169], v[124:127]
	v_mfma_f32_16x16x32_bf16 v[120:123], v[182:185], v[174:177], v[120:123]
	v_mfma_f32_16x16x32_bf16 v[116:119], v[190:193], v[166:169], v[116:119]
	v_mfma_f32_16x16x32_bf16 v[112:115], v[190:193], v[174:177], v[112:115]
	v_mfma_f32_16x16x32_bf16 v[108:111], v[198:201], v[166:169], v[108:111]
	v_mfma_f32_16x16x32_bf16 v[104:107], v[198:201], v[174:177], v[104:107]
	v_mfma_f32_16x16x32_bf16 v[100:103], v[208:211], v[166:169], v[100:103]
	v_mfma_f32_16x16x32_bf16 v[96:99], v[208:211], v[174:177], v[96:99]
	s_barrier
	s_setprio 0
	v_lshl_add_u64 v[230:231], s[36:37], 0, v[128:129]
	s_mov_b64 s[40:41], 0x100
	v_readfirstlane_b32 s31, v134
	v_lshl_add_u64 v[232:233], v[230:231], 0, s[40:41]
	s_mov_b32 m0, s31
	s_mov_b64 s[40:41], 0x40100
	v_readfirstlane_b32 s31, v137
	ds_read_b128 v[212:215], v156
	ds_read_b128 v[216:219], v156 offset:1024
	ds_read_b128 v[220:223], v156 offset:2048
	ds_read_b128 v[224:227], v156 offset:3072
	global_load_lds_dwordx4 v[232:233], off
	v_lshl_add_u64 v[232:233], v[230:231], 0, s[40:41]
	s_mov_b32 m0, s31
	s_nop 0
	global_load_lds_dwordx4 v[232:233], off
	s_mov_b64 s[40:41], 0x6202100
	v_readfirstlane_b32 s31, v138
	v_lshl_add_u64 v[232:233], v[228:229], 0, s[40:41]
	s_mov_b32 m0, s31
	s_mov_b64 s[40:41], 0x6242100
	v_readfirstlane_b32 s31, v140
	s_setprio 1
	s_barrier
	s_waitcnt lgkmcnt(0)
	v_mfma_f32_16x16x32_bf16 v[92:95], v[178:181], v[212:215], v[92:95]
	v_mfma_f32_16x16x32_bf16 v[88:91], v[178:181], v[220:223], v[88:91]
	v_mfma_f32_16x16x32_bf16 v[84:87], v[186:189], v[212:215], v[84:87]
	v_mfma_f32_16x16x32_bf16 v[80:83], v[186:189], v[220:223], v[80:83]
	v_mfma_f32_16x16x32_bf16 v[76:79], v[194:197], v[212:215], v[76:79]
	v_mfma_f32_16x16x32_bf16 v[72:75], v[194:197], v[220:223], v[72:75]
	v_mfma_f32_16x16x32_bf16 v[68:71], v[202:205], v[212:215], v[68:71]
	v_mfma_f32_16x16x32_bf16 v[64:67], v[202:205], v[220:223], v[64:67]
	v_mfma_f32_16x16x32_bf16 v[92:95], v[182:185], v[216:219], v[92:95]
	v_mfma_f32_16x16x32_bf16 v[88:91], v[182:185], v[224:227], v[88:91]
	v_mfma_f32_16x16x32_bf16 v[84:87], v[190:193], v[216:219], v[84:87]
	v_mfma_f32_16x16x32_bf16 v[80:83], v[190:193], v[224:227], v[80:83]
	v_mfma_f32_16x16x32_bf16 v[76:79], v[198:201], v[216:219], v[76:79]
	v_mfma_f32_16x16x32_bf16 v[72:75], v[198:201], v[224:227], v[72:75]
	v_mfma_f32_16x16x32_bf16 v[68:71], v[208:211], v[216:219], v[68:71]
	v_mfma_f32_16x16x32_bf16 v[64:67], v[208:211], v[224:227], v[64:67]
	s_barrier
	s_setprio 0
	ds_read_b128 v[178:181], v136 offset:16384
	ds_read_b128 v[182:185], v136 offset:17408
	ds_read_b128 v[186:189], v135 offset:16384
	ds_read_b128 v[190:193], v135 offset:17408
	ds_read_b128 v[194:197], v131 offset:16384
	ds_read_b128 v[198:201], v131 offset:17408
	ds_read_b128 v[202:205], v130 offset:16384
	ds_read_b128 v[208:211], v130 offset:17408
	global_load_lds_dwordx4 v[232:233], off
	v_lshl_add_u64 v[232:233], v[228:229], 0, s[40:41]
	s_mov_b32 m0, s31
	s_nop 0
	global_load_lds_dwordx4 v[232:233], off
	s_setprio 1
	s_barrier
	s_waitcnt lgkmcnt(0)
	v_mfma_f32_16x16x32_bf16 v[60:63], v[178:181], v[162:165], v[60:63]
	v_mfma_f32_16x16x32_bf16 v[56:59], v[178:181], v[170:173], v[56:59]
	v_mfma_f32_16x16x32_bf16 v[52:55], v[186:189], v[162:165], v[52:55]
	v_mfma_f32_16x16x32_bf16 v[48:51], v[186:189], v[170:173], v[48:51]
	v_mfma_f32_16x16x32_bf16 v[44:47], v[194:197], v[162:165], v[44:47]
	v_mfma_f32_16x16x32_bf16 v[40:43], v[194:197], v[170:173], v[40:43]
	v_mfma_f32_16x16x32_bf16 v[36:39], v[202:205], v[162:165], v[36:39]
	v_mfma_f32_16x16x32_bf16 v[32:35], v[202:205], v[170:173], v[32:35]
	v_mfma_f32_16x16x32_bf16 v[60:63], v[182:185], v[166:169], v[60:63]
	v_mfma_f32_16x16x32_bf16 v[56:59], v[182:185], v[174:177], v[56:59]
	v_mfma_f32_16x16x32_bf16 v[52:55], v[190:193], v[166:169], v[52:55]
	v_mfma_f32_16x16x32_bf16 v[48:51], v[190:193], v[174:177], v[48:51]
	v_mfma_f32_16x16x32_bf16 v[44:47], v[198:201], v[166:169], v[44:47]
	v_mfma_f32_16x16x32_bf16 v[40:43], v[198:201], v[174:177], v[40:43]
	v_mfma_f32_16x16x32_bf16 v[36:39], v[208:211], v[166:169], v[36:39]
	v_mfma_f32_16x16x32_bf16 v[32:35], v[208:211], v[174:177], v[32:35]
	s_barrier
; #define WAIT_V(n) asm volatile("s_waitcnt vmcnt(" #n ")" ::: "memory")
; #define WAIT_L(n) asm volatile("s_waitcnt lgkmcnt(" #n ")" ::: "memory")
; #define BAR __builtin_amdgcn_s_barrier()
; #define SCHED __builtin_amdgcn_sched_barrier(0)
; template <int EPI>
; __device__ __forceinline__ void gemm_tile(const Params& p, const bf16* __restrict__ A, const bf16* __restrict__ Bt, const int K,
;                                           const int nt, const int brow, const int bcol, int pm, int pn) {
;     ...
;   for (int t = 0; t < nt - 2; t += 2) {
;     LDB(B0, 0, 0); SCHED; LDA(At, 0, 0); STAGE(SA(1, 1), A, brow + HALF, t + 1);
;     WAIT_L(8); BAR; WAIT_L(0); MMA(0, 0, At, B0); BAR; SCHED;
;     LDB(B1, 0, 1); STAGE(SB(0, 0), Bt, bcol, t + 2);
;     BAR; WAIT_L(0); MMA(0, 1, At, B1); BAR;
;     LDA(At, 0, 1); STAGE(SA(0, 0), A, brow, t + 2);
;     BAR; WAIT_L(0); MMA(1, 0, At, B0); BAR; SCHED;
;     STAGE(SB(0, 1), Bt, bcol + HALF, t + 2);
;     WAIT_V(6); BAR; MMA(1, 1, At, B1); BAR;
;     LDB(B0, 1, 0); SCHED; LDA(At, 1, 0); STAGE(SA(0, 1), A, brow + HALF, t + 2);
;     WAIT_L(8); BAR; WAIT_L(0); MMA(0, 0, At, B0); BAR; SCHED;
;     LDB(B1, 1, 1); STAGE(SB(1, 0), Bt, bcol, t + 3);
;     BAR; WAIT_L(0); MMA(0, 1, At, B1); BAR;
;     LDA(At, 1, 1); STAGE(SA(1, 0), A, brow, t + 3);
;     BAR; WAIT_L(0); MMA(1, 0, At, B0); BAR; SCHED;
;     STAGE(SB(1, 1), Bt, bcol + HALF, t + 3);
;     WAIT_V(6); BAR; MMA(1, 1, At, B1); BAR;
;   }
	s_setprio 0
	s_add_i32 s9, s9, 2
	s_add_u32 s38, s38, 0x100
	s_addc_u32 s39, s39, 0
	s_add_u32 s36, s36, 0x100
	s_addc_u32 s37, s37, 0
	s_mov_b64 s[40:41], 0x80100
	v_readfirstlane_b32 s31, v141
	v_lshl_add_u64 v[162:163], v[230:231], 0, s[40:41]
	s_mov_b32 m0, s31
	s_mov_b64 s[40:41], 0xc0100
	v_readfirstlane_b32 s31, v147
	global_load_lds_dwordx4 v[162:163], off
	v_lshl_add_u64 v[162:163], v[230:231], 0, s[40:41]
	s_mov_b32 m0, s31
	s_nop 0
	global_load_lds_dwordx4 v[162:163], off
	s_mov_b64 s[40:41], 0x6282100
	v_lshl_add_u64 v[248:249], v[228:229], 0, s[40:41]
	s_mov_b64 s[40:41], 0x62c2100
	v_lshl_add_u64 v[250:251], v[228:229], 0, s[40:41]
	s_waitcnt vmcnt(6)
	s_setprio 1
	s_barrier
	v_mfma_f32_16x16x32_bf16 v[28:31], v[178:181], v[212:215], v[28:31]
	v_mfma_f32_16x16x32_bf16 v[24:27], v[178:181], v[220:223], v[24:27]
	v_mfma_f32_16x16x32_bf16 v[20:23], v[186:189], v[212:215], v[20:23]
	v_mfma_f32_16x16x32_bf16 v[16:19], v[186:189], v[220:223], v[16:19]
	v_mfma_f32_16x16x32_bf16 v[12:15], v[194:197], v[212:215], v[12:15]
	v_mfma_f32_16x16x32_bf16 v[8:11], v[194:197], v[220:223], v[8:11]
	v_mfma_f32_16x16x32_bf16 v[4:7], v[202:205], v[212:215], v[4:7]
	v_mfma_f32_16x16x32_bf16 v[0:3], v[202:205], v[220:223], v[0:3]
	v_mfma_f32_16x16x32_bf16 v[28:31], v[182:185], v[216:219], v[28:31]
	v_mfma_f32_16x16x32_bf16 v[24:27], v[182:185], v[224:227], v[24:27]
	v_mfma_f32_16x16x32_bf16 v[20:23], v[190:193], v[216:219], v[20:23]
	v_mfma_f32_16x16x32_bf16 v[16:19], v[190:193], v[224:227], v[16:19]
	v_mfma_f32_16x16x32_bf16 v[12:15], v[198:201], v[216:219], v[12:15]
	v_mfma_f32_16x16x32_bf16 v[8:11], v[198:201], v[224:227], v[8:11]
	v_mfma_f32_16x16x32_bf16 v[4:7], v[208:211], v[216:219], v[4:7]
	v_mfma_f32_16x16x32_bf16 v[0:3], v[208:211], v[224:227], v[0:3]
	s_barrier
	s_setprio 0
	ds_read_b128 v[162:165], v149
	ds_read_b128 v[166:169], v149 offset:1024
	ds_read_b128 v[170:173], v149 offset:2048
	ds_read_b128 v[174:177], v149 offset:3072
	s_mov_b32 m0, s100
	ds_read_b128 v[178:181], v136 offset:32768
	ds_read_b128 v[182:185], v136 offset:33792
	ds_read_b128 v[186:189], v135 offset:32768
	ds_read_b128 v[190:193], v135 offset:33792
	ds_read_b128 v[194:197], v131 offset:32768
	ds_read_b128 v[198:201], v131 offset:33792
	ds_read_b128 v[202:205], v130 offset:32768
	ds_read_b128 v[208:211], v130 offset:33792
	global_load_lds_dwordx4 v[248:249], off
	s_mov_b32 m0, s101
	s_nop 0
	global_load_lds_dwordx4 v[250:251], off
	s_waitcnt lgkmcnt(8)
	s_setprio 1
	s_barrier
	s_waitcnt lgkmcnt(0)
	v_mfma_f32_16x16x32_bf16 v[124:127], v[178:181], v[162:165], v[124:127]
	v_mfma_f32_16x16x32_bf16 v[120:123], v[178:181], v[170:173], v[120:123]
	v_mfma_f32_16x16x32_bf16 v[116:119], v[186:189], v[162:165], v[116:119]
	v_mfma_f32_16x16x32_bf16 v[112:115], v[186:189], v[170:173], v[112:115]
	v_mfma_f32_16x16x32_bf16 v[108:111], v[194:197], v[162:165], v[108:111]
	v_mfma_f32_16x16x32_bf16 v[104:107], v[194:197], v[170:173], v[104:107]
	v_mfma_f32_16x16x32_bf16 v[100:103], v[202:205], v[162:165], v[100:103]
	v_mfma_f32_16x16x32_bf16 v[96:99], v[202:205], v[170:173], v[96:99]
	v_mfma_f32_16x16x32_bf16 v[124:127], v[182:185], v[166:169], v[124:127]
	v_mfma_f32_16x16x32_bf16 v[120:123], v[182:185], v[174:177], v[120:123]
	v_mfma_f32_16x16x32_bf16 v[116:119], v[190:193], v[166:169], v[116:119]
	v_mfma_f32_16x16x32_bf16 v[112:115], v[190:193], v[174:177], v[112:115]
	v_mfma_f32_16x16x32_bf16 v[108:111], v[198:201], v[166:169], v[108:111]
	v_mfma_f32_16x16x32_bf16 v[104:107], v[198:201], v[174:177], v[104:107]
	v_mfma_f32_16x16x32_bf16 v[100:103], v[208:211], v[166:169], v[100:103]
	v_mfma_f32_16x16x32_bf16 v[96:99], v[208:211], v[174:177], v[96:99]
	s_barrier
	s_setprio 0
	s_mov_b64 s[40:41], 0x180
	v_readfirstlane_b32 s31, v151
	v_lshl_add_u64 v[232:233], v[230:231], 0, s[40:41]
	s_mov_b32 m0, s31
	s_mov_b64 s[40:41], 0x40180
	v_readfirstlane_b32 s31, v152
	ds_read_b128 v[212:215], v139
	ds_read_b128 v[216:219], v139 offset:1024
	ds_read_b128 v[220:223], v139 offset:2048
	ds_read_b128 v[224:227], v139 offset:3072
	global_load_lds_dwordx4 v[232:233], off
	v_lshl_add_u64 v[232:233], v[230:231], 0, s[40:41]
	s_mov_b32 m0, s31
	s_nop 0
	global_load_lds_dwordx4 v[232:233], off
	s_mov_b64 s[40:41], 0x6202180
	v_readfirstlane_b32 s31, v153
	v_lshl_add_u64 v[232:233], v[228:229], 0, s[40:41]
	s_mov_b32 m0, s31
	s_mov_b64 s[40:41], 0x6242180
	v_readfirstlane_b32 s31, v154
	s_setprio 1
	s_barrier
	s_waitcnt lgkmcnt(0)
	v_mfma_f32_16x16x32_bf16 v[92:95], v[178:181], v[212:215], v[92:95]
	v_mfma_f32_16x16x32_bf16 v[88:91], v[178:181], v[220:223], v[88:91]
	v_mfma_f32_16x16x32_bf16 v[84:87], v[186:189], v[212:215], v[84:87]
	v_mfma_f32_16x16x32_bf16 v[80:83], v[186:189], v[220:223], v[80:83]
	v_mfma_f32_16x16x32_bf16 v[76:79], v[194:197], v[212:215], v[76:79]
	v_mfma_f32_16x16x32_bf16 v[72:75], v[194:197], v[220:223], v[72:75]
	v_mfma_f32_16x16x32_bf16 v[68:71], v[202:205], v[212:215], v[68:71]
	v_mfma_f32_16x16x32_bf16 v[64:67], v[202:205], v[220:223], v[64:67]
	v_mfma_f32_16x16x32_bf16 v[92:95], v[182:185], v[216:219], v[92:95]
	v_mfma_f32_16x16x32_bf16 v[88:91], v[182:185], v[224:227], v[88:91]
	v_mfma_f32_16x16x32_bf16 v[84:87], v[190:193], v[216:219], v[84:87]
	v_mfma_f32_16x16x32_bf16 v[80:83], v[190:193], v[224:227], v[80:83]
	v_mfma_f32_16x16x32_bf16 v[76:79], v[198:201], v[216:219], v[76:79]
	v_mfma_f32_16x16x32_bf16 v[72:75], v[198:201], v[224:227], v[72:75]
	v_mfma_f32_16x16x32_bf16 v[68:71], v[208:211], v[216:219], v[68:71]
	v_mfma_f32_16x16x32_bf16 v[64:67], v[208:211], v[224:227], v[64:67]
	s_barrier
; #define WAIT_V(n) asm volatile("s_waitcnt vmcnt(" #n ")" ::: "memory")
; #define WAIT_L(n) asm volatile("s_waitcnt lgkmcnt(" #n ")" ::: "memory")
; #define BAR __builtin_amdgcn_s_barrier()
; #define SCHED __builtin_amdgcn_sched_barrier(0)
; template <int EPI>
; __device__ __forceinline__ void gemm_tile(const Params& p, const bf16* __restrict__ A, const bf16* __restrict__ Bt, const int K,
;                                           const int nt, const int brow, const int bcol, int pm, int pn) {
;     ...
;     BAR; WAIT_L(0); MMA(1, 0, At, B0); BAR; SCHED;
;     STAGE(SB(1, 1), Bt, bcol + HALF, t + 3);
;     WAIT_V(6); BAR; MMA(1, 1, At, B1); BAR;
;   }
;   { LDB(B0, 0, 0); LDA(At, 0, 0); STAGE(SA(1, 1), A, brow + HALF, nt - 1);
;     BAR; WAIT_L(0); MMA(0, 0, At, B0); BAR;
	s_setprio 0
	ds_read_b128 v[178:181], v136 offset:49152
	ds_read_b128 v[182:185], v136 offset:50176
	ds_read_b128 v[186:189], v135 offset:49152
	ds_read_b128 v[190:193], v135 offset:50176
	ds_read_b128 v[194:197], v131 offset:49152
	ds_read_b128 v[198:201], v131 offset:50176
	ds_read_b128 v[202:205], v130 offset:49152
	ds_read_b128 v[208:211], v130 offset:50176
	global_load_lds_dwordx4 v[232:233], off
	v_lshl_add_u64 v[228:229], v[228:229], 0, s[40:41]
	s_mov_b32 m0, s31
	s_nop 0
	global_load_lds_dwordx4 v[228:229], off
	s_setprio 1
	s_barrier
	s_waitcnt lgkmcnt(0)
	v_mfma_f32_16x16x32_bf16 v[60:63], v[178:181], v[162:165], v[60:63]
	v_mfma_f32_16x16x32_bf16 v[56:59], v[178:181], v[170:173], v[56:59]
	v_mfma_f32_16x16x32_bf16 v[52:55], v[186:189], v[162:165], v[52:55]
	v_mfma_f32_16x16x32_bf16 v[48:51], v[186:189], v[170:173], v[48:51]
	v_mfma_f32_16x16x32_bf16 v[44:47], v[194:197], v[162:165], v[44:47]
	v_mfma_f32_16x16x32_bf16 v[40:43], v[194:197], v[170:173], v[40:43]
	v_mfma_f32_16x16x32_bf16 v[36:39], v[202:205], v[162:165], v[36:39]
	v_mfma_f32_16x16x32_bf16 v[32:35], v[202:205], v[170:173], v[32:35]
	v_mfma_f32_16x16x32_bf16 v[60:63], v[182:185], v[166:169], v[60:63]
	v_mfma_f32_16x16x32_bf16 v[56:59], v[182:185], v[174:177], v[56:59]
	v_mfma_f32_16x16x32_bf16 v[52:55], v[190:193], v[166:169], v[52:55]
	v_mfma_f32_16x16x32_bf16 v[48:51], v[190:193], v[174:177], v[48:51]
	v_mfma_f32_16x16x32_bf16 v[44:47], v[198:201], v[166:169], v[44:47]
	v_mfma_f32_16x16x32_bf16 v[40:43], v[198:201], v[174:177], v[40:43]
	v_mfma_f32_16x16x32_bf16 v[36:39], v[208:211], v[166:169], v[36:39]
	v_mfma_f32_16x16x32_bf16 v[32:35], v[208:211], v[174:177], v[32:35]
	s_barrier
	s_setprio 0
	s_mov_b64 s[40:41], 0x80180
	v_readfirstlane_b32 s31, v155
	v_lshl_add_u64 v[162:163], v[230:231], 0, s[40:41]
	s_mov_b32 m0, s31
	s_mov_b64 s[40:41], 0xc0180
	v_readfirstlane_b32 s31, v157
	global_load_lds_dwordx4 v[162:163], off
	v_lshl_add_u64 v[162:163], v[230:231], 0, s[40:41]
	s_mov_b32 m0, s31
	s_nop 0
	global_load_lds_dwordx4 v[162:163], off
	v_lshl_add_u64 v[228:229], s[38:39], 0, v[128:129]
	s_mov_b64 s[40:41], 0x6282080
	v_lshl_add_u64 v[246:247], v[228:229], 0, s[40:41]
	s_mov_b64 s[40:41], 0x62c2080
	v_lshl_add_u64 v[244:245], v[228:229], 0, s[40:41]
	s_waitcnt vmcnt(6)
	s_setprio 1
	s_barrier
	v_mfma_f32_16x16x32_bf16 v[28:31], v[178:181], v[212:215], v[28:31]
	v_mfma_f32_16x16x32_bf16 v[24:27], v[178:181], v[220:223], v[24:27]
	v_mfma_f32_16x16x32_bf16 v[20:23], v[186:189], v[212:215], v[20:23]
	v_mfma_f32_16x16x32_bf16 v[16:19], v[186:189], v[220:223], v[16:19]
	v_mfma_f32_16x16x32_bf16 v[12:15], v[194:197], v[212:215], v[12:15]
	v_mfma_f32_16x16x32_bf16 v[8:11], v[194:197], v[220:223], v[8:11]
	v_mfma_f32_16x16x32_bf16 v[4:7], v[202:205], v[212:215], v[4:7]
	v_mfma_f32_16x16x32_bf16 v[0:3], v[202:205], v[220:223], v[0:3]
	v_mfma_f32_16x16x32_bf16 v[28:31], v[182:185], v[216:219], v[28:31]
	v_mfma_f32_16x16x32_bf16 v[24:27], v[182:185], v[224:227], v[24:27]
	v_mfma_f32_16x16x32_bf16 v[20:23], v[190:193], v[216:219], v[20:23]
	v_mfma_f32_16x16x32_bf16 v[16:19], v[190:193], v[224:227], v[16:19]
	v_mfma_f32_16x16x32_bf16 v[12:15], v[198:201], v[216:219], v[12:15]
	v_mfma_f32_16x16x32_bf16 v[8:11], v[198:201], v[224:227], v[8:11]
	v_mfma_f32_16x16x32_bf16 v[4:7], v[208:211], v[216:219], v[4:7]
	v_mfma_f32_16x16x32_bf16 v[0:3], v[208:211], v[224:227], v[0:3]
	s_barrier
	s_setprio 0
	s_cmp_lt_u32 s9, 28
	s_cbranch_scc1 .LBB0_415
	s_add_u32 s6, s60, s6
	s_addc_u32 s7, s61, s7
	v_lshl_add_u64 v[128:129], s[6:7], 0, v[132:133]
	v_readfirstlane_b32 s6, v159
	s_mov_b32 m0, s6
	s_add_u32 s6, s60, s34
	v_lshl_add_u64 v[128:129], v[128:129], 0, s[28:29]
	s_addc_u32 s7, s61, s35
	ds_read_b128 v[150:153], v160
	ds_read_b128 v[162:165], v160 offset:1024
	ds_read_b128 v[166:169], v160 offset:2048
	ds_read_b128 v[170:173], v160 offset:3072
	ds_read_b128 v[174:177], v136
	ds_read_b128 v[178:181], v136 offset:1024
	ds_read_b128 v[182:185], v135
	ds_read_b128 v[186:189], v135 offset:1024
	ds_read_b128 v[190:193], v131
	ds_read_b128 v[194:197], v131 offset:1024
	ds_read_b128 v[198:201], v130
	ds_read_b128 v[202:205], v130 offset:1024
	global_load_lds_dwordx4 v[128:129], off
	v_lshl_add_u64 v[128:129], s[6:7], 0, v[132:133]
	v_readfirstlane_b32 s6, v158
	v_lshl_add_u64 v[128:129], v[128:129], 0, s[28:29]
	s_mov_b32 m0, s6
	s_nop 0
	global_load_lds_dwordx4 v[128:129], off
	s_setprio 1
	s_barrier
	s_waitcnt lgkmcnt(0)
	v_mfma_f32_16x16x32_bf16 v[124:127], v[174:177], v[150:153], v[124:127]
	v_mfma_f32_16x16x32_bf16 v[120:123], v[174:177], v[166:169], v[120:123]
	v_mfma_f32_16x16x32_bf16 v[116:119], v[182:185], v[150:153], v[116:119]
	v_mfma_f32_16x16x32_bf16 v[108:111], v[190:193], v[150:153], v[108:111]
	v_mfma_f32_16x16x32_bf16 v[124:127], v[178:181], v[162:165], v[124:127]
	v_mfma_f32_16x16x32_bf16 v[120:123], v[178:181], v[170:173], v[120:123]
	v_mfma_f32_16x16x32_bf16 v[116:119], v[186:189], v[162:165], v[116:119]
	v_mfma_f32_16x16x32_bf16 v[112:115], v[182:185], v[166:169], v[112:115]
	v_mfma_f32_16x16x32_bf16 v[108:111], v[194:197], v[162:165], v[108:111]
	v_mfma_f32_16x16x32_bf16 v[104:107], v[190:193], v[166:169], v[104:107]
	v_mfma_f32_16x16x32_bf16 v[100:103], v[198:201], v[150:153], v[100:103]
	v_mfma_f32_16x16x32_bf16 v[96:99], v[198:201], v[166:169], v[96:99]
	v_mfma_f32_16x16x32_bf16 v[158:161], v[186:189], v[170:173], v[112:115]
	v_mfma_f32_16x16x32_bf16 v[208:211], v[194:197], v[170:173], v[104:107]
	v_mfma_f32_16x16x32_bf16 v[212:215], v[202:205], v[162:165], v[100:103]
	v_mfma_f32_16x16x32_bf16 v[216:219], v[202:205], v[170:173], v[96:99]
	s_barrier
; #define WAIT_V(n) asm volatile("s_waitcnt vmcnt(" #n ")" ::: "memory")
; #define WAIT_L(n) asm volatile("s_waitcnt lgkmcnt(" #n ")" ::: "memory")
; #define BAR __builtin_amdgcn_s_barrier()
; template <int EPI>
; __device__ __forceinline__ void gemm_tile(const Params& p, const bf16* __restrict__ A, const bf16* __restrict__ Bt, const int K,
;                                           const int nt, const int brow, const int bcol, int pm, int pn) {
;     ...
;   { LDB(B0, 0, 0); LDA(At, 0, 0); STAGE(SA(1, 1), A, brow + HALF, nt - 1);
;     BAR; WAIT_L(0); MMA(0, 0, At, B0); BAR;
;     LDB(B1, 0, 1); BAR; WAIT_L(0); MMA(0, 1, At, B1); BAR;
;     LDA(At, 0, 1); WAIT_V(4); BAR; WAIT_L(0); MMA(1, 0, At, B0); MMA(1, 1, At, B1); BAR; }
;   { LDB(B0, 1, 0); LDA(At, 1, 0); WAIT_V(2); BAR; WAIT_L(0); MMA(0, 0, At, B0); BAR;
	s_setprio 0
	s_nop 1
	ds_read_b128 v[96:99], v156
	ds_read_b128 v[100:103], v156 offset:1024
	ds_read_b128 v[104:107], v156 offset:2048
	ds_read_b128 v[112:115], v156 offset:3072
	s_setprio 1
	s_barrier
	s_waitcnt lgkmcnt(0)
	v_mfma_f32_16x16x32_bf16 v[92:95], v[174:177], v[96:99], v[92:95]
	v_mfma_f32_16x16x32_bf16 v[88:91], v[174:177], v[104:107], v[88:91]
	v_mfma_f32_16x16x32_bf16 v[84:87], v[182:185], v[96:99], v[84:87]
	v_mfma_f32_16x16x32_bf16 v[76:79], v[190:193], v[96:99], v[76:79]
	v_mfma_f32_16x16x32_bf16 v[92:95], v[178:181], v[100:103], v[92:95]
	v_mfma_f32_16x16x32_bf16 v[88:91], v[178:181], v[112:115], v[88:91]
	v_mfma_f32_16x16x32_bf16 v[84:87], v[186:189], v[100:103], v[84:87]
	v_mfma_f32_16x16x32_bf16 v[80:83], v[182:185], v[104:107], v[80:83]
	v_mfma_f32_16x16x32_bf16 v[76:79], v[194:197], v[100:103], v[76:79]
	v_mfma_f32_16x16x32_bf16 v[72:75], v[190:193], v[104:107], v[72:75]
	v_mfma_f32_16x16x32_bf16 v[68:71], v[198:201], v[96:99], v[68:71]
	v_mfma_f32_16x16x32_bf16 v[64:67], v[198:201], v[104:107], v[64:67]
	v_mfma_f32_16x16x32_bf16 v[154:157], v[186:189], v[112:115], v[80:83]
	v_mfma_f32_16x16x32_bf16 v[174:177], v[194:197], v[112:115], v[72:75]
	v_mfma_f32_16x16x32_bf16 v[178:181], v[202:205], v[100:103], v[68:71]
	v_mfma_f32_16x16x32_bf16 v[182:185], v[202:205], v[112:115], v[64:67]
	s_barrier
	s_setprio 0
	s_nop 1
	ds_read_b128 v[64:67], v136 offset:16384
	ds_read_b128 v[68:71], v136 offset:17408
	ds_read_b128 v[72:75], v135 offset:16384
	ds_read_b128 v[80:83], v135 offset:17408
	ds_read_b128 v[186:189], v131 offset:16384
	ds_read_b128 v[190:193], v131 offset:17408
	ds_read_b128 v[194:197], v130 offset:16384
	ds_read_b128 v[198:201], v130 offset:17408
	s_waitcnt vmcnt(4)
	s_setprio 1
	s_barrier
	s_waitcnt lgkmcnt(0)
	v_mfma_f32_16x16x32_bf16 v[60:63], v[64:67], v[150:153], v[60:63]
	v_mfma_f32_16x16x32_bf16 v[56:59], v[64:67], v[166:169], v[56:59]
	v_mfma_f32_16x16x32_bf16 v[52:55], v[72:75], v[150:153], v[52:55]
	v_mfma_f32_16x16x32_bf16 v[44:47], v[186:189], v[150:153], v[44:47]
	v_mfma_f32_16x16x32_bf16 v[60:63], v[68:71], v[162:165], v[60:63]
	v_mfma_f32_16x16x32_bf16 v[56:59], v[68:71], v[170:173], v[56:59]
	v_mfma_f32_16x16x32_bf16 v[52:55], v[80:83], v[162:165], v[52:55]
	v_mfma_f32_16x16x32_bf16 v[48:51], v[72:75], v[166:169], v[48:51]
	v_mfma_f32_16x16x32_bf16 v[44:47], v[190:193], v[162:165], v[44:47]
	v_mfma_f32_16x16x32_bf16 v[40:43], v[186:189], v[166:169], v[40:43]
	v_mfma_f32_16x16x32_bf16 v[36:39], v[194:197], v[150:153], v[36:39]
	v_mfma_f32_16x16x32_bf16 v[32:35], v[194:197], v[166:169], v[32:35]
	v_mfma_f32_16x16x32_bf16 v[202:205], v[80:83], v[170:173], v[48:51]
	v_mfma_f32_16x16x32_bf16 v[220:223], v[190:193], v[170:173], v[40:43]
	v_mfma_f32_16x16x32_bf16 v[150:153], v[198:201], v[162:165], v[36:39]
	v_mfma_f32_16x16x32_bf16 v[162:165], v[198:201], v[170:173], v[32:35]
	s_setprio 0
	s_setprio 1
	v_mfma_f32_16x16x32_bf16 v[28:31], v[64:67], v[96:99], v[28:31]
	v_mfma_f32_16x16x32_bf16 v[24:27], v[64:67], v[104:107], v[24:27]
	v_mfma_f32_16x16x32_bf16 v[20:23], v[72:75], v[96:99], v[20:23]
	v_mfma_f32_16x16x32_bf16 v[12:15], v[186:189], v[96:99], v[12:15]
	v_mfma_f32_16x16x32_bf16 v[28:31], v[68:71], v[100:103], v[28:31]
	v_mfma_f32_16x16x32_bf16 v[24:27], v[68:71], v[112:115], v[24:27]
	v_mfma_f32_16x16x32_bf16 v[20:23], v[80:83], v[100:103], v[20:23]
	v_mfma_f32_16x16x32_bf16 v[16:19], v[72:75], v[104:107], v[16:19]
	v_mfma_f32_16x16x32_bf16 v[12:15], v[190:193], v[100:103], v[12:15]
	v_mfma_f32_16x16x32_bf16 v[8:11], v[186:189], v[104:107], v[8:11]
	v_mfma_f32_16x16x32_bf16 v[4:7], v[194:197], v[96:99], v[4:7]
	v_mfma_f32_16x16x32_bf16 v[0:3], v[194:197], v[104:107], v[0:3]
	v_mfma_f32_16x16x32_bf16 v[166:169], v[80:83], v[112:115], v[16:19]
	v_mfma_f32_16x16x32_bf16 v[170:173], v[190:193], v[112:115], v[8:11]
	v_mfma_f32_16x16x32_bf16 v[186:189], v[198:201], v[100:103], v[4:7]
	v_mfma_f32_16x16x32_bf16 v[190:193], v[198:201], v[112:115], v[0:3]
	s_barrier
	s_setprio 0
	s_nop 1
	ds_read_b128 v[0:3], v149
	ds_read_b128 v[4:7], v149 offset:1024
	ds_read_b128 v[8:11], v149 offset:2048
	ds_read_b128 v[16:19], v149 offset:3072
	ds_read_b128 v[32:35], v136 offset:32768
	ds_read_b128 v[36:39], v136 offset:33792
	ds_read_b128 v[40:43], v135 offset:32768
	ds_read_b128 v[48:51], v135 offset:33792
	ds_read_b128 v[194:197], v131 offset:32768
	ds_read_b128 v[198:201], v131 offset:33792
	ds_read_b128 v[224:227], v130 offset:32768
	ds_read_b128 v[228:231], v130 offset:33792
	s_waitcnt vmcnt(2)
	s_setprio 1
	s_barrier
; #define WAIT_V(n) asm volatile("s_waitcnt vmcnt(" #n ")" ::: "memory")
; #define WAIT_L(n) asm volatile("s_waitcnt lgkmcnt(" #n ")" ::: "memory")
; #define BAR __builtin_amdgcn_s_barrier()
; template <int EPI>
; __device__ __forceinline__ void gemm_tile(const Params& p, const bf16* __restrict__ A, const bf16* __restrict__ Bt, const int K,
;                                           const int nt, const int brow, const int bcol, int pm, int pn) {
;     ...
;     LDA(At, 0, 1); WAIT_V(4); BAR; WAIT_L(0); MMA(1, 0, At, B0); MMA(1, 1, At, B1); BAR; }
;   { LDB(B0, 1, 0); LDA(At, 1, 0); WAIT_V(2); BAR; WAIT_L(0); MMA(0, 0, At, B0); BAR;
;     LDB(B1, 1, 1); WAIT_V(0); BAR; WAIT_L(0); MMA(0, 1, At, B1); BAR;
;     LDA(At, 1, 1); BAR; WAIT_L(0); MMA(1, 0, At, B0); MMA(1, 1, At, B1); BAR; }
;   if (wr == 0) BAR;
	s_waitcnt lgkmcnt(0)
	v_mfma_f32_16x16x32_bf16 v[64:67], v[32:35], v[0:3], v[124:127]
	v_mfma_f32_16x16x32_bf16 v[96:99], v[36:39], v[4:7], v[64:67]
	v_mfma_f32_16x16x32_bf16 v[64:67], v[32:35], v[8:11], v[120:123]
	v_mfma_f32_16x16x32_bf16 v[112:115], v[36:39], v[16:19], v[64:67]
	v_mfma_f32_16x16x32_bf16 v[64:67], v[40:43], v[0:3], v[116:119]
	v_mfma_f32_16x16x32_bf16 v[100:103], v[48:51], v[4:7], v[64:67]
	v_mfma_f32_16x16x32_bf16 v[64:67], v[40:43], v[8:11], v[158:161]
	v_mfma_f32_16x16x32_bf16 v[116:119], v[48:51], v[16:19], v[64:67]
	v_mfma_f32_16x16x32_bf16 v[64:67], v[194:197], v[0:3], v[108:111]
	v_mfma_f32_16x16x32_bf16 v[104:107], v[198:201], v[4:7], v[64:67]
	v_mfma_f32_16x16x32_bf16 v[64:67], v[194:197], v[8:11], v[208:211]
	v_mfma_f32_16x16x32_bf16 v[120:123], v[198:201], v[16:19], v[64:67]
	v_mfma_f32_16x16x32_bf16 v[64:67], v[224:227], v[0:3], v[212:215]
	v_mfma_f32_16x16x32_bf16 v[108:111], v[228:231], v[4:7], v[64:67]
	v_mfma_f32_16x16x32_bf16 v[64:67], v[224:227], v[8:11], v[216:219]
	v_mfma_f32_16x16x32_bf16 v[124:127], v[228:231], v[16:19], v[64:67]
	s_barrier
	s_setprio 0
	ds_read_b128 v[158:161], v139
	ds_read_b128 v[208:211], v139 offset:1024
	ds_read_b128 v[212:215], v139 offset:2048
	ds_read_b128 v[138:141], v139 offset:3072
	s_waitcnt vmcnt(0)
	s_setprio 1
	s_barrier
	s_waitcnt lgkmcnt(0)
	v_mfma_f32_16x16x32_bf16 v[64:67], v[32:35], v[158:161], v[92:95]
	v_mfma_f32_16x16x32_bf16 v[32:35], v[32:35], v[212:215], v[88:91]
	v_mfma_f32_16x16x32_bf16 v[80:83], v[36:39], v[138:141], v[32:35]
	v_mfma_f32_16x16x32_bf16 v[32:35], v[40:43], v[158:161], v[84:87]
	v_mfma_f32_16x16x32_bf16 v[68:71], v[48:51], v[208:211], v[32:35]
	v_mfma_f32_16x16x32_bf16 v[32:35], v[40:43], v[212:215], v[154:157]
	v_mfma_f32_16x16x32_bf16 v[84:87], v[48:51], v[138:141], v[32:35]
	v_mfma_f32_16x16x32_bf16 v[32:35], v[194:197], v[158:161], v[76:79]
	v_mfma_f32_16x16x32_bf16 v[72:75], v[198:201], v[208:211], v[32:35]
	v_mfma_f32_16x16x32_bf16 v[32:35], v[194:197], v[212:215], v[174:177]
	v_mfma_f32_16x16x32_bf16 v[88:91], v[198:201], v[138:141], v[32:35]
	v_mfma_f32_16x16x32_bf16 v[32:35], v[224:227], v[158:161], v[178:181]
	v_mfma_f32_16x16x32_bf16 v[76:79], v[228:231], v[208:211], v[32:35]
	v_mfma_f32_16x16x32_bf16 v[32:35], v[224:227], v[212:215], v[182:185]
	v_mfma_f32_16x16x32_bf16 v[64:67], v[36:39], v[208:211], v[64:67]
	v_mfma_f32_16x16x32_bf16 v[92:95], v[228:231], v[138:141], v[32:35]
	s_barrier
	s_setprio 0
	ds_read_b128 v[154:157], v136 offset:49152
	ds_read_b128 v[174:177], v136 offset:50176
	ds_read_b128 v[178:181], v135 offset:49152
	ds_read_b128 v[134:137], v135 offset:50176
	ds_read_b128 v[182:185], v131 offset:49152
	ds_read_b128 v[194:197], v131 offset:50176
	ds_read_b128 v[198:201], v130 offset:49152
	ds_read_b128 v[128:131], v130 offset:50176
	s_setprio 1
	s_barrier
	s_waitcnt lgkmcnt(0)
	v_mfma_f32_16x16x32_bf16 v[36:39], v[154:157], v[8:11], v[56:59]
	v_mfma_f32_16x16x32_bf16 v[40:43], v[178:181], v[8:11], v[202:205]
	v_mfma_f32_16x16x32_bf16 v[32:35], v[154:157], v[0:3], v[60:63]
	v_mfma_f32_16x16x32_bf16 v[48:51], v[174:177], v[16:19], v[36:39]
	v_mfma_f32_16x16x32_bf16 v[36:39], v[178:181], v[0:3], v[52:55]
	v_mfma_f32_16x16x32_bf16 v[52:55], v[134:137], v[16:19], v[40:43]
	v_mfma_f32_16x16x32_bf16 v[40:43], v[182:185], v[0:3], v[44:47]
	v_mfma_f32_16x16x32_bf16 v[44:47], v[182:185], v[8:11], v[220:223]
	v_mfma_f32_16x16x32_bf16 v[0:3], v[198:201], v[0:3], v[150:153]
	v_mfma_f32_16x16x32_bf16 v[56:59], v[194:197], v[16:19], v[44:47]
	v_mfma_f32_16x16x32_bf16 v[44:47], v[128:131], v[4:7], v[0:3]
	v_mfma_f32_16x16x32_bf16 v[0:3], v[198:201], v[8:11], v[162:165]
	v_mfma_f32_16x16x32_bf16 v[32:35], v[174:177], v[4:7], v[32:35]
	v_mfma_f32_16x16x32_bf16 v[36:39], v[134:137], v[4:7], v[36:39]
	v_mfma_f32_16x16x32_bf16 v[40:43], v[194:197], v[4:7], v[40:43]
	v_mfma_f32_16x16x32_bf16 v[60:63], v[128:131], v[16:19], v[0:3]
	s_setprio 0
	s_setprio 1
	v_mfma_f32_16x16x32_bf16 v[4:7], v[154:157], v[212:215], v[24:27]
	v_mfma_f32_16x16x32_bf16 v[8:11], v[178:181], v[212:215], v[166:169]
	v_mfma_f32_16x16x32_bf16 v[16:19], v[174:177], v[138:141], v[4:7]
	v_mfma_f32_16x16x32_bf16 v[4:7], v[178:181], v[158:161], v[20:23]
	v_mfma_f32_16x16x32_bf16 v[20:23], v[134:137], v[138:141], v[8:11]
	v_mfma_f32_16x16x32_bf16 v[8:11], v[182:185], v[158:161], v[12:15]
	v_mfma_f32_16x16x32_bf16 v[12:15], v[182:185], v[212:215], v[170:173]
	v_mfma_f32_16x16x32_bf16 v[0:3], v[154:157], v[158:161], v[28:31]
	v_mfma_f32_16x16x32_bf16 v[24:27], v[194:197], v[138:141], v[12:15]
	v_mfma_f32_16x16x32_bf16 v[12:15], v[198:201], v[158:161], v[186:189]
	v_mfma_f32_16x16x32_bf16 v[28:31], v[198:201], v[212:215], v[190:193]
	v_mfma_f32_16x16x32_bf16 v[0:3], v[174:177], v[208:211], v[0:3]
	v_mfma_f32_16x16x32_bf16 v[4:7], v[134:137], v[208:211], v[4:7]
	v_mfma_f32_16x16x32_bf16 v[8:11], v[194:197], v[208:211], v[8:11]
	v_mfma_f32_16x16x32_bf16 v[12:15], v[128:131], v[208:211], v[12:15]
	v_mfma_f32_16x16x32_bf16 v[28:31], v[128:131], v[138:141], v[28:31]
	s_barrier
	s_setprio 0
	s_cmpk_gt_u32 s5, 0xff
	s_cbranch_scc1 .LBB0_418
	s_barrier

; #define WAIT_V(n) asm volatile("s_waitcnt vmcnt(" #n ")" ::: "memory")
; #define BAR __builtin_amdgcn_s_barrier()
; template <int EPI>
; __device__ __forceinline__ void gemm_tile(const Params& p, const bf16* __restrict__ A, const bf16* __restrict__ Bt, const int K,
;                                           const int nt, const int brow, const int bcol, int pm, int pn) {
;     ...
;   const int wid = __builtin_amdgcn_readfirstlane(tid >> 6), lane = tid & 63, wr = wid >> 2, wc = wid & 3, fr = lane & 15, fq = lane >> 4;
;   unsigned toff;
;   { int _r, _c; stage_rc(tid * 16, _r, _c); toff = (unsigned)(_r * K + _c) * 2u; }
;   f32x4 acc[2][2][4][2] = {};
;   float pre0 = 0.f, pre1 = 0.f, pre2 = 0.f;
;   if constexpr (EPI == EPI_GU) {
;     const int base = (pm == 65) ? SEQ : 254 * pm - 2;
;     if (tid < 256) pre0 = P_SSQ(p)[max(base + tid, 0)];
;     else if (tid < 384) { const int c = pn * 128 + tid - 256; pre0 = p.w_ffn_conv[c]; pre1 = p.w_ffn_conv[DFF + c]; pre2 = p.w_ffn_conv[2 * DFF + c]; }
;   }
;   bf16x8 At[4][2], B0[2][2], B1[2][2];
;   STAGE(SB(0, 0), Bt, bcol, 0); STAGE(SA(0, 0), A, brow, 0);
;   STAGE(SB(0, 1), Bt, bcol + HALF, 0); STAGE(SA(0, 1), A, brow + HALF, 0);
;   if (wr == 1) BAR;
;   WAIT_V(4); BAR;
;   STAGE(SB(1, 0), Bt, bcol, 1); STAGE(SA(1, 0), A, brow, 1); STAGE(SB(1, 1), Bt, bcol + HALF, 1);
;   WAIT_V(6); BAR;
.LBB0_1377:
	s_add_u32 s94, s8, s54
	v_add_u32_e32 v139, s74, v4
	s_addc_u32 s95, s9, s55
	v_lshl_add_u64 v[6:7], s[94:95], 0, v[156:157]
	v_readfirstlane_b32 s85, v139
	s_add_u32 s52, s8, s52
	v_lshl_add_u64 v[6:7], v[6:7], 0, s[12:13]
	s_mov_b32 m0, s85
	s_addc_u32 s53, s9, s53
	v_add_u32_e32 v140, 0x2000, v139
	s_waitcnt vmcnt(4)
	s_barrier
	global_load_lds_dwordx4 v[6:7], off
	v_lshl_add_u64 v[6:7], s[52:53], 0, v[156:157]
	v_readfirstlane_b32 s52, v140
	s_mov_b32 m0, s52
	s_add_u32 s52, s64, s66
	v_lshl_add_u64 v[6:7], v[6:7], 0, s[12:13]
	s_addc_u32 s53, s65, s67
	v_add_u32_e32 v141, 0x8000, v132
	global_load_lds_dwordx4 v[6:7], off
	v_lshl_add_u64 v[6:7], s[52:53], 0, v[156:157]
	v_readfirstlane_b32 s52, v141
	s_mov_b32 m0, s52
	s_add_u32 s52, s64, s56
	v_lshl_add_u64 v[6:7], v[6:7], 0, s[12:13]
	s_addc_u32 s53, s65, s57
	v_add_u32_e32 v142, 0xa000, v132
	global_load_lds_dwordx4 v[6:7], off
	v_lshl_add_u64 v[6:7], s[52:53], 0, v[156:157]
	v_readfirstlane_b32 s52, v142
	s_mov_b32 m0, s52
	s_add_u32 s52, s8, s68
	v_add_u32_e32 v143, s75, v4
	s_addc_u32 s53, s9, s69
	v_lshl_add_u64 v[6:7], v[6:7], 0, s[12:13]
	v_lshl_add_u64 v[4:5], s[52:53], 0, v[156:157]
	v_readfirstlane_b32 s52, v143
	global_load_lds_dwordx4 v[6:7], off
	s_mov_b32 m0, s52
	s_add_u32 s52, s8, s70
	v_lshl_add_u64 v[4:5], v[4:5], 0, s[12:13]
	s_addc_u32 s53, s9, s71
	v_add_u32_e32 v148, 0x2000, v143
	global_load_lds_dwordx4 v[4:5], off
	v_lshl_add_u64 v[4:5], s[52:53], 0, v[156:157]
	v_readfirstlane_b32 s52, v148
	v_lshl_add_u64 v[4:5], v[4:5], 0, s[12:13]
	s_mov_b32 m0, s52
	s_sub_i32 s53, s90, s92
	global_load_lds_dwordx4 v[4:5], off
	s_lshl_b32 s56, s91, 6
	s_lshl_b32 s52, s89, 6
	s_sub_i32 s53, s53, s56
	v_and_b32_e32 v8, 15, v1
	v_and_b32_e32 v9, 48, v1
	v_lshlrev_b32_e32 v5, 2, v1
	s_and_b32 s57, s52, 0x3000
	v_lshlrev_b32_e32 v1, 6, v1
	s_movk_i32 s52, 0x3c0
	s_sext_i32_i8 s53, s53
	v_and_or_b32 v1, v1, s52, v9
	s_lshl_b32 s52, s91, 11
	s_lshl_b32 s53, s53, 8
	v_lshlrev_b32_e32 v4, 6, v8
	v_and_b32_e32 v5, 32, v5
	s_add_i32 s52, s52, s53
	v_bitop3_b32 v4, v4, v5, v9 bitop3:0x36
	s_lshl_b32 s66, s84, 13
	v_xad_u32 v1, v1, v5, 16
	v_lshlrev_b32_e32 v5, 15, v0
	s_ashr_i32 s53, s52, 31
	s_or_b32 s67, s66, 0x800
	s_or_b32 s68, s66, 0x1000
	s_or_b32 s69, s66, 0x1800
	v_and_b32_e32 v5, 0xffff0000, v5
	s_lshl_b64 s[52:53], s[52:53], 12
	v_lshl_add_u32 v2, v2, 12, v5
	v_and_b32_e32 v0, 1, v0
	s_add_u32 s52, s46, s52
	s_waitcnt vmcnt(6)
	v_lshl_or_b32 v0, v0, 6, v2
	s_addc_u32 s53, s47, s53
	v_add_u32_e32 v6, s72, v4
	v_add_u32_e32 v7, s73, v4
	v_add_u32_e32 v8, s74, v4
	v_add_u32_e32 v10, s75, v4
	v_add_u32_e32 v4, 16, v4
	v_lshl_add_u32 v128, v3, 1, v0
	s_add_u32 s54, s46, s54
	v_mov_b32_e32 v0, 0
	v_mov_b32_e32 v129, v157
	s_addc_u32 s55, s47, s55
	s_mov_b32 s56, -2
	v_add_u32_e32 v153, s57, v6
	v_add_u32_e32 v147, s66, v4
	v_add_u32_e32 v146, s67, v1
	v_add_u32_e32 v145, s68, v1
	v_add_u32_e32 v144, s69, v1
	v_add_u32_e32 v151, 0xc000, v132
	v_add_u32_e32 v150, 0xe000, v132
	v_add_u32_e32 v149, s57, v7
	v_add_u32_e32 v138, s57, v8
	v_add_u32_e32 v152, s57, v10
	v_mov_b32_e32 v1, v0
	v_mov_b32_e32 v2, v0
	v_mov_b32_e32 v3, v0
	v_mov_b32_e32 v4, v0
	v_mov_b32_e32 v5, v0
	v_mov_b32_e32 v6, v0
	v_mov_b32_e32 v7, v0
	v_mov_b32_e32 v8, v0
	v_mov_b32_e32 v9, v0
	v_mov_b32_e32 v10, v0
	v_mov_b32_e32 v11, v0
	v_mov_b32_e32 v12, v0
	v_mov_b32_e32 v13, v0
	v_mov_b32_e32 v14, v0
	v_mov_b32_e32 v15, v0
	v_mov_b32_e32 v16, v0
	v_mov_b32_e32 v17, v0
	v_mov_b32_e32 v18, v0
	v_mov_b32_e32 v19, v0
	v_mov_b32_e32 v20, v0
	v_mov_b32_e32 v21, v0
	v_mov_b32_e32 v22, v0
	v_mov_b32_e32 v23, v0
	v_mov_b32_e32 v24, v0
	v_mov_b32_e32 v25, v0
	v_mov_b32_e32 v26, v0
	v_mov_b32_e32 v27, v0
	v_mov_b32_e32 v28, v0
	v_mov_b32_e32 v29, v0
	v_mov_b32_e32 v30, v0
	v_mov_b32_e32 v31, v0
	v_mov_b32_e32 v32, v0
	v_mov_b32_e32 v33, v0
	v_mov_b32_e32 v34, v0
	v_mov_b32_e32 v35, v0
	v_mov_b32_e32 v36, v0
	v_mov_b32_e32 v37, v0
	v_mov_b32_e32 v38, v0
	v_mov_b32_e32 v39, v0
	v_mov_b32_e32 v40, v0
	v_mov_b32_e32 v41, v0
	v_mov_b32_e32 v42, v0
	v_mov_b32_e32 v43, v0
	v_mov_b32_e32 v44, v0
	v_mov_b32_e32 v45, v0
	v_mov_b32_e32 v46, v0
	v_mov_b32_e32 v47, v0
	v_mov_b32_e32 v48, v0
	v_mov_b32_e32 v49, v0
	v_mov_b32_e32 v50, v0
	v_mov_b32_e32 v51, v0
	v_mov_b32_e32 v52, v0
	v_mov_b32_e32 v53, v0
	v_mov_b32_e32 v54, v0
	v_mov_b32_e32 v55, v0
	v_mov_b32_e32 v56, v0
	v_mov_b32_e32 v57, v0
	v_mov_b32_e32 v58, v0
	v_mov_b32_e32 v59, v0
	v_mov_b32_e32 v60, v0
	v_mov_b32_e32 v61, v0
	v_mov_b32_e32 v62, v0
	v_mov_b32_e32 v63, v0
	v_mov_b32_e32 v64, v0
	v_mov_b32_e32 v65, v0
	v_mov_b32_e32 v66, v0
	v_mov_b32_e32 v67, v0
	v_mov_b32_e32 v68, v0
	v_mov_b32_e32 v69, v0
	v_mov_b32_e32 v70, v0
	v_mov_b32_e32 v71, v0
	v_mov_b32_e32 v72, v0
	v_mov_b32_e32 v73, v0
	v_mov_b32_e32 v74, v0
	v_mov_b32_e32 v75, v0
	v_mov_b32_e32 v76, v0
	v_mov_b32_e32 v77, v0
	v_mov_b32_e32 v78, v0
	v_mov_b32_e32 v79, v0
	v_mov_b32_e32 v80, v0
	v_mov_b32_e32 v81, v0
	v_mov_b32_e32 v82, v0
	v_mov_b32_e32 v83, v0
	v_mov_b32_e32 v84, v0
	v_mov_b32_e32 v85, v0
	v_mov_b32_e32 v86, v0
	v_mov_b32_e32 v87, v0
	v_mov_b32_e32 v88, v0
	v_mov_b32_e32 v89, v0
	v_mov_b32_e32 v90, v0
	v_mov_b32_e32 v91, v0
	v_mov_b32_e32 v92, v0
	v_mov_b32_e32 v93, v0
	v_mov_b32_e32 v94, v0
	v_mov_b32_e32 v95, v0
	v_mov_b32_e32 v96, v0
	v_mov_b32_e32 v97, v0
	v_mov_b32_e32 v98, v0
	v_mov_b32_e32 v99, v0
	v_mov_b32_e32 v100, v0
	v_mov_b32_e32 v101, v0
	v_mov_b32_e32 v102, v0
	v_mov_b32_e32 v103, v0
	v_mov_b32_e32 v104, v0
	v_mov_b32_e32 v105, v0
	v_mov_b32_e32 v106, v0
	v_mov_b32_e32 v107, v0
	v_mov_b32_e32 v108, v0
	v_mov_b32_e32 v109, v0
	v_mov_b32_e32 v110, v0
	v_mov_b32_e32 v111, v0
	v_mov_b32_e32 v112, v0
	v_mov_b32_e32 v113, v0
	v_mov_b32_e32 v114, v0
	v_mov_b32_e32 v115, v0
	v_mov_b32_e32 v116, v0
	v_mov_b32_e32 v117, v0
	v_mov_b32_e32 v118, v0
	v_mov_b32_e32 v119, v0
	v_mov_b32_e32 v120, v0
	v_mov_b32_e32 v121, v0
	v_mov_b32_e32 v122, v0
	v_mov_b32_e32 v123, v0
	v_mov_b32_e32 v124, v0
	v_mov_b32_e32 v125, v0
	v_mov_b32_e32 v126, v0
	v_mov_b32_e32 v127, v0
	s_barrier
	v_lshl_add_u64 v[154:155], s[52:53], 0, v[128:129]
	s_mov_b64 s[66:67], 0x14602080
	v_lshl_add_u64 v[246:247], v[154:155], 0, s[66:67]
	s_mov_b64 s[66:67], 0x14642080
	v_lshl_add_u64 v[244:245], v[154:155], 0, s[66:67]
	v_readfirstlane_b32 s99, v151
	v_readfirstlane_b32 s98, v150
	v_readfirstlane_b32 s100, v136
	v_readfirstlane_b32 s101, v137
; #define WAIT_L(n) asm volatile("s_waitcnt lgkmcnt(" #n ")" ::: "memory")
; #define BAR __builtin_amdgcn_s_barrier()
; #define SCHED __builtin_amdgcn_sched_barrier(0)
; template <int EPI>
; __device__ __forceinline__ void gemm_tile(const Params& p, const bf16* __restrict__ A, const bf16* __restrict__ Bt, const int K,
;                                           const int nt, const int brow, const int bcol, int pm, int pn) {
;     ...
;   for (int t = 0; t < nt - 2; t += 2) {
;     LDB(B0, 0, 0); SCHED; LDA(At, 0, 0); STAGE(SA(1, 1), A, brow + HALF, t + 1);
;     WAIT_L(8); BAR; WAIT_L(0); MMA(0, 0, At, B0); BAR; SCHED;
;     LDB(B1, 0, 1); STAGE(SB(0, 0), Bt, bcol, t + 2);
;     BAR; WAIT_L(0); MMA(0, 1, At, B1); BAR;
;     LDA(At, 0, 1); STAGE(SA(0, 0), A, brow, t + 2);
.LBB0_1378:
	ds_read_b128 v[158:161], v153
	ds_read_b128 v[162:165], v153 offset:1024
	ds_read_b128 v[166:169], v153 offset:2048
	ds_read_b128 v[170:173], v153 offset:3072
	s_mov_b32 m0, s99
	ds_read_b128 v[174:177], v147
	ds_read_b128 v[178:181], v147 offset:1024
	ds_read_b128 v[182:185], v146
	ds_read_b128 v[186:189], v146 offset:1024
	ds_read_b128 v[190:193], v145
	ds_read_b128 v[196:199], v145 offset:1024
	ds_read_b128 v[200:203], v144
	ds_read_b128 v[208:211], v144 offset:1024
	global_load_lds_dwordx4 v[246:247], off
	s_mov_b32 m0, s98
	s_nop 0
	global_load_lds_dwordx4 v[244:245], off
	s_waitcnt lgkmcnt(8)
	s_setprio 1
	s_barrier
	s_waitcnt lgkmcnt(0)
	v_mfma_f32_16x16x32_bf16 v[124:127], v[174:177], v[158:161], v[124:127]
	v_mfma_f32_16x16x32_bf16 v[120:123], v[174:177], v[166:169], v[120:123]
	v_mfma_f32_16x16x32_bf16 v[116:119], v[182:185], v[158:161], v[116:119]
	v_mfma_f32_16x16x32_bf16 v[112:115], v[182:185], v[166:169], v[112:115]
	v_mfma_f32_16x16x32_bf16 v[108:111], v[190:193], v[158:161], v[108:111]
	v_mfma_f32_16x16x32_bf16 v[104:107], v[190:193], v[166:169], v[104:107]
	v_mfma_f32_16x16x32_bf16 v[100:103], v[200:203], v[158:161], v[100:103]
	v_mfma_f32_16x16x32_bf16 v[96:99], v[200:203], v[166:169], v[96:99]
	v_mfma_f32_16x16x32_bf16 v[124:127], v[178:181], v[162:165], v[124:127]
	v_mfma_f32_16x16x32_bf16 v[120:123], v[178:181], v[170:173], v[120:123]
	v_mfma_f32_16x16x32_bf16 v[116:119], v[186:189], v[162:165], v[116:119]
	v_mfma_f32_16x16x32_bf16 v[112:115], v[186:189], v[170:173], v[112:115]
	v_mfma_f32_16x16x32_bf16 v[108:111], v[196:199], v[162:165], v[108:111]
	v_mfma_f32_16x16x32_bf16 v[104:107], v[196:199], v[170:173], v[104:107]
	v_mfma_f32_16x16x32_bf16 v[100:103], v[208:211], v[162:165], v[100:103]
	v_mfma_f32_16x16x32_bf16 v[96:99], v[208:211], v[170:173], v[96:99]
	s_barrier
	s_setprio 0
	v_lshl_add_u64 v[204:205], s[54:55], 0, v[128:129]
	s_mov_b64 s[66:67], 0x1800100
	v_readfirstlane_b32 s57, v130
	v_lshl_add_u64 v[228:229], v[204:205], 0, s[66:67]
	s_mov_b32 m0, s57
	s_mov_b64 s[66:67], 0x1840100
	v_readfirstlane_b32 s57, v131
	ds_read_b128 v[212:215], v149
	ds_read_b128 v[216:219], v149 offset:1024
	ds_read_b128 v[220:223], v149 offset:2048
	ds_read_b128 v[224:227], v149 offset:3072
	global_load_lds_dwordx4 v[228:229], off
	v_lshl_add_u64 v[228:229], v[204:205], 0, s[66:67]
	s_mov_b32 m0, s57
	s_nop 0
	global_load_lds_dwordx4 v[228:229], off
	s_mov_b64 s[66:67], 0x14582100
	v_readfirstlane_b32 s57, v132
	v_lshl_add_u64 v[228:229], v[154:155], 0, s[66:67]
	s_mov_b32 m0, s57
	v_readfirstlane_b32 s57, v133
	s_setprio 1
	s_barrier
	s_waitcnt lgkmcnt(0)
	v_mfma_f32_16x16x32_bf16 v[92:95], v[174:177], v[212:215], v[92:95]
	v_mfma_f32_16x16x32_bf16 v[88:91], v[174:177], v[220:223], v[88:91]
	v_mfma_f32_16x16x32_bf16 v[84:87], v[182:185], v[212:215], v[84:87]
	v_mfma_f32_16x16x32_bf16 v[80:83], v[182:185], v[220:223], v[80:83]
	v_mfma_f32_16x16x32_bf16 v[76:79], v[190:193], v[212:215], v[76:79]
	v_mfma_f32_16x16x32_bf16 v[72:75], v[190:193], v[220:223], v[72:75]
	v_mfma_f32_16x16x32_bf16 v[68:71], v[200:203], v[212:215], v[68:71]
	v_mfma_f32_16x16x32_bf16 v[64:67], v[200:203], v[220:223], v[64:67]
	v_mfma_f32_16x16x32_bf16 v[92:95], v[178:181], v[216:219], v[92:95]
	v_mfma_f32_16x16x32_bf16 v[88:91], v[178:181], v[224:227], v[88:91]
	v_mfma_f32_16x16x32_bf16 v[84:87], v[186:189], v[216:219], v[84:87]
	v_mfma_f32_16x16x32_bf16 v[80:83], v[186:189], v[224:227], v[80:83]
	v_mfma_f32_16x16x32_bf16 v[76:79], v[196:199], v[216:219], v[76:79]
	v_mfma_f32_16x16x32_bf16 v[72:75], v[196:199], v[224:227], v[72:75]
	v_mfma_f32_16x16x32_bf16 v[68:71], v[208:211], v[216:219], v[68:71]
	v_mfma_f32_16x16x32_bf16 v[64:67], v[208:211], v[224:227], v[64:67]
	s_barrier
	s_setprio 0
	ds_read_b128 v[174:177], v147 offset:16384
	ds_read_b128 v[178:181], v147 offset:17408
	ds_read_b128 v[182:185], v146 offset:16384
	ds_read_b128 v[186:189], v146 offset:17408
	ds_read_b128 v[190:193], v145 offset:16384
	ds_read_b128 v[196:199], v145 offset:17408
	ds_read_b128 v[200:203], v144 offset:16384
	ds_read_b128 v[208:211], v144 offset:17408
	global_load_lds_dwordx4 v[228:229], off
	v_lshl_add_u64 v[228:229], v[154:155], 0, s[14:15]
	s_mov_b32 m0, s57
	s_nop 0
	global_load_lds_dwordx4 v[228:229], off
	s_setprio 1
	s_barrier
	s_waitcnt lgkmcnt(0)
	v_mfma_f32_16x16x32_bf16 v[60:63], v[174:177], v[158:161], v[60:63]
	v_mfma_f32_16x16x32_bf16 v[56:59], v[174:177], v[166:169], v[56:59]
	v_mfma_f32_16x16x32_bf16 v[52:55], v[182:185], v[158:161], v[52:55]
	v_mfma_f32_16x16x32_bf16 v[48:51], v[182:185], v[166:169], v[48:51]
	v_mfma_f32_16x16x32_bf16 v[44:47], v[190:193], v[158:161], v[44:47]
	v_mfma_f32_16x16x32_bf16 v[40:43], v[190:193], v[166:169], v[40:43]
	v_mfma_f32_16x16x32_bf16 v[36:39], v[200:203], v[158:161], v[36:39]
	v_mfma_f32_16x16x32_bf16 v[32:35], v[200:203], v[166:169], v[32:35]
	v_mfma_f32_16x16x32_bf16 v[60:63], v[178:181], v[162:165], v[60:63]
	v_mfma_f32_16x16x32_bf16 v[56:59], v[178:181], v[170:173], v[56:59]
	v_mfma_f32_16x16x32_bf16 v[52:55], v[186:189], v[162:165], v[52:55]
	v_mfma_f32_16x16x32_bf16 v[48:51], v[186:189], v[170:173], v[48:51]
	v_mfma_f32_16x16x32_bf16 v[44:47], v[196:199], v[162:165], v[44:47]
	v_mfma_f32_16x16x32_bf16 v[40:43], v[196:199], v[170:173], v[40:43]
	v_mfma_f32_16x16x32_bf16 v[36:39], v[208:211], v[162:165], v[36:39]
	v_mfma_f32_16x16x32_bf16 v[32:35], v[208:211], v[170:173], v[32:35]
	s_barrier
; #define WAIT_V(n) asm volatile("s_waitcnt vmcnt(" #n ")" ::: "memory")
; #define WAIT_L(n) asm volatile("s_waitcnt lgkmcnt(" #n ")" ::: "memory")
; #define BAR __builtin_amdgcn_s_barrier()
; #define SCHED __builtin_amdgcn_sched_barrier(0)
; template <int EPI>
; __device__ __forceinline__ void gemm_tile(const Params& p, const bf16* __restrict__ A, const bf16* __restrict__ Bt, const int K,
;                                           const int nt, const int brow, const int bcol, int pm, int pn) {
;     ...
;     BAR; WAIT_L(0); MMA(1, 0, At, B0); BAR; SCHED;
;     STAGE(SB(0, 1), Bt, bcol + HALF, t + 2);
;     WAIT_V(6); BAR; MMA(1, 1, At, B1); BAR;
;     LDB(B0, 1, 0); SCHED; LDA(At, 1, 0); STAGE(SA(0, 1), A, brow + HALF, t + 2);
;     WAIT_L(8); BAR; WAIT_L(0); MMA(0, 0, At, B0); BAR; SCHED;
;     LDB(B1, 1, 1); STAGE(SB(1, 0), Bt, bcol, t + 3);
;     BAR; WAIT_L(0); MMA(0, 1, At, B1); BAR;
;     LDA(At, 1, 1); STAGE(SA(1, 0), A, brow, t + 3);
	s_setprio 0
	s_add_i32 s56, s56, 2
	s_add_u32 s52, s52, 0x100
	s_addc_u32 s53, s53, 0
	s_add_u32 s54, s54, 0x100
	s_addc_u32 s55, s55, 0
	v_readfirstlane_b32 s57, v134
	v_lshl_add_u64 v[158:159], v[204:205], 0, s[16:17]
	s_mov_b32 m0, s57
	v_readfirstlane_b32 s57, v135
	global_load_lds_dwordx4 v[158:159], off
	v_lshl_add_u64 v[158:159], v[204:205], 0, s[18:19]
	s_mov_b32 m0, s57
	s_nop 0
	global_load_lds_dwordx4 v[158:159], off
	v_lshl_add_u64 v[248:249], v[154:155], 0, s[20:21]
	v_lshl_add_u64 v[250:251], v[154:155], 0, s[22:23]
	s_waitcnt vmcnt(6)
	s_setprio 1
	s_barrier
	v_mfma_f32_16x16x32_bf16 v[28:31], v[174:177], v[212:215], v[28:31]
	v_mfma_f32_16x16x32_bf16 v[24:27], v[174:177], v[220:223], v[24:27]
	v_mfma_f32_16x16x32_bf16 v[20:23], v[182:185], v[212:215], v[20:23]
	v_mfma_f32_16x16x32_bf16 v[16:19], v[182:185], v[220:223], v[16:19]
	v_mfma_f32_16x16x32_bf16 v[12:15], v[190:193], v[212:215], v[12:15]
	v_mfma_f32_16x16x32_bf16 v[8:11], v[190:193], v[220:223], v[8:11]
	v_mfma_f32_16x16x32_bf16 v[4:7], v[200:203], v[212:215], v[4:7]
	v_mfma_f32_16x16x32_bf16 v[0:3], v[200:203], v[220:223], v[0:3]
	v_mfma_f32_16x16x32_bf16 v[28:31], v[178:181], v[216:219], v[28:31]
	v_mfma_f32_16x16x32_bf16 v[24:27], v[178:181], v[224:227], v[24:27]
	v_mfma_f32_16x16x32_bf16 v[20:23], v[186:189], v[216:219], v[20:23]
	v_mfma_f32_16x16x32_bf16 v[16:19], v[186:189], v[224:227], v[16:19]
	v_mfma_f32_16x16x32_bf16 v[12:15], v[196:199], v[216:219], v[12:15]
	v_mfma_f32_16x16x32_bf16 v[8:11], v[196:199], v[224:227], v[8:11]
	v_mfma_f32_16x16x32_bf16 v[4:7], v[208:211], v[216:219], v[4:7]
	v_mfma_f32_16x16x32_bf16 v[0:3], v[208:211], v[224:227], v[0:3]
	s_barrier
	s_setprio 0
	ds_read_b128 v[158:161], v138
	ds_read_b128 v[162:165], v138 offset:1024
	ds_read_b128 v[166:169], v138 offset:2048
	ds_read_b128 v[170:173], v138 offset:3072
	s_mov_b32 m0, s100
	ds_read_b128 v[174:177], v147 offset:32768
	ds_read_b128 v[178:181], v147 offset:33792
	ds_read_b128 v[182:185], v146 offset:32768
	ds_read_b128 v[186:189], v146 offset:33792
	ds_read_b128 v[190:193], v145 offset:32768
	ds_read_b128 v[196:199], v145 offset:33792
	ds_read_b128 v[200:203], v144 offset:32768
	ds_read_b128 v[208:211], v144 offset:33792
	global_load_lds_dwordx4 v[248:249], off
	s_mov_b32 m0, s101
	s_nop 0
	global_load_lds_dwordx4 v[250:251], off
	s_waitcnt lgkmcnt(8)
	s_setprio 1
	s_barrier
	s_waitcnt lgkmcnt(0)
	v_mfma_f32_16x16x32_bf16 v[124:127], v[174:177], v[158:161], v[124:127]
	v_mfma_f32_16x16x32_bf16 v[120:123], v[174:177], v[166:169], v[120:123]
	v_mfma_f32_16x16x32_bf16 v[116:119], v[182:185], v[158:161], v[116:119]
	v_mfma_f32_16x16x32_bf16 v[112:115], v[182:185], v[166:169], v[112:115]
	v_mfma_f32_16x16x32_bf16 v[108:111], v[190:193], v[158:161], v[108:111]
	v_mfma_f32_16x16x32_bf16 v[104:107], v[190:193], v[166:169], v[104:107]
	v_mfma_f32_16x16x32_bf16 v[100:103], v[200:203], v[158:161], v[100:103]
	v_mfma_f32_16x16x32_bf16 v[96:99], v[200:203], v[166:169], v[96:99]
	v_mfma_f32_16x16x32_bf16 v[124:127], v[178:181], v[162:165], v[124:127]
	v_mfma_f32_16x16x32_bf16 v[120:123], v[178:181], v[170:173], v[120:123]
	v_mfma_f32_16x16x32_bf16 v[116:119], v[186:189], v[162:165], v[116:119]
	v_mfma_f32_16x16x32_bf16 v[112:115], v[186:189], v[170:173], v[112:115]
	v_mfma_f32_16x16x32_bf16 v[108:111], v[196:199], v[162:165], v[108:111]
	v_mfma_f32_16x16x32_bf16 v[104:107], v[196:199], v[170:173], v[104:107]
	v_mfma_f32_16x16x32_bf16 v[100:103], v[208:211], v[162:165], v[100:103]
	v_mfma_f32_16x16x32_bf16 v[96:99], v[208:211], v[170:173], v[96:99]
	s_barrier
	s_setprio 0
	v_readfirstlane_b32 s57, v139
	v_lshl_add_u64 v[228:229], v[204:205], 0, s[24:25]
	s_mov_b32 m0, s57
	v_readfirstlane_b32 s57, v140
	ds_read_b128 v[212:215], v152
	ds_read_b128 v[216:219], v152 offset:1024
	ds_read_b128 v[220:223], v152 offset:2048
	ds_read_b128 v[224:227], v152 offset:3072
	global_load_lds_dwordx4 v[228:229], off
	v_lshl_add_u64 v[228:229], v[204:205], 0, s[26:27]
	s_mov_b32 m0, s57
	s_nop 0
	global_load_lds_dwordx4 v[228:229], off
	v_readfirstlane_b32 s57, v141
	v_lshl_add_u64 v[228:229], v[154:155], 0, s[28:29]
	s_mov_b32 m0, s57
	v_readfirstlane_b32 s57, v142
	s_setprio 1
	s_barrier
	s_waitcnt lgkmcnt(0)
	v_mfma_f32_16x16x32_bf16 v[92:95], v[174:177], v[212:215], v[92:95]
	v_mfma_f32_16x16x32_bf16 v[88:91], v[174:177], v[220:223], v[88:91]
	v_mfma_f32_16x16x32_bf16 v[84:87], v[182:185], v[212:215], v[84:87]
	v_mfma_f32_16x16x32_bf16 v[80:83], v[182:185], v[220:223], v[80:83]
	v_mfma_f32_16x16x32_bf16 v[76:79], v[190:193], v[212:215], v[76:79]
	v_mfma_f32_16x16x32_bf16 v[72:75], v[190:193], v[220:223], v[72:75]
	v_mfma_f32_16x16x32_bf16 v[68:71], v[200:203], v[212:215], v[68:71]
	v_mfma_f32_16x16x32_bf16 v[64:67], v[200:203], v[220:223], v[64:67]
	v_mfma_f32_16x16x32_bf16 v[92:95], v[178:181], v[216:219], v[92:95]
	v_mfma_f32_16x16x32_bf16 v[88:91], v[178:181], v[224:227], v[88:91]
	v_mfma_f32_16x16x32_bf16 v[84:87], v[186:189], v[216:219], v[84:87]
	v_mfma_f32_16x16x32_bf16 v[80:83], v[186:189], v[224:227], v[80:83]
	v_mfma_f32_16x16x32_bf16 v[76:79], v[196:199], v[216:219], v[76:79]
	v_mfma_f32_16x16x32_bf16 v[72:75], v[196:199], v[224:227], v[72:75]
	v_mfma_f32_16x16x32_bf16 v[68:71], v[208:211], v[216:219], v[68:71]
	v_mfma_f32_16x16x32_bf16 v[64:67], v[208:211], v[224:227], v[64:67]
	s_barrier
	s_setprio 0
	ds_read_b128 v[174:177], v147 offset:49152
	ds_read_b128 v[178:181], v147 offset:50176
	ds_read_b128 v[182:185], v146 offset:49152
	ds_read_b128 v[186:189], v146 offset:50176
	ds_read_b128 v[190:193], v145 offset:49152
	ds_read_b128 v[196:199], v145 offset:50176
	ds_read_b128 v[200:203], v144 offset:49152
	ds_read_b128 v[208:211], v144 offset:50176
	global_load_lds_dwordx4 v[228:229], off
	v_lshl_add_u64 v[154:155], v[154:155], 0, s[30:31]
	s_mov_b32 m0, s57
	s_nop 0
	global_load_lds_dwordx4 v[154:155], off
	s_setprio 1
	s_barrier
; #define WAIT_V(n) asm volatile("s_waitcnt vmcnt(" #n ")" ::: "memory")
; #define WAIT_L(n) asm volatile("s_waitcnt lgkmcnt(" #n ")" ::: "memory")
; #define BAR __builtin_amdgcn_s_barrier()
; #define SCHED __builtin_amdgcn_sched_barrier(0)
; template <int EPI>
; __device__ __forceinline__ void gemm_tile(const Params& p, const bf16* __restrict__ A, const bf16* __restrict__ Bt, const int K,
;                                           const int nt, const int brow, const int bcol, int pm, int pn) {
;     ...
;     BAR; WAIT_L(0); MMA(1, 0, At, B0); BAR; SCHED;
;     STAGE(SB(1, 1), Bt, bcol + HALF, t + 3);
;     WAIT_V(6); BAR; MMA(1, 1, At, B1); BAR;
;   }
;   { LDB(B0, 0, 0); LDA(At, 0, 0); STAGE(SA(1, 1), A, brow + HALF, nt - 1);
;     BAR; WAIT_L(0); MMA(0, 0, At, B0); BAR;
	s_waitcnt lgkmcnt(0)
	v_mfma_f32_16x16x32_bf16 v[60:63], v[174:177], v[158:161], v[60:63]
	v_mfma_f32_16x16x32_bf16 v[56:59], v[174:177], v[166:169], v[56:59]
	v_mfma_f32_16x16x32_bf16 v[52:55], v[182:185], v[158:161], v[52:55]
	v_mfma_f32_16x16x32_bf16 v[48:51], v[182:185], v[166:169], v[48:51]
	v_mfma_f32_16x16x32_bf16 v[44:47], v[190:193], v[158:161], v[44:47]
	v_mfma_f32_16x16x32_bf16 v[40:43], v[190:193], v[166:169], v[40:43]
	v_mfma_f32_16x16x32_bf16 v[36:39], v[200:203], v[158:161], v[36:39]
	v_mfma_f32_16x16x32_bf16 v[32:35], v[200:203], v[166:169], v[32:35]
	v_mfma_f32_16x16x32_bf16 v[60:63], v[178:181], v[162:165], v[60:63]
	v_mfma_f32_16x16x32_bf16 v[56:59], v[178:181], v[170:173], v[56:59]
	v_mfma_f32_16x16x32_bf16 v[52:55], v[186:189], v[162:165], v[52:55]
	v_mfma_f32_16x16x32_bf16 v[48:51], v[186:189], v[170:173], v[48:51]
	v_mfma_f32_16x16x32_bf16 v[44:47], v[196:199], v[162:165], v[44:47]
	v_mfma_f32_16x16x32_bf16 v[40:43], v[196:199], v[170:173], v[40:43]
	v_mfma_f32_16x16x32_bf16 v[36:39], v[208:211], v[162:165], v[36:39]
	v_mfma_f32_16x16x32_bf16 v[32:35], v[208:211], v[170:173], v[32:35]
	s_barrier
	s_setprio 0
	v_readfirstlane_b32 s57, v143
	v_lshl_add_u64 v[154:155], v[204:205], 0, s[34:35]
	s_mov_b32 m0, s57
	v_readfirstlane_b32 s57, v148
	global_load_lds_dwordx4 v[154:155], off
	v_lshl_add_u64 v[154:155], v[204:205], 0, s[36:37]
	s_mov_b32 m0, s57
	s_nop 0
	global_load_lds_dwordx4 v[154:155], off
	v_lshl_add_u64 v[154:155], s[52:53], 0, v[128:129]
	s_mov_b64 s[66:67], 0x14602080
	v_lshl_add_u64 v[246:247], v[154:155], 0, s[66:67]
	s_mov_b64 s[66:67], 0x14642080
	v_lshl_add_u64 v[244:245], v[154:155], 0, s[66:67]
	s_waitcnt vmcnt(6)
	s_setprio 1
	s_barrier
	v_mfma_f32_16x16x32_bf16 v[28:31], v[174:177], v[212:215], v[28:31]
	v_mfma_f32_16x16x32_bf16 v[24:27], v[174:177], v[220:223], v[24:27]
	v_mfma_f32_16x16x32_bf16 v[20:23], v[182:185], v[212:215], v[20:23]
	v_mfma_f32_16x16x32_bf16 v[16:19], v[182:185], v[220:223], v[16:19]
	v_mfma_f32_16x16x32_bf16 v[12:15], v[190:193], v[212:215], v[12:15]
	v_mfma_f32_16x16x32_bf16 v[8:11], v[190:193], v[220:223], v[8:11]
	v_mfma_f32_16x16x32_bf16 v[4:7], v[200:203], v[212:215], v[4:7]
	v_mfma_f32_16x16x32_bf16 v[0:3], v[200:203], v[220:223], v[0:3]
	v_mfma_f32_16x16x32_bf16 v[28:31], v[178:181], v[216:219], v[28:31]
	v_mfma_f32_16x16x32_bf16 v[24:27], v[178:181], v[224:227], v[24:27]
	v_mfma_f32_16x16x32_bf16 v[20:23], v[186:189], v[216:219], v[20:23]
	v_mfma_f32_16x16x32_bf16 v[16:19], v[186:189], v[224:227], v[16:19]
	v_mfma_f32_16x16x32_bf16 v[12:15], v[196:199], v[216:219], v[12:15]
	v_mfma_f32_16x16x32_bf16 v[8:11], v[196:199], v[224:227], v[8:11]
	v_mfma_f32_16x16x32_bf16 v[4:7], v[208:211], v[216:219], v[4:7]
	v_mfma_f32_16x16x32_bf16 v[0:3], v[208:211], v[224:227], v[0:3]
	s_barrier
	s_setprio 0
	s_cmp_lt_u32 s56, 28
	s_cbranch_scc1 .LBB0_1378
	s_add_u32 s6, s64, s6
	s_addc_u32 s7, s65, s7
	v_lshl_add_u64 v[136:137], s[6:7], 0, v[156:157]
	v_readfirstlane_b32 s6, v151
	s_mov_b32 m0, s6
	s_add_u32 s6, s64, s42
	v_lshl_add_u64 v[136:137], v[136:137], 0, s[38:39]
	s_addc_u32 s7, s65, s43
	ds_read_b128 v[128:131], v153
	ds_read_b128 v[132:135], v153 offset:1024
	ds_read_b128 v[140:143], v153 offset:2048
	ds_read_b128 v[158:161], v153 offset:3072
	ds_read_b128 v[162:165], v147
	ds_read_b128 v[166:169], v147 offset:1024
	ds_read_b128 v[170:173], v146
	ds_read_b128 v[174:177], v146 offset:1024
	ds_read_b128 v[178:181], v145
	ds_read_b128 v[182:185], v145 offset:1024
	ds_read_b128 v[186:189], v144
	ds_read_b128 v[190:193], v144 offset:1024
	global_load_lds_dwordx4 v[136:137], off
	v_lshl_add_u64 v[136:137], s[6:7], 0, v[156:157]
	v_readfirstlane_b32 s6, v150
	v_lshl_add_u64 v[136:137], v[136:137], 0, s[38:39]
	s_mov_b32 m0, s6
	s_nop 0
	global_load_lds_dwordx4 v[136:137], off
	s_setprio 1
	s_barrier
	s_waitcnt lgkmcnt(0)
	v_mfma_f32_16x16x32_bf16 v[124:127], v[162:165], v[128:131], v[124:127]
	v_mfma_f32_16x16x32_bf16 v[120:123], v[162:165], v[140:143], v[120:123]
	v_mfma_f32_16x16x32_bf16 v[116:119], v[170:173], v[128:131], v[116:119]
	v_mfma_f32_16x16x32_bf16 v[124:127], v[166:169], v[132:135], v[124:127]
	v_mfma_f32_16x16x32_bf16 v[120:123], v[166:169], v[158:161], v[120:123]
	v_mfma_f32_16x16x32_bf16 v[116:119], v[174:177], v[132:135], v[116:119]
	v_mfma_f32_16x16x32_bf16 v[112:115], v[170:173], v[140:143], v[112:115]
	v_mfma_f32_16x16x32_bf16 v[108:111], v[178:181], v[128:131], v[108:111]
	v_mfma_f32_16x16x32_bf16 v[104:107], v[178:181], v[140:143], v[104:107]
	v_mfma_f32_16x16x32_bf16 v[100:103], v[186:189], v[128:131], v[100:103]
	v_mfma_f32_16x16x32_bf16 v[96:99], v[186:189], v[140:143], v[96:99]
	v_mfma_f32_16x16x32_bf16 v[112:115], v[174:177], v[158:161], v[112:115]
	v_mfma_f32_16x16x32_bf16 v[108:111], v[182:185], v[132:135], v[108:111]
	v_mfma_f32_16x16x32_bf16 v[104:107], v[182:185], v[158:161], v[104:107]
	v_mfma_f32_16x16x32_bf16 v[100:103], v[190:193], v[132:135], v[100:103]
	v_mfma_f32_16x16x32_bf16 v[96:99], v[190:193], v[158:161], v[96:99]
	s_barrier
	s_setprio 0
	ds_read_b128 v[196:199], v149
	ds_read_b128 v[200:203], v149 offset:1024
	ds_read_b128 v[208:211], v149 offset:2048
	ds_read_b128 v[148:151], v149 offset:3072
	s_setprio 1
	s_barrier
; #define WAIT_V(n) asm volatile("s_waitcnt vmcnt(" #n ")" ::: "memory")
; #define WAIT_L(n) asm volatile("s_waitcnt lgkmcnt(" #n ")" ::: "memory")
; #define BAR __builtin_amdgcn_s_barrier()
; template <int EPI>
; __device__ __forceinline__ void gemm_tile(const Params& p, const bf16* __restrict__ A, const bf16* __restrict__ Bt, const int K,
;                                           const int nt, const int brow, const int bcol, int pm, int pn) {
;     ...
;     LDB(B1, 0, 1); BAR; WAIT_L(0); MMA(0, 1, At, B1); BAR;
;     LDA(At, 0, 1); WAIT_V(4); BAR; WAIT_L(0); MMA(1, 0, At, B0); MMA(1, 1, At, B1); BAR; }
;   { LDB(B0, 1, 0); LDA(At, 1, 0); WAIT_V(2); BAR; WAIT_L(0); MMA(0, 0, At, B0); BAR;
;     LDB(B1, 1, 1); WAIT_V(0); BAR; WAIT_L(0); MMA(0, 1, At, B1); BAR;
	s_waitcnt lgkmcnt(0)
	v_mfma_f32_16x16x32_bf16 v[92:95], v[162:165], v[196:199], v[92:95]
	v_mfma_f32_16x16x32_bf16 v[88:91], v[162:165], v[208:211], v[88:91]
	v_mfma_f32_16x16x32_bf16 v[84:87], v[170:173], v[196:199], v[84:87]
	v_mfma_f32_16x16x32_bf16 v[76:79], v[178:181], v[196:199], v[76:79]
	v_mfma_f32_16x16x32_bf16 v[92:95], v[166:169], v[200:203], v[92:95]
	v_mfma_f32_16x16x32_bf16 v[88:91], v[166:169], v[148:151], v[88:91]
	v_mfma_f32_16x16x32_bf16 v[84:87], v[174:177], v[200:203], v[84:87]
	v_mfma_f32_16x16x32_bf16 v[80:83], v[170:173], v[208:211], v[80:83]
	v_mfma_f32_16x16x32_bf16 v[76:79], v[182:185], v[200:203], v[76:79]
	v_mfma_f32_16x16x32_bf16 v[72:75], v[178:181], v[208:211], v[72:75]
	v_mfma_f32_16x16x32_bf16 v[68:71], v[186:189], v[196:199], v[68:71]
	v_mfma_f32_16x16x32_bf16 v[64:67], v[186:189], v[208:211], v[64:67]
	v_mfma_f32_16x16x32_bf16 v[162:165], v[174:177], v[148:151], v[80:83]
	v_mfma_f32_16x16x32_bf16 v[166:169], v[182:185], v[148:151], v[72:75]
	v_mfma_f32_16x16x32_bf16 v[170:173], v[190:193], v[200:203], v[68:71]
	v_mfma_f32_16x16x32_bf16 v[174:177], v[190:193], v[148:151], v[64:67]
	s_barrier
	s_setprio 0
	s_nop 1
	ds_read_b128 v[64:67], v147 offset:16384
	ds_read_b128 v[68:71], v147 offset:17408
	ds_read_b128 v[72:75], v146 offset:16384
	ds_read_b128 v[80:83], v146 offset:17408
	ds_read_b128 v[178:181], v145 offset:16384
	ds_read_b128 v[182:185], v145 offset:17408
	ds_read_b128 v[186:189], v144 offset:16384
	ds_read_b128 v[190:193], v144 offset:17408
	s_waitcnt vmcnt(4)
	s_setprio 1
	s_barrier
	s_waitcnt lgkmcnt(0)
	v_mfma_f32_16x16x32_bf16 v[60:63], v[64:67], v[128:131], v[60:63]
	v_mfma_f32_16x16x32_bf16 v[56:59], v[64:67], v[140:143], v[56:59]
	v_mfma_f32_16x16x32_bf16 v[52:55], v[72:75], v[128:131], v[52:55]
	v_mfma_f32_16x16x32_bf16 v[44:47], v[178:181], v[128:131], v[44:47]
	v_mfma_f32_16x16x32_bf16 v[60:63], v[68:71], v[132:135], v[60:63]
	v_mfma_f32_16x16x32_bf16 v[56:59], v[68:71], v[158:161], v[56:59]
	v_mfma_f32_16x16x32_bf16 v[52:55], v[80:83], v[132:135], v[52:55]
	v_mfma_f32_16x16x32_bf16 v[48:51], v[72:75], v[140:143], v[48:51]
	v_mfma_f32_16x16x32_bf16 v[44:47], v[182:185], v[132:135], v[44:47]
	v_mfma_f32_16x16x32_bf16 v[40:43], v[178:181], v[140:143], v[40:43]
	v_mfma_f32_16x16x32_bf16 v[36:39], v[186:189], v[128:131], v[36:39]
	v_mfma_f32_16x16x32_bf16 v[32:35], v[186:189], v[140:143], v[32:35]
	v_mfma_f32_16x16x32_bf16 v[212:215], v[80:83], v[158:161], v[48:51]
	v_mfma_f32_16x16x32_bf16 v[216:219], v[182:185], v[158:161], v[40:43]
	v_mfma_f32_16x16x32_bf16 v[220:223], v[190:193], v[132:135], v[36:39]
	v_mfma_f32_16x16x32_bf16 v[158:161], v[190:193], v[158:161], v[32:35]
	s_setprio 0
	s_setprio 1
	v_mfma_f32_16x16x32_bf16 v[28:31], v[64:67], v[196:199], v[28:31]
	v_mfma_f32_16x16x32_bf16 v[24:27], v[64:67], v[208:211], v[24:27]
	v_mfma_f32_16x16x32_bf16 v[20:23], v[72:75], v[196:199], v[20:23]
	v_mfma_f32_16x16x32_bf16 v[12:15], v[178:181], v[196:199], v[12:15]
	v_mfma_f32_16x16x32_bf16 v[28:31], v[68:71], v[200:203], v[28:31]
	v_mfma_f32_16x16x32_bf16 v[24:27], v[68:71], v[148:151], v[24:27]
	v_mfma_f32_16x16x32_bf16 v[20:23], v[80:83], v[200:203], v[20:23]
	v_mfma_f32_16x16x32_bf16 v[16:19], v[72:75], v[208:211], v[16:19]
	v_mfma_f32_16x16x32_bf16 v[12:15], v[182:185], v[200:203], v[12:15]
	v_mfma_f32_16x16x32_bf16 v[8:11], v[178:181], v[208:211], v[8:11]
	v_mfma_f32_16x16x32_bf16 v[4:7], v[186:189], v[196:199], v[4:7]
	v_mfma_f32_16x16x32_bf16 v[0:3], v[186:189], v[208:211], v[0:3]
	v_mfma_f32_16x16x32_bf16 v[224:227], v[80:83], v[148:151], v[16:19]
	v_mfma_f32_16x16x32_bf16 v[178:181], v[182:185], v[148:151], v[8:11]
	v_mfma_f32_16x16x32_bf16 v[182:185], v[190:193], v[200:203], v[4:7]
	v_mfma_f32_16x16x32_bf16 v[186:189], v[190:193], v[148:151], v[0:3]
	s_barrier
	s_setprio 0
	s_nop 1
	ds_read_b128 v[0:3], v138
	ds_read_b128 v[4:7], v138 offset:1024
	ds_read_b128 v[8:11], v138 offset:2048
	ds_read_b128 v[16:19], v138 offset:3072
	ds_read_b128 v[32:35], v147 offset:32768
	ds_read_b128 v[36:39], v147 offset:33792
	ds_read_b128 v[40:43], v146 offset:32768
	ds_read_b128 v[48:51], v146 offset:33792
	ds_read_b128 v[190:193], v145 offset:32768
	ds_read_b128 v[196:199], v145 offset:33792
	ds_read_b128 v[200:203], v144 offset:32768
	ds_read_b128 v[208:211], v144 offset:33792
	s_waitcnt vmcnt(2)
	s_setprio 1
	s_barrier
; #define WAIT_V(n) asm volatile("s_waitcnt vmcnt(" #n ")" ::: "memory")
; #define WAIT_L(n) asm volatile("s_waitcnt lgkmcnt(" #n ")" ::: "memory")
; #define BAR __builtin_amdgcn_s_barrier()
; template <int EPI>
; __device__ __forceinline__ void gemm_tile(const Params& p, const bf16* __restrict__ A, const bf16* __restrict__ Bt, const int K,
;                                           const int nt, const int brow, const int bcol, int pm, int pn) {
;     ...
;   { LDB(B0, 1, 0); LDA(At, 1, 0); WAIT_V(2); BAR; WAIT_L(0); MMA(0, 0, At, B0); BAR;
;     LDB(B1, 1, 1); WAIT_V(0); BAR; WAIT_L(0); MMA(0, 1, At, B1); BAR;
;     LDA(At, 1, 1); BAR; WAIT_L(0); MMA(1, 0, At, B0); MMA(1, 1, At, B1); BAR; }
;   if (wr == 0) BAR;
	s_waitcnt lgkmcnt(0)
	v_mfma_f32_16x16x32_bf16 v[64:67], v[32:35], v[0:3], v[124:127]
	v_mfma_f32_16x16x32_bf16 v[136:139], v[36:39], v[4:7], v[64:67]
	v_mfma_f32_16x16x32_bf16 v[64:67], v[32:35], v[8:11], v[120:123]
	v_mfma_f32_16x16x32_bf16 v[148:151], v[36:39], v[16:19], v[64:67]
	v_mfma_f32_16x16x32_bf16 v[64:67], v[40:43], v[0:3], v[116:119]
	v_mfma_f32_16x16x32_bf16 v[132:135], v[48:51], v[4:7], v[64:67]
	v_mfma_f32_16x16x32_bf16 v[64:67], v[40:43], v[8:11], v[112:115]
	v_mfma_f32_16x16x32_bf16 v[140:143], v[48:51], v[16:19], v[64:67]
	v_mfma_f32_16x16x32_bf16 v[64:67], v[190:193], v[0:3], v[108:111]
	v_mfma_f32_16x16x32_bf16 v[124:127], v[196:199], v[4:7], v[64:67]
	v_mfma_f32_16x16x32_bf16 v[64:67], v[190:193], v[8:11], v[104:107]
	v_mfma_f32_16x16x32_bf16 v[128:131], v[196:199], v[16:19], v[64:67]
	v_mfma_f32_16x16x32_bf16 v[64:67], v[200:203], v[0:3], v[100:103]
	v_mfma_f32_16x16x32_bf16 v[116:119], v[208:211], v[4:7], v[64:67]
	v_mfma_f32_16x16x32_bf16 v[64:67], v[200:203], v[8:11], v[96:99]
	v_mfma_f32_16x16x32_bf16 v[120:123], v[208:211], v[16:19], v[64:67]
	s_barrier
	s_setprio 0
	ds_read_b128 v[96:99], v152
	ds_read_b128 v[100:103], v152 offset:1024
	ds_read_b128 v[104:107], v152 offset:2048
	ds_read_b128 v[108:111], v152 offset:3072
	s_waitcnt vmcnt(0)
	s_setprio 1
	s_barrier
	s_waitcnt lgkmcnt(0)
	v_mfma_f32_16x16x32_bf16 v[64:67], v[32:35], v[96:99], v[92:95]
	v_mfma_f32_16x16x32_bf16 v[32:35], v[32:35], v[104:107], v[88:91]
	v_mfma_f32_16x16x32_bf16 v[80:83], v[36:39], v[108:111], v[32:35]
	v_mfma_f32_16x16x32_bf16 v[32:35], v[40:43], v[96:99], v[84:87]
	v_mfma_f32_16x16x32_bf16 v[68:71], v[48:51], v[100:103], v[32:35]
	v_mfma_f32_16x16x32_bf16 v[32:35], v[40:43], v[104:107], v[162:165]
	v_mfma_f32_16x16x32_bf16 v[84:87], v[48:51], v[108:111], v[32:35]
	v_mfma_f32_16x16x32_bf16 v[32:35], v[190:193], v[96:99], v[76:79]
	v_mfma_f32_16x16x32_bf16 v[72:75], v[196:199], v[100:103], v[32:35]
	v_mfma_f32_16x16x32_bf16 v[32:35], v[190:193], v[104:107], v[166:169]
	v_mfma_f32_16x16x32_bf16 v[88:91], v[196:199], v[108:111], v[32:35]
	v_mfma_f32_16x16x32_bf16 v[32:35], v[200:203], v[96:99], v[170:173]
	v_mfma_f32_16x16x32_bf16 v[76:79], v[208:211], v[100:103], v[32:35]
	v_mfma_f32_16x16x32_bf16 v[32:35], v[200:203], v[104:107], v[174:177]
	v_mfma_f32_16x16x32_bf16 v[64:67], v[36:39], v[100:103], v[64:67]
	v_mfma_f32_16x16x32_bf16 v[92:95], v[208:211], v[108:111], v[32:35]
	s_barrier
	s_setprio 0
	ds_read_b128 v[112:115], v147 offset:49152
	ds_read_b128 v[152:155], v147 offset:50176
	ds_read_b128 v[162:165], v146 offset:49152
	ds_read_b128 v[166:169], v146 offset:50176
	ds_read_b128 v[170:173], v145 offset:49152
	ds_read_b128 v[174:177], v145 offset:50176
	ds_read_b128 v[190:193], v144 offset:49152
	ds_read_b128 v[144:147], v144 offset:50176
	s_setprio 1
	s_barrier
	s_waitcnt lgkmcnt(0)
	v_mfma_f32_16x16x32_bf16 v[36:39], v[112:115], v[8:11], v[56:59]
	v_mfma_f32_16x16x32_bf16 v[40:43], v[162:165], v[8:11], v[212:215]
	v_mfma_f32_16x16x32_bf16 v[32:35], v[112:115], v[0:3], v[60:63]
	v_mfma_f32_16x16x32_bf16 v[48:51], v[152:155], v[16:19], v[36:39]
	v_mfma_f32_16x16x32_bf16 v[36:39], v[162:165], v[0:3], v[52:55]
	v_mfma_f32_16x16x32_bf16 v[52:55], v[166:169], v[16:19], v[40:43]
	v_mfma_f32_16x16x32_bf16 v[40:43], v[170:173], v[0:3], v[44:47]
	v_mfma_f32_16x16x32_bf16 v[44:47], v[170:173], v[8:11], v[216:219]
	v_mfma_f32_16x16x32_bf16 v[0:3], v[190:193], v[0:3], v[220:223]
	v_mfma_f32_16x16x32_bf16 v[56:59], v[174:177], v[16:19], v[44:47]
	v_mfma_f32_16x16x32_bf16 v[44:47], v[144:147], v[4:7], v[0:3]
	v_mfma_f32_16x16x32_bf16 v[0:3], v[190:193], v[8:11], v[158:161]
	v_mfma_f32_16x16x32_bf16 v[32:35], v[152:155], v[4:7], v[32:35]
	v_mfma_f32_16x16x32_bf16 v[36:39], v[166:169], v[4:7], v[36:39]
	v_mfma_f32_16x16x32_bf16 v[40:43], v[174:177], v[4:7], v[40:43]
	v_mfma_f32_16x16x32_bf16 v[60:63], v[144:147], v[16:19], v[0:3]
	s_setprio 0
	s_setprio 1
	v_mfma_f32_16x16x32_bf16 v[4:7], v[112:115], v[104:107], v[24:27]
	v_mfma_f32_16x16x32_bf16 v[8:11], v[162:165], v[104:107], v[224:227]
	v_mfma_f32_16x16x32_bf16 v[16:19], v[152:155], v[108:111], v[4:7]
	v_mfma_f32_16x16x32_bf16 v[4:7], v[162:165], v[96:99], v[20:23]
	v_mfma_f32_16x16x32_bf16 v[20:23], v[166:169], v[108:111], v[8:11]
	v_mfma_f32_16x16x32_bf16 v[8:11], v[170:173], v[96:99], v[12:15]
	v_mfma_f32_16x16x32_bf16 v[12:15], v[170:173], v[104:107], v[178:181]
	v_mfma_f32_16x16x32_bf16 v[0:3], v[112:115], v[96:99], v[28:31]
	v_mfma_f32_16x16x32_bf16 v[24:27], v[174:177], v[108:111], v[12:15]
	v_mfma_f32_16x16x32_bf16 v[12:15], v[190:193], v[96:99], v[182:185]
	v_mfma_f32_16x16x32_bf16 v[28:31], v[190:193], v[104:107], v[186:189]
	v_mfma_f32_16x16x32_bf16 v[0:3], v[152:155], v[100:103], v[0:3]
	v_mfma_f32_16x16x32_bf16 v[4:7], v[166:169], v[100:103], v[4:7]
	v_mfma_f32_16x16x32_bf16 v[8:11], v[174:177], v[100:103], v[8:11]
	v_mfma_f32_16x16x32_bf16 v[12:15], v[144:147], v[100:103], v[12:15]
	v_mfma_f32_16x16x32_bf16 v[28:31], v[144:147], v[108:111], v[28:31]
	s_barrier
	s_setprio 0
	s_cmpk_gt_u32 s89, 0xff
	s_cbranch_scc1 .LBB0_1381
	s_barrier

; #define WAIT_V(n) asm volatile("s_waitcnt vmcnt(" #n ")" ::: "memory")
; #define BAR __builtin_amdgcn_s_barrier()
; template <int EPI>
; __device__ __forceinline__ void gemm_tile(const Params& p, const bf16* __restrict__ A, const bf16* __restrict__ Bt, const int K,
;                                           const int nt, const int brow, const int bcol, int pm, int pn) {
;     ...
;   const int wid = __builtin_amdgcn_readfirstlane(tid >> 6), lane = tid & 63, wr = wid >> 2, wc = wid & 3, fr = lane & 15, fq = lane >> 4;
;   unsigned toff;
;   { int _r, _c; stage_rc(tid * 16, _r, _c); toff = (unsigned)(_r * K + _c) * 2u; }
;   f32x4 acc[2][2][4][2] = {};
;   float pre0 = 0.f, pre1 = 0.f, pre2 = 0.f;
;   if constexpr (EPI == EPI_GU) {
;     const int base = (pm == 65) ? SEQ : 254 * pm - 2;
;     if (tid < 256) pre0 = P_SSQ(p)[max(base + tid, 0)];
;     else if (tid < 384) { const int c = pn * 128 + tid - 256; pre0 = p.w_ffn_conv[c]; pre1 = p.w_ffn_conv[DFF + c]; pre2 = p.w_ffn_conv[2 * DFF + c]; }
;   }
;   bf16x8 At[4][2], B0[2][2], B1[2][2];
;   STAGE(SB(0, 0), Bt, bcol, 0); STAGE(SA(0, 0), A, brow, 0);
;   STAGE(SB(0, 1), Bt, bcol + HALF, 0); STAGE(SA(0, 1), A, brow + HALF, 0);
;   if (wr == 1) BAR;
;   WAIT_V(4); BAR;
;   STAGE(SB(1, 0), Bt, bcol, 1); STAGE(SA(1, 0), A, brow, 1); STAGE(SB(1, 1), Bt, bcol + HALF, 1);
;   WAIT_V(6); BAR;
.LBB0_1561:
	s_add_u32 s84, s10, s54
	v_add_u32_e32 v146, s67, v4
	s_addc_u32 s85, s11, s55
	v_lshl_add_u64 v[6:7], s[84:85], 0, v[136:137]
	v_readfirstlane_b32 s39, v146
	s_add_u32 s42, s10, s42
	v_lshl_add_u64 v[6:7], v[6:7], 0, s[18:19]
	s_mov_b32 m0, s39
	s_addc_u32 s43, s11, s43
	v_add_u32_e32 v147, 0x2000, v146
	s_waitcnt vmcnt(4)
	s_barrier
	global_load_lds_dwordx4 v[6:7], off
	v_lshl_add_u64 v[6:7], s[42:43], 0, v[136:137]
	v_readfirstlane_b32 s39, v147
	s_add_u32 s42, s60, s50
	v_lshl_add_u64 v[6:7], v[6:7], 0, s[18:19]
	s_mov_b32 m0, s39
	s_addc_u32 s43, s61, s51
	v_add_u32_e32 v148, 0x8000, v132
	global_load_lds_dwordx4 v[6:7], off
	v_lshl_add_u64 v[6:7], s[42:43], 0, v[136:137]
	v_readfirstlane_b32 s39, v148
	s_add_u32 s42, s60, s52
	v_lshl_add_u64 v[6:7], v[6:7], 0, s[18:19]
	s_mov_b32 m0, s39
	s_addc_u32 s43, s61, s53
	global_load_lds_dwordx4 v[6:7], off
	v_lshl_add_u64 v[6:7], s[42:43], 0, v[136:137]
	v_add_u32_e32 v149, 0xa000, v132
	s_add_u32 s42, s10, s48
	v_readfirstlane_b32 s39, v149
	v_add_u32_e32 v150, s68, v4
	s_addc_u32 s43, s11, s49
	v_lshl_add_u64 v[6:7], v[6:7], 0, s[18:19]
	s_mov_b32 m0, s39
	v_lshl_add_u64 v[4:5], s[42:43], 0, v[136:137]
	v_readfirstlane_b32 s39, v150
	s_add_u32 s42, s10, s56
	global_load_lds_dwordx4 v[6:7], off
	v_lshl_add_u64 v[4:5], v[4:5], 0, s[18:19]
	s_mov_b32 m0, s39
	s_addc_u32 s43, s11, s57
	v_add_u32_e32 v151, 0x2000, v150
	global_load_lds_dwordx4 v[4:5], off
	v_lshl_add_u64 v[4:5], s[42:43], 0, v[136:137]
	v_readfirstlane_b32 s39, v151
	v_lshl_add_u64 v[4:5], v[4:5], 0, s[18:19]
	s_mov_b32 m0, s39
	v_and_b32_e32 v8, 15, v0
	global_load_lds_dwordx4 v[4:5], off
	v_and_b32_e32 v9, 48, v0
	v_lshlrev_b32_e32 v5, 2, v0
	s_lshl_b32 s39, s94, 6
	s_lshl_b32 s84, s37, 13
	v_lshlrev_b32_e32 v0, 6, v0
	s_movk_i32 s37, 0x3c0
	s_and_b32 s57, s39, 0x3000
	v_and_or_b32 v0, v0, s37, v9
	s_or_b32 s37, s84, 0x800
	s_or_b32 s39, s84, 0x1000
	s_or_b32 s41, s84, 0x1800
	s_add_u32 s42, s46, s4
	s_addc_u32 s43, s47, s5
	s_add_u32 s48, s46, s6
	v_and_b32_e32 v5, 32, v5
	s_addc_u32 s49, s47, s7
	v_xad_u32 v153, v0, v5, 16
	v_lshlrev_b32_e32 v0, 15, v1
	s_add_u32 s50, s46, s50
	v_and_b32_e32 v0, 0xffff0000, v0
	s_addc_u32 s51, s47, s51
	v_lshlrev_b32_e32 v4, 6, v8
	v_lshl_add_u32 v0, v2, 12, v0
	v_and_b32_e32 v1, 1, v1
	s_add_u32 s52, s46, s52
	s_waitcnt vmcnt(6)
	v_bitop3_b32 v4, v4, v5, v9 bitop3:0x36
	v_lshl_or_b32 v0, v1, 6, v0
	s_addc_u32 s53, s47, s53
	v_add_u32_e32 v6, s65, v4
	v_add_u32_e32 v7, s66, v4
	v_add_u32_e32 v8, s67, v4
	v_add_u32_e32 v10, s68, v4
	v_add_u32_e32 v4, 16, v4
	v_lshl_add_u32 v128, v3, 1, v0
	s_add_u32 s54, s46, s54
	v_mov_b32_e32 v0, 0
	v_mov_b32_e32 v129, v137
	s_addc_u32 s55, s47, s55
	s_mov_b32 s56, -2
	v_add_u32_e32 v154, s57, v6
	v_add_u32_e32 v141, s84, v4
	v_add_u32_e32 v152, s57, v7
	v_add_u32_e32 v145, s57, v8
	v_add_u32_e32 v142, s57, v10
	v_mov_b32_e32 v1, v0
	v_mov_b32_e32 v2, v0
	v_mov_b32_e32 v3, v0
	v_mov_b32_e32 v4, v0
	v_mov_b32_e32 v5, v0
	v_mov_b32_e32 v6, v0
	v_mov_b32_e32 v7, v0
	v_mov_b32_e32 v8, v0
	v_mov_b32_e32 v9, v0
	v_mov_b32_e32 v10, v0
	v_mov_b32_e32 v11, v0
	v_mov_b32_e32 v12, v0
	v_mov_b32_e32 v13, v0
	v_mov_b32_e32 v14, v0
	v_mov_b32_e32 v15, v0
	v_mov_b32_e32 v16, v0
	v_mov_b32_e32 v17, v0
	v_mov_b32_e32 v18, v0
	v_mov_b32_e32 v19, v0
	v_mov_b32_e32 v20, v0
	v_mov_b32_e32 v21, v0
	v_mov_b32_e32 v22, v0
	v_mov_b32_e32 v23, v0
	v_mov_b32_e32 v24, v0
	v_mov_b32_e32 v25, v0
	v_mov_b32_e32 v26, v0
	v_mov_b32_e32 v27, v0
	v_mov_b32_e32 v28, v0
	v_mov_b32_e32 v29, v0
	v_mov_b32_e32 v30, v0
	v_mov_b32_e32 v31, v0
	v_mov_b32_e32 v32, v0
	v_mov_b32_e32 v33, v0
	v_mov_b32_e32 v34, v0
	v_mov_b32_e32 v35, v0
	v_mov_b32_e32 v36, v0
	v_mov_b32_e32 v37, v0
	v_mov_b32_e32 v38, v0
	v_mov_b32_e32 v39, v0
	v_mov_b32_e32 v40, v0
	v_mov_b32_e32 v41, v0
	v_mov_b32_e32 v42, v0
	v_mov_b32_e32 v43, v0
	v_mov_b32_e32 v44, v0
	v_mov_b32_e32 v45, v0
	v_mov_b32_e32 v46, v0
	v_mov_b32_e32 v47, v0
	v_mov_b32_e32 v48, v0
	v_mov_b32_e32 v49, v0
	v_mov_b32_e32 v50, v0
	v_mov_b32_e32 v51, v0
	v_mov_b32_e32 v52, v0
	v_mov_b32_e32 v53, v0
	v_mov_b32_e32 v54, v0
	v_mov_b32_e32 v55, v0
	v_mov_b32_e32 v56, v0
	v_mov_b32_e32 v57, v0
	v_mov_b32_e32 v58, v0
	v_mov_b32_e32 v59, v0
	v_mov_b32_e32 v60, v0
	v_mov_b32_e32 v61, v0
	v_mov_b32_e32 v62, v0
	v_mov_b32_e32 v63, v0
	v_mov_b32_e32 v64, v0
	v_mov_b32_e32 v65, v0
	v_mov_b32_e32 v66, v0
	v_mov_b32_e32 v67, v0
	v_mov_b32_e32 v68, v0
	v_mov_b32_e32 v69, v0
	v_mov_b32_e32 v70, v0
	v_mov_b32_e32 v71, v0
	v_mov_b32_e32 v72, v0
	v_mov_b32_e32 v73, v0
	v_mov_b32_e32 v74, v0
	v_mov_b32_e32 v75, v0
	v_mov_b32_e32 v76, v0
	v_mov_b32_e32 v77, v0
	v_mov_b32_e32 v78, v0
	v_mov_b32_e32 v79, v0
	v_mov_b32_e32 v80, v0
	v_mov_b32_e32 v81, v0
	v_mov_b32_e32 v82, v0
	v_mov_b32_e32 v83, v0
	v_mov_b32_e32 v84, v0
	v_mov_b32_e32 v85, v0
	v_mov_b32_e32 v86, v0
	v_mov_b32_e32 v87, v0
	v_mov_b32_e32 v88, v0
	v_mov_b32_e32 v89, v0
	v_mov_b32_e32 v90, v0
	v_mov_b32_e32 v91, v0
	v_mov_b32_e32 v92, v0
	v_mov_b32_e32 v93, v0
	v_mov_b32_e32 v94, v0
	v_mov_b32_e32 v95, v0
	v_mov_b32_e32 v96, v0
	v_mov_b32_e32 v97, v0
	v_mov_b32_e32 v98, v0
	v_mov_b32_e32 v99, v0
	v_mov_b32_e32 v100, v0
	v_mov_b32_e32 v101, v0
	v_mov_b32_e32 v102, v0
	v_mov_b32_e32 v103, v0
	v_mov_b32_e32 v104, v0
	v_mov_b32_e32 v105, v0
	v_mov_b32_e32 v106, v0
	v_mov_b32_e32 v107, v0
	v_mov_b32_e32 v108, v0
	v_mov_b32_e32 v109, v0
	v_mov_b32_e32 v110, v0
	v_mov_b32_e32 v111, v0
	v_mov_b32_e32 v112, v0
	v_mov_b32_e32 v113, v0
	v_mov_b32_e32 v114, v0
	v_mov_b32_e32 v115, v0
	v_mov_b32_e32 v116, v0
	v_mov_b32_e32 v117, v0
	v_mov_b32_e32 v118, v0
	v_mov_b32_e32 v119, v0
	v_mov_b32_e32 v120, v0
	v_mov_b32_e32 v121, v0
	v_mov_b32_e32 v122, v0
	v_mov_b32_e32 v123, v0
	v_mov_b32_e32 v124, v0
	v_mov_b32_e32 v125, v0
	v_mov_b32_e32 v126, v0
	v_mov_b32_e32 v127, v0
	s_barrier
	v_add_u32_e32 v159, 0xc000, v132
	v_add_u32_e32 v158, 0xe000, v132
	v_add_u32_e32 v155, s37, v153
	v_add_u32_e32 v156, s39, v153
	v_add_u32_e32 v157, s41, v153
	v_lshl_add_u64 v[204:205], s[42:43], 0, v[128:129]
	v_lshl_add_u64 v[246:247], v[204:205], 0, s[20:21]
	v_lshl_add_u64 v[232:233], s[48:49], 0, v[128:129]
	v_lshl_add_u64 v[244:245], v[232:233], 0, s[20:21]
	v_readfirstlane_b32 s98, v158
	v_readfirstlane_b32 s99, v159
	v_readfirstlane_b32 s100, v143
	v_readfirstlane_b32 s101, v144
; #define WAIT_L(n) asm volatile("s_waitcnt lgkmcnt(" #n ")" ::: "memory")
; #define BAR __builtin_amdgcn_s_barrier()
; #define SCHED __builtin_amdgcn_sched_barrier(0)
; template <int EPI>
; __device__ __forceinline__ void gemm_tile(const Params& p, const bf16* __restrict__ A, const bf16* __restrict__ Bt, const int K,
;                                           const int nt, const int brow, const int bcol, int pm, int pn) {
;     ...
;   for (int t = 0; t < nt - 2; t += 2) {
;     LDB(B0, 0, 0); SCHED; LDA(At, 0, 0); STAGE(SA(1, 1), A, brow + HALF, t + 1);
;     WAIT_L(8); BAR; WAIT_L(0); MMA(0, 0, At, B0); BAR; SCHED;
;     LDB(B1, 0, 1); STAGE(SB(0, 0), Bt, bcol, t + 2);
;     BAR; WAIT_L(0); MMA(0, 1, At, B1); BAR;
;     LDA(At, 0, 1); STAGE(SA(0, 0), A, brow, t + 2);
.LBB0_1562:
	ds_read_b128 v[162:165], v154
	ds_read_b128 v[166:169], v154 offset:1024
	ds_read_b128 v[170:173], v154 offset:2048
	ds_read_b128 v[174:177], v154 offset:3072
	s_mov_b32 m0, s99
	ds_read_b128 v[178:181], v141
	ds_read_b128 v[182:185], v141 offset:1024
	ds_read_b128 v[186:189], v155
	ds_read_b128 v[190:193], v155 offset:1024
	ds_read_b128 v[196:199], v156
	ds_read_b128 v[200:203], v156 offset:1024
	ds_read_b128 v[208:211], v157
	ds_read_b128 v[212:215], v157 offset:1024
	global_load_lds_dwordx4 v[246:247], off
	s_mov_b32 m0, s98
	s_nop 0
	global_load_lds_dwordx4 v[244:245], off
	s_waitcnt lgkmcnt(8)
	s_setprio 1
	s_barrier
	s_waitcnt lgkmcnt(0)
	v_mfma_f32_16x16x32_bf16 v[124:127], v[178:181], v[162:165], v[124:127]
	v_mfma_f32_16x16x32_bf16 v[120:123], v[178:181], v[170:173], v[120:123]
	v_mfma_f32_16x16x32_bf16 v[116:119], v[186:189], v[162:165], v[116:119]
	v_mfma_f32_16x16x32_bf16 v[112:115], v[186:189], v[170:173], v[112:115]
	v_mfma_f32_16x16x32_bf16 v[108:111], v[196:199], v[162:165], v[108:111]
	v_mfma_f32_16x16x32_bf16 v[104:107], v[196:199], v[170:173], v[104:107]
	v_mfma_f32_16x16x32_bf16 v[100:103], v[208:211], v[162:165], v[100:103]
	v_mfma_f32_16x16x32_bf16 v[96:99], v[208:211], v[170:173], v[96:99]
	v_mfma_f32_16x16x32_bf16 v[124:127], v[182:185], v[166:169], v[124:127]
	v_mfma_f32_16x16x32_bf16 v[120:123], v[182:185], v[174:177], v[120:123]
	v_mfma_f32_16x16x32_bf16 v[116:119], v[190:193], v[166:169], v[116:119]
	v_mfma_f32_16x16x32_bf16 v[112:115], v[190:193], v[174:177], v[112:115]
	v_mfma_f32_16x16x32_bf16 v[108:111], v[200:203], v[166:169], v[108:111]
	v_mfma_f32_16x16x32_bf16 v[104:107], v[200:203], v[174:177], v[104:107]
	v_mfma_f32_16x16x32_bf16 v[100:103], v[212:215], v[166:169], v[100:103]
	v_mfma_f32_16x16x32_bf16 v[96:99], v[212:215], v[174:177], v[96:99]
	s_barrier
	s_setprio 0
	v_lshl_add_u64 v[234:235], s[54:55], 0, v[128:129]
	s_mov_b64 s[84:85], 0x2000100
	v_readfirstlane_b32 s57, v130
	v_lshl_add_u64 v[236:237], v[234:235], 0, s[84:85]
	s_mov_b32 m0, s57
	s_mov_b64 s[84:85], 0x2040100
	v_readfirstlane_b32 s57, v131
	ds_read_b128 v[216:219], v152
	ds_read_b128 v[220:223], v152 offset:1024
	ds_read_b128 v[224:227], v152 offset:2048
	ds_read_b128 v[228:231], v152 offset:3072
	global_load_lds_dwordx4 v[236:237], off
	v_lshl_add_u64 v[236:237], v[234:235], 0, s[84:85]
	s_mov_b32 m0, s57
	s_nop 0
	global_load_lds_dwordx4 v[236:237], off
	v_lshl_add_u64 v[236:237], s[50:51], 0, v[128:129]
	v_readfirstlane_b32 s57, v132
	v_lshl_add_u64 v[238:239], v[236:237], 0, s[22:23]
	s_mov_b32 m0, s57
	s_setprio 1
	s_barrier
	s_waitcnt lgkmcnt(0)
	v_mfma_f32_16x16x32_bf16 v[92:95], v[178:181], v[216:219], v[92:95]
	v_mfma_f32_16x16x32_bf16 v[88:91], v[178:181], v[224:227], v[88:91]
	v_mfma_f32_16x16x32_bf16 v[84:87], v[186:189], v[216:219], v[84:87]
	v_mfma_f32_16x16x32_bf16 v[80:83], v[186:189], v[224:227], v[80:83]
	v_mfma_f32_16x16x32_bf16 v[76:79], v[196:199], v[216:219], v[76:79]
	v_mfma_f32_16x16x32_bf16 v[72:75], v[196:199], v[224:227], v[72:75]
	v_mfma_f32_16x16x32_bf16 v[68:71], v[208:211], v[216:219], v[68:71]
	v_mfma_f32_16x16x32_bf16 v[64:67], v[208:211], v[224:227], v[64:67]
	v_mfma_f32_16x16x32_bf16 v[92:95], v[182:185], v[220:223], v[92:95]
	v_mfma_f32_16x16x32_bf16 v[88:91], v[182:185], v[228:231], v[88:91]
	v_mfma_f32_16x16x32_bf16 v[84:87], v[190:193], v[220:223], v[84:87]
	v_mfma_f32_16x16x32_bf16 v[80:83], v[190:193], v[228:231], v[80:83]
	v_mfma_f32_16x16x32_bf16 v[76:79], v[200:203], v[220:223], v[76:79]
	v_mfma_f32_16x16x32_bf16 v[72:75], v[200:203], v[228:231], v[72:75]
	v_mfma_f32_16x16x32_bf16 v[68:71], v[212:215], v[220:223], v[68:71]
	v_mfma_f32_16x16x32_bf16 v[64:67], v[212:215], v[228:231], v[64:67]
	s_barrier
	s_setprio 0
	ds_read_b128 v[178:181], v141 offset:16384
	ds_read_b128 v[182:185], v141 offset:17408
	ds_read_b128 v[186:189], v155 offset:16384
	ds_read_b128 v[190:193], v155 offset:17408
	ds_read_b128 v[196:199], v156 offset:16384
	ds_read_b128 v[200:203], v156 offset:17408
	ds_read_b128 v[208:211], v157 offset:16384
	ds_read_b128 v[212:215], v157 offset:17408
	global_load_lds_dwordx4 v[238:239], off
	v_lshl_add_u64 v[238:239], s[52:53], 0, v[128:129]
	v_readfirstlane_b32 s57, v133
	v_lshl_add_u64 v[240:241], v[238:239], 0, s[22:23]
	s_mov_b32 m0, s57
	s_nop 0
	global_load_lds_dwordx4 v[240:241], off
	s_setprio 1
	s_barrier
	s_waitcnt lgkmcnt(0)
	v_mfma_f32_16x16x32_bf16 v[60:63], v[178:181], v[162:165], v[60:63]
	v_mfma_f32_16x16x32_bf16 v[56:59], v[178:181], v[170:173], v[56:59]
	v_mfma_f32_16x16x32_bf16 v[52:55], v[186:189], v[162:165], v[52:55]
	v_mfma_f32_16x16x32_bf16 v[48:51], v[186:189], v[170:173], v[48:51]
	v_mfma_f32_16x16x32_bf16 v[44:47], v[196:199], v[162:165], v[44:47]
	v_mfma_f32_16x16x32_bf16 v[40:43], v[196:199], v[170:173], v[40:43]
	v_mfma_f32_16x16x32_bf16 v[36:39], v[208:211], v[162:165], v[36:39]
	v_mfma_f32_16x16x32_bf16 v[32:35], v[208:211], v[170:173], v[32:35]
	v_mfma_f32_16x16x32_bf16 v[60:63], v[182:185], v[166:169], v[60:63]
	v_mfma_f32_16x16x32_bf16 v[56:59], v[182:185], v[174:177], v[56:59]
	v_mfma_f32_16x16x32_bf16 v[52:55], v[190:193], v[166:169], v[52:55]
	v_mfma_f32_16x16x32_bf16 v[48:51], v[190:193], v[174:177], v[48:51]
	v_mfma_f32_16x16x32_bf16 v[44:47], v[200:203], v[166:169], v[44:47]
	v_mfma_f32_16x16x32_bf16 v[40:43], v[200:203], v[174:177], v[40:43]
	v_mfma_f32_16x16x32_bf16 v[36:39], v[212:215], v[166:169], v[36:39]
	v_mfma_f32_16x16x32_bf16 v[32:35], v[212:215], v[174:177], v[32:35]
	s_barrier
; #define WAIT_V(n) asm volatile("s_waitcnt vmcnt(" #n ")" ::: "memory")
; #define WAIT_L(n) asm volatile("s_waitcnt lgkmcnt(" #n ")" ::: "memory")
; #define BAR __builtin_amdgcn_s_barrier()
; #define SCHED __builtin_amdgcn_sched_barrier(0)
; template <int EPI>
; __device__ __forceinline__ void gemm_tile(const Params& p, const bf16* __restrict__ A, const bf16* __restrict__ Bt, const int K,
;                                           const int nt, const int brow, const int bcol, int pm, int pn) {
;     ...
;     BAR; WAIT_L(0); MMA(1, 0, At, B0); BAR; SCHED;
;     STAGE(SB(0, 1), Bt, bcol + HALF, t + 2);
;     WAIT_V(6); BAR; MMA(1, 1, At, B1); BAR;
;     LDB(B0, 1, 0); SCHED; LDA(At, 1, 0); STAGE(SA(0, 1), A, brow + HALF, t + 2);
;     WAIT_L(8); BAR; WAIT_L(0); MMA(0, 0, At, B0); BAR; SCHED;
;     LDB(B1, 1, 1); STAGE(SB(1, 0), Bt, bcol, t + 3);
;     BAR; WAIT_L(0); MMA(0, 1, At, B1); BAR;
;     LDA(At, 1, 1); STAGE(SA(1, 0), A, brow, t + 3);
	s_setprio 0
	s_add_i32 s56, s56, 2
	s_add_u32 s42, s42, 0x100
	s_addc_u32 s43, s43, 0
	s_add_u32 s48, s48, 0x100
	s_addc_u32 s49, s49, 0
	s_add_u32 s50, s50, 0x100
	s_addc_u32 s51, s51, 0
	s_add_u32 s52, s52, 0x100
	s_addc_u32 s53, s53, 0
	s_add_u32 s54, s54, 0x100
	s_addc_u32 s55, s55, 0
	s_mov_b64 s[84:85], 0x2080100
	v_readfirstlane_b32 s57, v134
	v_lshl_add_u64 v[162:163], v[234:235], 0, s[84:85]
	s_mov_b32 m0, s57
	s_mov_b64 s[84:85], 0x20c0100
	v_readfirstlane_b32 s57, v135
	global_load_lds_dwordx4 v[162:163], off
	v_lshl_add_u64 v[162:163], v[234:235], 0, s[84:85]
	s_mov_b32 m0, s57
	s_nop 0
	global_load_lds_dwordx4 v[162:163], off
	v_lshl_add_u64 v[248:249], v[204:205], 0, s[22:23]
	v_lshl_add_u64 v[250:251], v[232:233], 0, s[22:23]
	s_waitcnt vmcnt(6)
	s_setprio 1
	s_barrier
	v_mfma_f32_16x16x32_bf16 v[28:31], v[178:181], v[216:219], v[28:31]
	v_mfma_f32_16x16x32_bf16 v[24:27], v[178:181], v[224:227], v[24:27]
	v_mfma_f32_16x16x32_bf16 v[20:23], v[186:189], v[216:219], v[20:23]
	v_mfma_f32_16x16x32_bf16 v[16:19], v[186:189], v[224:227], v[16:19]
	v_mfma_f32_16x16x32_bf16 v[12:15], v[196:199], v[216:219], v[12:15]
	v_mfma_f32_16x16x32_bf16 v[8:11], v[196:199], v[224:227], v[8:11]
	v_mfma_f32_16x16x32_bf16 v[4:7], v[208:211], v[216:219], v[4:7]
	v_mfma_f32_16x16x32_bf16 v[0:3], v[208:211], v[224:227], v[0:3]
	v_mfma_f32_16x16x32_bf16 v[28:31], v[182:185], v[220:223], v[28:31]
	v_mfma_f32_16x16x32_bf16 v[24:27], v[182:185], v[228:231], v[24:27]
	v_mfma_f32_16x16x32_bf16 v[20:23], v[190:193], v[220:223], v[20:23]
	v_mfma_f32_16x16x32_bf16 v[16:19], v[190:193], v[228:231], v[16:19]
	v_mfma_f32_16x16x32_bf16 v[12:15], v[200:203], v[220:223], v[12:15]
	v_mfma_f32_16x16x32_bf16 v[8:11], v[200:203], v[228:231], v[8:11]
	v_mfma_f32_16x16x32_bf16 v[4:7], v[212:215], v[220:223], v[4:7]
	v_mfma_f32_16x16x32_bf16 v[0:3], v[212:215], v[228:231], v[0:3]
	s_barrier
	s_setprio 0
	ds_read_b128 v[162:165], v145
	ds_read_b128 v[166:169], v145 offset:1024
	ds_read_b128 v[170:173], v145 offset:2048
	ds_read_b128 v[174:177], v145 offset:3072
	s_mov_b32 m0, s100
	ds_read_b128 v[178:181], v141 offset:32768
	ds_read_b128 v[182:185], v141 offset:33792
	ds_read_b128 v[186:189], v155 offset:32768
	ds_read_b128 v[190:193], v155 offset:33792
	ds_read_b128 v[196:199], v156 offset:32768
	ds_read_b128 v[200:203], v156 offset:33792
	ds_read_b128 v[208:211], v157 offset:32768
	ds_read_b128 v[212:215], v157 offset:33792
	global_load_lds_dwordx4 v[248:249], off
	s_mov_b32 m0, s101
	s_nop 0
	global_load_lds_dwordx4 v[250:251], off
	s_waitcnt lgkmcnt(8)
	s_setprio 1
	s_barrier
	s_waitcnt lgkmcnt(0)
	v_mfma_f32_16x16x32_bf16 v[124:127], v[178:181], v[162:165], v[124:127]
	v_mfma_f32_16x16x32_bf16 v[120:123], v[178:181], v[170:173], v[120:123]
	v_mfma_f32_16x16x32_bf16 v[116:119], v[186:189], v[162:165], v[116:119]
	v_mfma_f32_16x16x32_bf16 v[112:115], v[186:189], v[170:173], v[112:115]
	v_mfma_f32_16x16x32_bf16 v[108:111], v[196:199], v[162:165], v[108:111]
	v_mfma_f32_16x16x32_bf16 v[104:107], v[196:199], v[170:173], v[104:107]
	v_mfma_f32_16x16x32_bf16 v[100:103], v[208:211], v[162:165], v[100:103]
	v_mfma_f32_16x16x32_bf16 v[96:99], v[208:211], v[170:173], v[96:99]
	v_mfma_f32_16x16x32_bf16 v[124:127], v[182:185], v[166:169], v[124:127]
	v_mfma_f32_16x16x32_bf16 v[120:123], v[182:185], v[174:177], v[120:123]
	v_mfma_f32_16x16x32_bf16 v[116:119], v[190:193], v[166:169], v[116:119]
	v_mfma_f32_16x16x32_bf16 v[112:115], v[190:193], v[174:177], v[112:115]
	v_mfma_f32_16x16x32_bf16 v[108:111], v[200:203], v[166:169], v[108:111]
	v_mfma_f32_16x16x32_bf16 v[104:107], v[200:203], v[174:177], v[104:107]
	v_mfma_f32_16x16x32_bf16 v[100:103], v[212:215], v[166:169], v[100:103]
	v_mfma_f32_16x16x32_bf16 v[96:99], v[212:215], v[174:177], v[96:99]
	s_barrier
	s_setprio 0
	s_mov_b64 s[84:85], 0x2000180
	v_readfirstlane_b32 s57, v146
	v_lshl_add_u64 v[204:205], v[234:235], 0, s[84:85]
	s_mov_b32 m0, s57
	s_mov_b64 s[84:85], 0x2040180
	v_readfirstlane_b32 s57, v147
	ds_read_b128 v[216:219], v142
	ds_read_b128 v[220:223], v142 offset:1024
	ds_read_b128 v[224:227], v142 offset:2048
	ds_read_b128 v[228:231], v142 offset:3072
	global_load_lds_dwordx4 v[204:205], off
	v_lshl_add_u64 v[204:205], v[234:235], 0, s[84:85]
	s_mov_b32 m0, s57
	s_nop 0
	global_load_lds_dwordx4 v[204:205], off
	v_readfirstlane_b32 s57, v148
	v_lshl_add_u64 v[204:205], v[236:237], 0, s[24:25]
	s_mov_b32 m0, s57
	v_readfirstlane_b32 s57, v149
	s_setprio 1
	s_barrier
	s_waitcnt lgkmcnt(0)
	v_mfma_f32_16x16x32_bf16 v[92:95], v[178:181], v[216:219], v[92:95]
	v_mfma_f32_16x16x32_bf16 v[88:91], v[178:181], v[224:227], v[88:91]
	v_mfma_f32_16x16x32_bf16 v[84:87], v[186:189], v[216:219], v[84:87]
	v_mfma_f32_16x16x32_bf16 v[80:83], v[186:189], v[224:227], v[80:83]
	v_mfma_f32_16x16x32_bf16 v[76:79], v[196:199], v[216:219], v[76:79]
	v_mfma_f32_16x16x32_bf16 v[72:75], v[196:199], v[224:227], v[72:75]
	v_mfma_f32_16x16x32_bf16 v[68:71], v[208:211], v[216:219], v[68:71]
	v_mfma_f32_16x16x32_bf16 v[64:67], v[208:211], v[224:227], v[64:67]
	v_mfma_f32_16x16x32_bf16 v[92:95], v[182:185], v[220:223], v[92:95]
	v_mfma_f32_16x16x32_bf16 v[88:91], v[182:185], v[228:231], v[88:91]
	v_mfma_f32_16x16x32_bf16 v[84:87], v[190:193], v[220:223], v[84:87]
	v_mfma_f32_16x16x32_bf16 v[80:83], v[190:193], v[228:231], v[80:83]
	v_mfma_f32_16x16x32_bf16 v[76:79], v[200:203], v[220:223], v[76:79]
	v_mfma_f32_16x16x32_bf16 v[72:75], v[200:203], v[228:231], v[72:75]
	v_mfma_f32_16x16x32_bf16 v[68:71], v[212:215], v[220:223], v[68:71]
	v_mfma_f32_16x16x32_bf16 v[64:67], v[212:215], v[228:231], v[64:67]
	s_barrier
; #define WAIT_V(n) asm volatile("s_waitcnt vmcnt(" #n ")" ::: "memory")
; #define WAIT_L(n) asm volatile("s_waitcnt lgkmcnt(" #n ")" ::: "memory")
; #define BAR __builtin_amdgcn_s_barrier()
; #define SCHED __builtin_amdgcn_sched_barrier(0)
; template <int EPI>
; __device__ __forceinline__ void gemm_tile(const Params& p, const bf16* __restrict__ A, const bf16* __restrict__ Bt, const int K,
;                                           const int nt, const int brow, const int bcol, int pm, int pn) {
;     ...
;     BAR; WAIT_L(0); MMA(1, 0, At, B0); BAR; SCHED;
;     STAGE(SB(1, 1), Bt, bcol + HALF, t + 3);
;     WAIT_V(6); BAR; MMA(1, 1, At, B1); BAR;
;   }
;   { LDB(B0, 0, 0); LDA(At, 0, 0); STAGE(SA(1, 1), A, brow + HALF, nt - 1);
;     BAR; WAIT_L(0); MMA(0, 0, At, B0); BAR;
	s_setprio 0
	ds_read_b128 v[178:181], v141 offset:49152
	ds_read_b128 v[182:185], v141 offset:50176
	ds_read_b128 v[186:189], v155 offset:49152
	ds_read_b128 v[190:193], v155 offset:50176
	ds_read_b128 v[196:199], v156 offset:49152
	ds_read_b128 v[200:203], v156 offset:50176
	ds_read_b128 v[208:211], v157 offset:49152
	ds_read_b128 v[212:215], v157 offset:50176
	global_load_lds_dwordx4 v[204:205], off
	v_lshl_add_u64 v[204:205], v[238:239], 0, s[24:25]
	s_mov_b32 m0, s57
	s_nop 0
	global_load_lds_dwordx4 v[204:205], off
	s_setprio 1
	s_barrier
	s_waitcnt lgkmcnt(0)
	v_mfma_f32_16x16x32_bf16 v[60:63], v[178:181], v[162:165], v[60:63]
	v_mfma_f32_16x16x32_bf16 v[56:59], v[178:181], v[170:173], v[56:59]
	v_mfma_f32_16x16x32_bf16 v[52:55], v[186:189], v[162:165], v[52:55]
	v_mfma_f32_16x16x32_bf16 v[48:51], v[186:189], v[170:173], v[48:51]
	v_mfma_f32_16x16x32_bf16 v[44:47], v[196:199], v[162:165], v[44:47]
	v_mfma_f32_16x16x32_bf16 v[40:43], v[196:199], v[170:173], v[40:43]
	v_mfma_f32_16x16x32_bf16 v[36:39], v[208:211], v[162:165], v[36:39]
	v_mfma_f32_16x16x32_bf16 v[32:35], v[208:211], v[170:173], v[32:35]
	v_mfma_f32_16x16x32_bf16 v[60:63], v[182:185], v[166:169], v[60:63]
	v_mfma_f32_16x16x32_bf16 v[56:59], v[182:185], v[174:177], v[56:59]
	v_mfma_f32_16x16x32_bf16 v[52:55], v[190:193], v[166:169], v[52:55]
	v_mfma_f32_16x16x32_bf16 v[48:51], v[190:193], v[174:177], v[48:51]
	v_mfma_f32_16x16x32_bf16 v[44:47], v[200:203], v[166:169], v[44:47]
	v_mfma_f32_16x16x32_bf16 v[40:43], v[200:203], v[174:177], v[40:43]
	v_mfma_f32_16x16x32_bf16 v[36:39], v[212:215], v[166:169], v[36:39]
	v_mfma_f32_16x16x32_bf16 v[32:35], v[212:215], v[174:177], v[32:35]
	s_barrier
	s_setprio 0
	s_mov_b64 s[84:85], 0x2080180
	v_readfirstlane_b32 s57, v150
	v_lshl_add_u64 v[162:163], v[234:235], 0, s[84:85]
	s_mov_b32 m0, s57
	v_readfirstlane_b32 s57, v151
	global_load_lds_dwordx4 v[162:163], off
	v_lshl_add_u64 v[162:163], v[234:235], 0, s[26:27]
	s_mov_b32 m0, s57
	s_nop 0
	global_load_lds_dwordx4 v[162:163], off
	v_lshl_add_u64 v[204:205], s[42:43], 0, v[128:129]
	v_lshl_add_u64 v[246:247], v[204:205], 0, s[20:21]
	v_lshl_add_u64 v[232:233], s[48:49], 0, v[128:129]
	v_lshl_add_u64 v[244:245], v[232:233], 0, s[20:21]
	s_waitcnt vmcnt(6)
	s_setprio 1
	s_barrier
	v_mfma_f32_16x16x32_bf16 v[28:31], v[178:181], v[216:219], v[28:31]
	v_mfma_f32_16x16x32_bf16 v[24:27], v[178:181], v[224:227], v[24:27]
	v_mfma_f32_16x16x32_bf16 v[20:23], v[186:189], v[216:219], v[20:23]
	v_mfma_f32_16x16x32_bf16 v[16:19], v[186:189], v[224:227], v[16:19]
	v_mfma_f32_16x16x32_bf16 v[12:15], v[196:199], v[216:219], v[12:15]
	v_mfma_f32_16x16x32_bf16 v[8:11], v[196:199], v[224:227], v[8:11]
	v_mfma_f32_16x16x32_bf16 v[4:7], v[208:211], v[216:219], v[4:7]
	v_mfma_f32_16x16x32_bf16 v[0:3], v[208:211], v[224:227], v[0:3]
	v_mfma_f32_16x16x32_bf16 v[28:31], v[182:185], v[220:223], v[28:31]
	v_mfma_f32_16x16x32_bf16 v[24:27], v[182:185], v[228:231], v[24:27]
	v_mfma_f32_16x16x32_bf16 v[20:23], v[190:193], v[220:223], v[20:23]
	v_mfma_f32_16x16x32_bf16 v[16:19], v[190:193], v[228:231], v[16:19]
	v_mfma_f32_16x16x32_bf16 v[12:15], v[200:203], v[220:223], v[12:15]
	v_mfma_f32_16x16x32_bf16 v[8:11], v[200:203], v[228:231], v[8:11]
	v_mfma_f32_16x16x32_bf16 v[4:7], v[212:215], v[220:223], v[4:7]
	v_mfma_f32_16x16x32_bf16 v[0:3], v[212:215], v[228:231], v[0:3]
	s_barrier
	s_setprio 0
	s_cmp_lt_u32 s56, 28
	s_cbranch_scc1 .LBB0_1562
	s_add_u32 s4, s60, s4
	s_addc_u32 s5, s61, s5
	v_lshl_add_u64 v[150:151], s[4:5], 0, v[136:137]
	v_readfirstlane_b32 s4, v159
	s_mov_b32 m0, s4
	s_add_u32 s4, s60, s6
	v_lshl_add_u64 v[150:151], v[150:151], 0, s[28:29]
	s_addc_u32 s5, s61, s7
	ds_read_b128 v[128:131], v154
	ds_read_b128 v[132:135], v154 offset:1024
	ds_read_b128 v[146:149], v154 offset:2048
	ds_read_b128 v[162:165], v154 offset:3072
	ds_read_b128 v[166:169], v141
	ds_read_b128 v[170:173], v141 offset:1024
	ds_read_b128 v[174:177], v155
	ds_read_b128 v[178:181], v155 offset:1024
	ds_read_b128 v[182:185], v156
	ds_read_b128 v[186:189], v156 offset:1024
	ds_read_b128 v[190:193], v157
	ds_read_b128 v[196:199], v157 offset:1024
	global_load_lds_dwordx4 v[150:151], off
	v_lshl_add_u64 v[150:151], s[4:5], 0, v[136:137]
	v_readfirstlane_b32 s4, v158
	v_lshl_add_u64 v[150:151], v[150:151], 0, s[28:29]
	s_mov_b32 m0, s4
	s_nop 0
	global_load_lds_dwordx4 v[150:151], off
	s_setprio 1
	s_barrier
	s_waitcnt lgkmcnt(0)
	v_mfma_f32_16x16x32_bf16 v[124:127], v[166:169], v[128:131], v[124:127]
	v_mfma_f32_16x16x32_bf16 v[120:123], v[166:169], v[146:149], v[120:123]
	v_mfma_f32_16x16x32_bf16 v[116:119], v[174:177], v[128:131], v[116:119]
	v_mfma_f32_16x16x32_bf16 v[112:115], v[174:177], v[146:149], v[112:115]
	v_mfma_f32_16x16x32_bf16 v[108:111], v[182:185], v[128:131], v[108:111]
	v_mfma_f32_16x16x32_bf16 v[104:107], v[182:185], v[146:149], v[104:107]
	v_mfma_f32_16x16x32_bf16 v[124:127], v[170:173], v[132:135], v[124:127]
	v_mfma_f32_16x16x32_bf16 v[120:123], v[170:173], v[162:165], v[120:123]
	v_mfma_f32_16x16x32_bf16 v[116:119], v[178:181], v[132:135], v[116:119]
	v_mfma_f32_16x16x32_bf16 v[112:115], v[178:181], v[162:165], v[112:115]
	v_mfma_f32_16x16x32_bf16 v[108:111], v[186:189], v[132:135], v[108:111]
	v_mfma_f32_16x16x32_bf16 v[104:107], v[186:189], v[162:165], v[104:107]
	v_mfma_f32_16x16x32_bf16 v[100:103], v[190:193], v[128:131], v[100:103]
	v_mfma_f32_16x16x32_bf16 v[96:99], v[190:193], v[146:149], v[96:99]
	v_mfma_f32_16x16x32_bf16 v[100:103], v[196:199], v[132:135], v[100:103]
	v_mfma_f32_16x16x32_bf16 v[96:99], v[196:199], v[162:165], v[96:99]
	s_barrier
; #define WAIT_V(n) asm volatile("s_waitcnt vmcnt(" #n ")" ::: "memory")
; #define WAIT_L(n) asm volatile("s_waitcnt lgkmcnt(" #n ")" ::: "memory")
; #define BAR __builtin_amdgcn_s_barrier()
; template <int EPI>
; __device__ __forceinline__ void gemm_tile(const Params& p, const bf16* __restrict__ A, const bf16* __restrict__ Bt, const int K,
;                                           const int nt, const int brow, const int bcol, int pm, int pn) {
;     ...
;     LDB(B1, 0, 1); BAR; WAIT_L(0); MMA(0, 1, At, B1); BAR;
;     LDA(At, 0, 1); WAIT_V(4); BAR; WAIT_L(0); MMA(1, 0, At, B0); MMA(1, 1, At, B1); BAR; }
;   { LDB(B0, 1, 0); LDA(At, 1, 0); WAIT_V(2); BAR; WAIT_L(0); MMA(0, 0, At, B0); BAR;
;     LDB(B1, 1, 1); WAIT_V(0); BAR; WAIT_L(0); MMA(0, 1, At, B1); BAR;
	s_setprio 0
	ds_read_b128 v[200:203], v152
	ds_read_b128 v[208:211], v152 offset:1024
	ds_read_b128 v[212:215], v152 offset:2048
	ds_read_b128 v[150:153], v152 offset:3072
	s_setprio 1
	s_barrier
	s_waitcnt lgkmcnt(0)
	v_mfma_f32_16x16x32_bf16 v[92:95], v[166:169], v[200:203], v[92:95]
	v_mfma_f32_16x16x32_bf16 v[88:91], v[166:169], v[212:215], v[88:91]
	v_mfma_f32_16x16x32_bf16 v[68:71], v[190:193], v[200:203], v[68:71]
	v_mfma_f32_16x16x32_bf16 v[92:95], v[170:173], v[208:211], v[92:95]
	v_mfma_f32_16x16x32_bf16 v[88:91], v[170:173], v[150:153], v[88:91]
	v_mfma_f32_16x16x32_bf16 v[84:87], v[174:177], v[200:203], v[84:87]
	v_mfma_f32_16x16x32_bf16 v[80:83], v[174:177], v[212:215], v[80:83]
	v_mfma_f32_16x16x32_bf16 v[76:79], v[182:185], v[200:203], v[76:79]
	v_mfma_f32_16x16x32_bf16 v[72:75], v[182:185], v[212:215], v[72:75]
	v_mfma_f32_16x16x32_bf16 v[68:71], v[196:199], v[208:211], v[68:71]
	v_mfma_f32_16x16x32_bf16 v[64:67], v[190:193], v[212:215], v[64:67]
	v_mfma_f32_16x16x32_bf16 v[166:169], v[178:181], v[208:211], v[84:87]
	v_mfma_f32_16x16x32_bf16 v[170:173], v[178:181], v[150:153], v[80:83]
	v_mfma_f32_16x16x32_bf16 v[174:177], v[186:189], v[208:211], v[76:79]
	v_mfma_f32_16x16x32_bf16 v[178:181], v[186:189], v[150:153], v[72:75]
	v_mfma_f32_16x16x32_bf16 v[182:185], v[196:199], v[150:153], v[64:67]
	s_barrier
	s_setprio 0
	s_nop 0
	ds_read_b128 v[64:67], v141 offset:16384
	ds_read_b128 v[72:75], v141 offset:17408
	ds_read_b128 v[76:79], v155 offset:16384
	ds_read_b128 v[80:83], v155 offset:17408
	ds_read_b128 v[84:87], v156 offset:16384
	ds_read_b128 v[186:189], v156 offset:17408
	ds_read_b128 v[190:193], v157 offset:16384
	ds_read_b128 v[196:199], v157 offset:17408
	s_waitcnt vmcnt(4)
	s_setprio 1
	s_barrier
	s_waitcnt lgkmcnt(0)
	v_mfma_f32_16x16x32_bf16 v[60:63], v[64:67], v[128:131], v[60:63]
	v_mfma_f32_16x16x32_bf16 v[52:55], v[76:79], v[128:131], v[52:55]
	v_mfma_f32_16x16x32_bf16 v[44:47], v[84:87], v[128:131], v[44:47]
	v_mfma_f32_16x16x32_bf16 v[36:39], v[190:193], v[128:131], v[36:39]
	v_mfma_f32_16x16x32_bf16 v[32:35], v[190:193], v[146:149], v[32:35]
	v_mfma_f32_16x16x32_bf16 v[60:63], v[72:75], v[132:135], v[60:63]
	v_mfma_f32_16x16x32_bf16 v[56:59], v[64:67], v[146:149], v[56:59]
	v_mfma_f32_16x16x32_bf16 v[52:55], v[80:83], v[132:135], v[52:55]
	v_mfma_f32_16x16x32_bf16 v[48:51], v[76:79], v[146:149], v[48:51]
	v_mfma_f32_16x16x32_bf16 v[44:47], v[186:189], v[132:135], v[44:47]
	v_mfma_f32_16x16x32_bf16 v[40:43], v[84:87], v[146:149], v[40:43]
	v_mfma_f32_16x16x32_bf16 v[36:39], v[196:199], v[132:135], v[36:39]
	v_mfma_f32_16x16x32_bf16 v[32:35], v[196:199], v[162:165], v[32:35]
	v_mfma_f32_16x16x32_bf16 v[216:219], v[72:75], v[162:165], v[56:59]
	v_mfma_f32_16x16x32_bf16 v[220:223], v[80:83], v[162:165], v[48:51]
	v_mfma_f32_16x16x32_bf16 v[224:227], v[186:189], v[162:165], v[40:43]
	s_setprio 0
	s_setprio 1
	v_mfma_f32_16x16x32_bf16 v[28:31], v[64:67], v[200:203], v[28:31]
	v_mfma_f32_16x16x32_bf16 v[24:27], v[64:67], v[212:215], v[24:27]
	v_mfma_f32_16x16x32_bf16 v[20:23], v[76:79], v[200:203], v[20:23]
	v_mfma_f32_16x16x32_bf16 v[16:19], v[76:79], v[212:215], v[16:19]
	v_mfma_f32_16x16x32_bf16 v[4:7], v[190:193], v[200:203], v[4:7]
	v_mfma_f32_16x16x32_bf16 v[28:31], v[72:75], v[208:211], v[28:31]
	v_mfma_f32_16x16x32_bf16 v[24:27], v[72:75], v[150:153], v[24:27]
	v_mfma_f32_16x16x32_bf16 v[20:23], v[80:83], v[208:211], v[20:23]
	v_mfma_f32_16x16x32_bf16 v[16:19], v[80:83], v[150:153], v[16:19]
	v_mfma_f32_16x16x32_bf16 v[12:15], v[84:87], v[200:203], v[12:15]
	v_mfma_f32_16x16x32_bf16 v[8:11], v[84:87], v[212:215], v[8:11]
	v_mfma_f32_16x16x32_bf16 v[4:7], v[196:199], v[208:211], v[4:7]
	v_mfma_f32_16x16x32_bf16 v[0:3], v[190:193], v[212:215], v[0:3]
	v_mfma_f32_16x16x32_bf16 v[146:149], v[186:189], v[208:211], v[12:15]
	v_mfma_f32_16x16x32_bf16 v[162:165], v[186:189], v[150:153], v[8:11]
	v_mfma_f32_16x16x32_bf16 v[150:153], v[196:199], v[150:153], v[0:3]
	s_barrier
	s_setprio 0
	s_nop 2
	ds_read_b128 v[0:3], v145
	ds_read_b128 v[8:11], v145 offset:1024
	ds_read_b128 v[12:15], v145 offset:2048
	ds_read_b128 v[186:189], v145 offset:3072
	ds_read_b128 v[40:43], v141 offset:32768
	ds_read_b128 v[48:51], v141 offset:33792
	ds_read_b128 v[56:59], v155 offset:32768
	ds_read_b128 v[64:67], v155 offset:33792
	ds_read_b128 v[190:193], v156 offset:32768
	ds_read_b128 v[196:199], v156 offset:33792
	ds_read_b128 v[200:203], v157 offset:32768
	ds_read_b128 v[208:211], v157 offset:33792
	s_waitcnt vmcnt(2)
	s_setprio 1
	s_barrier
; #define WAIT_V(n) asm volatile("s_waitcnt vmcnt(" #n ")" ::: "memory")
; #define WAIT_L(n) asm volatile("s_waitcnt lgkmcnt(" #n ")" ::: "memory")
; #define BAR __builtin_amdgcn_s_barrier()
; template <int EPI>
; __device__ __forceinline__ void gemm_tile(const Params& p, const bf16* __restrict__ A, const bf16* __restrict__ Bt, const int K,
;                                           const int nt, const int brow, const int bcol, int pm, int pn) {
;     ...
;   { LDB(B0, 1, 0); LDA(At, 1, 0); WAIT_V(2); BAR; WAIT_L(0); MMA(0, 0, At, B0); BAR;
;     LDB(B1, 1, 1); WAIT_V(0); BAR; WAIT_L(0); MMA(0, 1, At, B1); BAR;
;     LDA(At, 1, 1); BAR; WAIT_L(0); MMA(1, 0, At, B0); MMA(1, 1, At, B1); BAR; }
;   if (wr == 0) BAR;
	s_waitcnt lgkmcnt(0)
	v_mfma_f32_16x16x32_bf16 v[72:75], v[40:43], v[0:3], v[124:127]
	v_mfma_f32_16x16x32_bf16 v[80:83], v[48:51], v[8:11], v[72:75]
	v_mfma_f32_16x16x32_bf16 v[72:75], v[40:43], v[12:15], v[120:123]
	v_mfma_f32_16x16x32_bf16 v[132:135], v[48:51], v[186:189], v[72:75]
	v_mfma_f32_16x16x32_bf16 v[72:75], v[56:59], v[0:3], v[116:119]
	v_mfma_f32_16x16x32_bf16 v[84:87], v[64:67], v[8:11], v[72:75]
	v_mfma_f32_16x16x32_bf16 v[72:75], v[56:59], v[12:15], v[112:115]
	v_mfma_f32_16x16x32_bf16 v[128:131], v[64:67], v[186:189], v[72:75]
	v_mfma_f32_16x16x32_bf16 v[72:75], v[190:193], v[0:3], v[108:111]
	v_mfma_f32_16x16x32_bf16 v[120:123], v[196:199], v[8:11], v[72:75]
	v_mfma_f32_16x16x32_bf16 v[72:75], v[190:193], v[12:15], v[104:107]
	v_mfma_f32_16x16x32_bf16 v[124:127], v[196:199], v[186:189], v[72:75]
	v_mfma_f32_16x16x32_bf16 v[72:75], v[200:203], v[0:3], v[100:103]
	v_mfma_f32_16x16x32_bf16 v[116:119], v[208:211], v[8:11], v[72:75]
	v_mfma_f32_16x16x32_bf16 v[72:75], v[200:203], v[12:15], v[96:99]
	v_mfma_f32_16x16x32_bf16 v[112:115], v[208:211], v[186:189], v[72:75]
	s_barrier
	s_setprio 0
	ds_read_b128 v[96:99], v142
	ds_read_b128 v[100:103], v142 offset:1024
	ds_read_b128 v[212:215], v142 offset:2048
	ds_read_b128 v[142:145], v142 offset:3072
	s_waitcnt vmcnt(0)
	s_setprio 1
	s_barrier
	s_waitcnt lgkmcnt(0)
	v_mfma_f32_16x16x32_bf16 v[72:75], v[40:43], v[96:99], v[92:95]
	v_mfma_f32_16x16x32_bf16 v[40:43], v[40:43], v[212:215], v[88:91]
	v_mfma_f32_16x16x32_bf16 v[108:111], v[48:51], v[142:145], v[40:43]
	v_mfma_f32_16x16x32_bf16 v[40:43], v[56:59], v[96:99], v[166:169]
	v_mfma_f32_16x16x32_bf16 v[76:79], v[64:67], v[100:103], v[40:43]
	v_mfma_f32_16x16x32_bf16 v[40:43], v[56:59], v[212:215], v[170:173]
	v_mfma_f32_16x16x32_bf16 v[104:107], v[64:67], v[142:145], v[40:43]
	v_mfma_f32_16x16x32_bf16 v[40:43], v[190:193], v[96:99], v[174:177]
	v_mfma_f32_16x16x32_bf16 v[92:95], v[196:199], v[100:103], v[40:43]
	v_mfma_f32_16x16x32_bf16 v[40:43], v[190:193], v[212:215], v[178:181]
	v_mfma_f32_16x16x32_bf16 v[64:67], v[196:199], v[142:145], v[40:43]
	v_mfma_f32_16x16x32_bf16 v[40:43], v[200:203], v[96:99], v[68:71]
	v_mfma_f32_16x16x32_bf16 v[88:91], v[208:211], v[100:103], v[40:43]
	v_mfma_f32_16x16x32_bf16 v[40:43], v[200:203], v[212:215], v[182:185]
	v_mfma_f32_16x16x32_bf16 v[72:75], v[48:51], v[100:103], v[72:75]
	v_mfma_f32_16x16x32_bf16 v[68:71], v[208:211], v[142:145], v[40:43]
	s_barrier
	s_setprio 0
	ds_read_b128 v[166:169], v141 offset:49152
	ds_read_b128 v[170:173], v141 offset:50176
	ds_read_b128 v[174:177], v155 offset:49152
	ds_read_b128 v[178:181], v155 offset:50176
	ds_read_b128 v[182:185], v156 offset:49152
	ds_read_b128 v[190:193], v156 offset:50176
	ds_read_b128 v[196:199], v157 offset:49152
	ds_read_b128 v[154:157], v157 offset:50176
	s_setprio 1
	s_barrier
	s_waitcnt lgkmcnt(0)
	v_mfma_f32_16x16x32_bf16 v[40:43], v[166:169], v[0:3], v[60:63]
	v_mfma_f32_16x16x32_bf16 v[56:59], v[170:173], v[8:11], v[40:43]
	v_mfma_f32_16x16x32_bf16 v[40:43], v[166:169], v[12:15], v[216:219]
	v_mfma_f32_16x16x32_bf16 v[60:63], v[170:173], v[186:189], v[40:43]
	v_mfma_f32_16x16x32_bf16 v[40:43], v[174:177], v[0:3], v[52:55]
	v_mfma_f32_16x16x32_bf16 v[48:51], v[178:181], v[8:11], v[40:43]
	v_mfma_f32_16x16x32_bf16 v[40:43], v[174:177], v[12:15], v[220:223]
	v_mfma_f32_16x16x32_bf16 v[52:55], v[178:181], v[186:189], v[40:43]
	v_mfma_f32_16x16x32_bf16 v[40:43], v[182:185], v[0:3], v[44:47]
	v_mfma_f32_16x16x32_bf16 v[0:3], v[196:199], v[0:3], v[36:39]
	v_mfma_f32_16x16x32_bf16 v[44:47], v[182:185], v[12:15], v[224:227]
	v_mfma_f32_16x16x32_bf16 v[36:39], v[154:157], v[8:11], v[0:3]
	v_mfma_f32_16x16x32_bf16 v[0:3], v[196:199], v[12:15], v[32:35]
	v_mfma_f32_16x16x32_bf16 v[40:43], v[190:193], v[8:11], v[40:43]
	v_mfma_f32_16x16x32_bf16 v[44:47], v[190:193], v[186:189], v[44:47]
	v_mfma_f32_16x16x32_bf16 v[32:35], v[154:157], v[186:189], v[0:3]
	s_setprio 0
	s_setprio 1
	v_mfma_f32_16x16x32_bf16 v[0:3], v[166:169], v[96:99], v[28:31]
	v_mfma_f32_16x16x32_bf16 v[8:11], v[170:173], v[100:103], v[0:3]
	v_mfma_f32_16x16x32_bf16 v[0:3], v[166:169], v[212:215], v[24:27]
	v_mfma_f32_16x16x32_bf16 v[28:31], v[170:173], v[142:145], v[0:3]
	v_mfma_f32_16x16x32_bf16 v[0:3], v[174:177], v[96:99], v[20:23]
	v_mfma_f32_16x16x32_bf16 v[12:15], v[178:181], v[100:103], v[0:3]
	v_mfma_f32_16x16x32_bf16 v[0:3], v[174:177], v[212:215], v[16:19]
	v_mfma_f32_16x16x32_bf16 v[24:27], v[178:181], v[142:145], v[0:3]
	v_mfma_f32_16x16x32_bf16 v[0:3], v[182:185], v[96:99], v[146:149]
	v_mfma_f32_16x16x32_bf16 v[4:7], v[196:199], v[96:99], v[4:7]
	v_mfma_f32_16x16x32_bf16 v[20:23], v[190:193], v[100:103], v[0:3]
	v_mfma_f32_16x16x32_bf16 v[0:3], v[182:185], v[212:215], v[162:165]
	v_mfma_f32_16x16x32_bf16 v[16:19], v[154:157], v[100:103], v[4:7]
	v_mfma_f32_16x16x32_bf16 v[4:7], v[196:199], v[212:215], v[150:153]
	v_mfma_f32_16x16x32_bf16 v[0:3], v[190:193], v[142:145], v[0:3]
	v_mfma_f32_16x16x32_bf16 v[4:7], v[154:157], v[142:145], v[4:7]
	s_barrier
	s_setprio 0
	s_cmpk_gt_u32 s94, 0xff
	s_cbranch_scc1 .LBB0_1565
	s_barrier

; #define WAIT_V(n) asm volatile("s_waitcnt vmcnt(" #n ")" ::: "memory")
; #define BAR __builtin_amdgcn_s_barrier()
; template <int EPI>
; __device__ __forceinline__ void gemm_tile(const Params& p, const bf16* __restrict__ A, const bf16* __restrict__ Bt, const int K,
;                                           const int nt, const int brow, const int bcol, int pm, int pn) {
;     ...
;   const int wid = __builtin_amdgcn_readfirstlane(tid >> 6), lane = tid & 63, wr = wid >> 2, wc = wid & 3, fr = lane & 15, fq = lane >> 4;
;   unsigned toff;
;   { int _r, _c; stage_rc(tid * 16, _r, _c); toff = (unsigned)(_r * K + _c) * 2u; }
;   f32x4 acc[2][2][4][2] = {};
;   float pre0 = 0.f, pre1 = 0.f, pre2 = 0.f;
;   if constexpr (EPI == EPI_GU) {
;     const int base = (pm == 65) ? SEQ : 254 * pm - 2;
;     if (tid < 256) pre0 = P_SSQ(p)[max(base + tid, 0)];
;     else if (tid < 384) { const int c = pn * 128 + tid - 256; pre0 = p.w_ffn_conv[c]; pre1 = p.w_ffn_conv[DFF + c]; pre2 = p.w_ffn_conv[2 * DFF + c]; }
;   }
;   bf16x8 At[4][2], B0[2][2], B1[2][2];
;   STAGE(SB(0, 0), Bt, bcol, 0); STAGE(SA(0, 0), A, brow, 0);
;   STAGE(SB(0, 1), Bt, bcol + HALF, 0); STAGE(SA(0, 1), A, brow + HALF, 0);
;   if (wr == 1) BAR;
;   WAIT_V(4); BAR;
;   STAGE(SB(1, 0), Bt, bcol, 1); STAGE(SA(1, 0), A, brow, 1); STAGE(SB(1, 1), Bt, bcol + HALF, 1);
;   WAIT_V(6); BAR;
.LBB0_1703:
	s_add_u32 s96, s4, s68
	v_add_u32_e32 v146, s73, v5
	s_addc_u32 s97, s5, s69
	v_lshl_add_u64 v[6:7], s[96:97], 0, v[128:129]
	v_readfirstlane_b32 s95, v146
	s_add_u32 s94, s4, s94
	v_lshl_add_u64 v[6:7], v[6:7], 0, s[8:9]
	s_mov_b32 m0, s95
	s_addc_u32 s95, s5, s93
	v_add_u32_e32 v147, 0x2000, v146
	s_waitcnt vmcnt(4)
	s_barrier
	global_load_lds_dwordx4 v[6:7], off
	v_lshl_add_u64 v[6:7], s[94:95], 0, v[128:129]
	v_readfirstlane_b32 s93, v147
	s_add_u32 s94, s62, s70
	v_lshl_add_u64 v[6:7], v[6:7], 0, s[8:9]
	s_mov_b32 m0, s93
	s_addc_u32 s95, s63, s71
	v_add_u32_e32 v148, 0x8000, v138
	global_load_lds_dwordx4 v[6:7], off
	v_lshl_add_u64 v[6:7], s[94:95], 0, v[128:129]
	v_readfirstlane_b32 s93, v148
	s_add_u32 s92, s62, s92
	v_lshl_add_u64 v[6:7], v[6:7], 0, s[8:9]
	s_mov_b32 m0, s93
	s_addc_u32 s93, s63, s91
	v_add_u32_e32 v149, 0xa000, v138
	global_load_lds_dwordx4 v[6:7], off
	v_lshl_add_u64 v[6:7], s[92:93], 0, v[128:129]
	v_readfirstlane_b32 s91, v149
	s_add_u32 s90, s4, s90
	v_lshl_add_u64 v[6:7], v[6:7], 0, s[8:9]
	s_mov_b32 m0, s91
	v_add_u32_e32 v150, s74, v5
	s_addc_u32 s91, s5, s89
	global_load_lds_dwordx4 v[6:7], off
	v_lshl_add_u64 v[6:7], s[90:91], 0, v[128:129]
	v_readfirstlane_b32 s89, v150
	s_add_u32 s90, s4, s85
	v_lshl_add_u64 v[6:7], v[6:7], 0, s[8:9]
	s_mov_b32 m0, s89
	s_addc_u32 s91, s5, s84
	v_add_u32_e32 v152, 0x2000, v150
	global_load_lds_dwordx4 v[6:7], off
	v_lshl_add_u64 v[6:7], s[90:91], 0, v[128:129]
	v_readfirstlane_b32 s84, v152
	v_lshl_add_u64 v[6:7], v[6:7], 0, s[8:9]
	s_mov_b32 m0, s84
	s_lshl_b32 s84, s77, 6
	global_load_lds_dwordx4 v[6:7], off
	v_and_b32_e32 v8, 15, v1
	v_and_b32_e32 v9, 48, v1
	v_lshlrev_b32_e32 v6, 2, v1
	s_and_b32 s89, s84, 0x3000
	v_lshlrev_b32_e32 v1, 6, v1
	s_movk_i32 s84, 0x3c0
	v_lshlrev_b32_e32 v5, 6, v8
	v_and_b32_e32 v6, 32, v6
	s_lshl_b32 s90, s88, 13
	v_and_or_b32 v1, v1, s84, v9
	v_bitop3_b32 v5, v5, v6, v9 bitop3:0x36
	v_xad_u32 v6, v1, v6, 16
	s_or_b32 s91, s90, 0x800
	s_or_b32 s92, s90, 0x1000
	s_or_b32 s93, s90, 0x1800
	v_lshrrev_b32_e32 v1, 1, v0
	v_mul_lo_u32 v0, v3, s2
	s_mov_b32 s84, 0x16000
	v_mad_u64_u32 v[0:1], s[84:85], v1, s84, v[0:1]
	s_add_u32 s68, s46, s68
	s_waitcnt vmcnt(6)
	v_or_b32_e32 v0, v0, v2
	s_addc_u32 s69, s47, s69
	v_add_u32_e32 v7, s3, v5
	v_add_u32_e32 v8, s72, v5
	v_add_u32_e32 v10, s73, v5
	v_add_u32_e32 v11, s74, v5
	v_add_u32_e32 v5, 16, v5
	v_add_lshl_u32 v130, v0, v4, 1
	s_add_u32 s70, s46, s70
	v_mov_b32_e32 v0, 0
	v_mov_b32_e32 v131, v129
	s_addc_u32 s71, s47, s71
	s_mov_b32 s88, -2
	v_add_u32_e32 v155, s89, v7
	v_add_u32_e32 v137, s90, v5
	v_add_u32_e32 v136, s91, v6
	v_add_u32_e32 v135, s92, v6
	v_add_u32_e32 v133, s93, v6
	v_add_u32_e32 v154, 0xc000, v138
	v_add_u32_e32 v153, 0xe000, v138
	v_add_u32_e32 v151, s89, v8
	v_add_u32_e32 v145, s89, v10
	v_add_u32_e32 v142, s89, v11
	v_mov_b32_e32 v1, v0
	v_mov_b32_e32 v2, v0
	v_mov_b32_e32 v3, v0
	v_mov_b32_e32 v4, v0
	v_mov_b32_e32 v5, v0
	v_mov_b32_e32 v6, v0
	v_mov_b32_e32 v7, v0
	v_mov_b32_e32 v8, v0
	v_mov_b32_e32 v9, v0
	v_mov_b32_e32 v10, v0
	v_mov_b32_e32 v11, v0
	v_mov_b32_e32 v12, v0
	v_mov_b32_e32 v13, v0
	v_mov_b32_e32 v14, v0
	v_mov_b32_e32 v15, v0
	v_mov_b32_e32 v16, v0
	v_mov_b32_e32 v17, v0
	v_mov_b32_e32 v18, v0
	v_mov_b32_e32 v19, v0
	v_mov_b32_e32 v20, v0
	v_mov_b32_e32 v21, v0
	v_mov_b32_e32 v22, v0
	v_mov_b32_e32 v23, v0
	v_mov_b32_e32 v24, v0
	v_mov_b32_e32 v25, v0
	v_mov_b32_e32 v26, v0
	v_mov_b32_e32 v27, v0
	v_mov_b32_e32 v28, v0
	v_mov_b32_e32 v29, v0
	v_mov_b32_e32 v30, v0
	v_mov_b32_e32 v31, v0
	v_mov_b32_e32 v32, v0
	v_mov_b32_e32 v33, v0
	v_mov_b32_e32 v34, v0
	v_mov_b32_e32 v35, v0
	v_mov_b32_e32 v36, v0
	v_mov_b32_e32 v37, v0
	v_mov_b32_e32 v38, v0
	v_mov_b32_e32 v39, v0
	v_mov_b32_e32 v40, v0
	v_mov_b32_e32 v41, v0
	v_mov_b32_e32 v42, v0
	v_mov_b32_e32 v43, v0
	v_mov_b32_e32 v44, v0
	v_mov_b32_e32 v45, v0
	v_mov_b32_e32 v46, v0
	v_mov_b32_e32 v47, v0
	v_mov_b32_e32 v48, v0
	v_mov_b32_e32 v49, v0
	v_mov_b32_e32 v50, v0
	v_mov_b32_e32 v51, v0
	v_mov_b32_e32 v52, v0
	v_mov_b32_e32 v53, v0
	v_mov_b32_e32 v54, v0
	v_mov_b32_e32 v55, v0
	v_mov_b32_e32 v56, v0
	v_mov_b32_e32 v57, v0
	v_mov_b32_e32 v58, v0
	v_mov_b32_e32 v59, v0
	v_mov_b32_e32 v60, v0
	v_mov_b32_e32 v61, v0
	v_mov_b32_e32 v62, v0
	v_mov_b32_e32 v63, v0
	v_mov_b32_e32 v64, v0
	v_mov_b32_e32 v65, v0
	v_mov_b32_e32 v66, v0
	v_mov_b32_e32 v67, v0
	v_mov_b32_e32 v68, v0
	v_mov_b32_e32 v69, v0
	v_mov_b32_e32 v70, v0
	v_mov_b32_e32 v71, v0
	v_mov_b32_e32 v72, v0
	v_mov_b32_e32 v73, v0
	v_mov_b32_e32 v74, v0
	v_mov_b32_e32 v75, v0
	v_mov_b32_e32 v76, v0
	v_mov_b32_e32 v77, v0
	v_mov_b32_e32 v78, v0
	v_mov_b32_e32 v79, v0
	v_mov_b32_e32 v80, v0
	v_mov_b32_e32 v81, v0
	v_mov_b32_e32 v82, v0
	v_mov_b32_e32 v83, v0
	v_mov_b32_e32 v84, v0
	v_mov_b32_e32 v85, v0
	v_mov_b32_e32 v86, v0
	v_mov_b32_e32 v87, v0
	v_mov_b32_e32 v88, v0
	v_mov_b32_e32 v89, v0
	v_mov_b32_e32 v90, v0
	v_mov_b32_e32 v91, v0
	v_mov_b32_e32 v92, v0
	v_mov_b32_e32 v93, v0
	v_mov_b32_e32 v94, v0
	v_mov_b32_e32 v95, v0
	v_mov_b32_e32 v96, v0
	v_mov_b32_e32 v97, v0
	v_mov_b32_e32 v98, v0
	v_mov_b32_e32 v99, v0
	v_mov_b32_e32 v100, v0
	v_mov_b32_e32 v101, v0
	v_mov_b32_e32 v102, v0
	v_mov_b32_e32 v103, v0
	v_mov_b32_e32 v104, v0
	v_mov_b32_e32 v105, v0
	v_mov_b32_e32 v106, v0
	v_mov_b32_e32 v107, v0
	v_mov_b32_e32 v108, v0
	v_mov_b32_e32 v109, v0
	v_mov_b32_e32 v110, v0
	v_mov_b32_e32 v111, v0
	v_mov_b32_e32 v112, v0
	v_mov_b32_e32 v113, v0
	v_mov_b32_e32 v114, v0
	v_mov_b32_e32 v115, v0
	v_mov_b32_e32 v116, v0
	v_mov_b32_e32 v117, v0
	v_mov_b32_e32 v118, v0
	v_mov_b32_e32 v119, v0
	v_mov_b32_e32 v120, v0
	v_mov_b32_e32 v121, v0
	v_mov_b32_e32 v122, v0
	v_mov_b32_e32 v123, v0
	v_mov_b32_e32 v124, v0
	v_mov_b32_e32 v125, v0
	v_mov_b32_e32 v126, v0
	v_mov_b32_e32 v127, v0
	s_barrier
	v_lshl_add_u64 v[204:205], s[70:71], 0, v[130:131]
	s_mov_b64 s[84:85], 0x12662080
	v_lshl_add_u64 v[246:247], v[204:205], 0, s[84:85]
	s_mov_b64 s[84:85], 0x12712080
	v_lshl_add_u64 v[244:245], v[204:205], 0, s[84:85]
	v_readfirstlane_b32 s99, v154
	v_readfirstlane_b32 s98, v153
	v_readfirstlane_b32 s100, v143
	v_readfirstlane_b32 s101, v144
; #define WAIT_L(n) asm volatile("s_waitcnt lgkmcnt(" #n ")" ::: "memory")
; #define BAR __builtin_amdgcn_s_barrier()
; #define SCHED __builtin_amdgcn_sched_barrier(0)
; template <int EPI>
; __device__ __forceinline__ void gemm_tile(const Params& p, const bf16* __restrict__ A, const bf16* __restrict__ Bt, const int K,
;                                           const int nt, const int brow, const int bcol, int pm, int pn) {
;     ...
;   for (int t = 0; t < nt - 2; t += 2) {
;     LDB(B0, 0, 0); SCHED; LDA(At, 0, 0); STAGE(SA(1, 1), A, brow + HALF, t + 1);
;     WAIT_L(8); BAR; WAIT_L(0); MMA(0, 0, At, B0); BAR; SCHED;
;     LDB(B1, 0, 1); STAGE(SB(0, 0), Bt, bcol, t + 2);
;     BAR; WAIT_L(0); MMA(0, 1, At, B1); BAR;
;     LDA(At, 0, 1); STAGE(SA(0, 0), A, brow, t + 2);
.LBB0_1704:
	ds_read_b128 v[158:161], v155
	ds_read_b128 v[162:165], v155 offset:1024
	ds_read_b128 v[166:169], v155 offset:2048
	ds_read_b128 v[170:173], v155 offset:3072
	s_mov_b32 m0, s99
	ds_read_b128 v[174:177], v137
	ds_read_b128 v[178:181], v137 offset:1024
	ds_read_b128 v[182:185], v136
	ds_read_b128 v[186:189], v136 offset:1024
	ds_read_b128 v[190:193], v135
	ds_read_b128 v[196:199], v135 offset:1024
	ds_read_b128 v[200:203], v133
	ds_read_b128 v[208:211], v133 offset:1024
	global_load_lds_dwordx4 v[246:247], off
	s_mov_b32 m0, s98
	s_nop 0
	global_load_lds_dwordx4 v[244:245], off
	s_waitcnt lgkmcnt(8)
	s_setprio 1
	s_barrier
	s_waitcnt lgkmcnt(0)
	v_mfma_f32_16x16x32_bf16 v[124:127], v[174:177], v[158:161], v[124:127]
	v_mfma_f32_16x16x32_bf16 v[120:123], v[174:177], v[166:169], v[120:123]
	v_mfma_f32_16x16x32_bf16 v[116:119], v[182:185], v[158:161], v[116:119]
	v_mfma_f32_16x16x32_bf16 v[112:115], v[182:185], v[166:169], v[112:115]
	v_mfma_f32_16x16x32_bf16 v[108:111], v[190:193], v[158:161], v[108:111]
	v_mfma_f32_16x16x32_bf16 v[104:107], v[190:193], v[166:169], v[104:107]
	v_mfma_f32_16x16x32_bf16 v[100:103], v[200:203], v[158:161], v[100:103]
	v_mfma_f32_16x16x32_bf16 v[96:99], v[200:203], v[166:169], v[96:99]
	v_mfma_f32_16x16x32_bf16 v[124:127], v[178:181], v[162:165], v[124:127]
	v_mfma_f32_16x16x32_bf16 v[120:123], v[178:181], v[170:173], v[120:123]
	v_mfma_f32_16x16x32_bf16 v[116:119], v[186:189], v[162:165], v[116:119]
	v_mfma_f32_16x16x32_bf16 v[112:115], v[186:189], v[170:173], v[112:115]
	v_mfma_f32_16x16x32_bf16 v[108:111], v[196:199], v[162:165], v[108:111]
	v_mfma_f32_16x16x32_bf16 v[104:107], v[196:199], v[170:173], v[104:107]
	v_mfma_f32_16x16x32_bf16 v[100:103], v[208:211], v[162:165], v[100:103]
	v_mfma_f32_16x16x32_bf16 v[96:99], v[208:211], v[170:173], v[96:99]
	s_barrier
	s_setprio 0
	v_lshl_add_u64 v[228:229], s[68:69], 0, v[130:131]
	s_mov_b64 s[84:85], 0x4c00100
	v_lshl_add_u64 v[230:231], v[228:229], 0, s[84:85]
	v_readfirstlane_b32 s84, v132
	s_mov_b32 m0, s84
	s_mov_b64 s[84:85], 0x4cb0100
	ds_read_b128 v[212:215], v151
	ds_read_b128 v[216:219], v151 offset:1024
	ds_read_b128 v[220:223], v151 offset:2048
	ds_read_b128 v[224:227], v151 offset:3072
	global_load_lds_dwordx4 v[230:231], off
	v_lshl_add_u64 v[230:231], v[228:229], 0, s[84:85]
	v_readfirstlane_b32 s84, v134
	s_mov_b32 m0, s84
	s_nop 0
	global_load_lds_dwordx4 v[230:231], off
	s_mov_b64 s[84:85], 0x12502100
	v_lshl_add_u64 v[230:231], v[204:205], 0, s[84:85]
	v_readfirstlane_b32 s84, v138
	s_mov_b32 m0, s84
	s_mov_b64 s[84:85], 0x125b2100
	s_setprio 1
	s_barrier
	s_waitcnt lgkmcnt(0)
	v_mfma_f32_16x16x32_bf16 v[92:95], v[174:177], v[212:215], v[92:95]
	v_mfma_f32_16x16x32_bf16 v[88:91], v[174:177], v[220:223], v[88:91]
	v_mfma_f32_16x16x32_bf16 v[84:87], v[182:185], v[212:215], v[84:87]
	v_mfma_f32_16x16x32_bf16 v[80:83], v[182:185], v[220:223], v[80:83]
	v_mfma_f32_16x16x32_bf16 v[76:79], v[190:193], v[212:215], v[76:79]
	v_mfma_f32_16x16x32_bf16 v[72:75], v[190:193], v[220:223], v[72:75]
	v_mfma_f32_16x16x32_bf16 v[68:71], v[200:203], v[212:215], v[68:71]
	v_mfma_f32_16x16x32_bf16 v[64:67], v[200:203], v[220:223], v[64:67]
	v_mfma_f32_16x16x32_bf16 v[92:95], v[178:181], v[216:219], v[92:95]
	v_mfma_f32_16x16x32_bf16 v[88:91], v[178:181], v[224:227], v[88:91]
	v_mfma_f32_16x16x32_bf16 v[84:87], v[186:189], v[216:219], v[84:87]
	v_mfma_f32_16x16x32_bf16 v[80:83], v[186:189], v[224:227], v[80:83]
	v_mfma_f32_16x16x32_bf16 v[76:79], v[196:199], v[216:219], v[76:79]
	v_mfma_f32_16x16x32_bf16 v[72:75], v[196:199], v[224:227], v[72:75]
	v_mfma_f32_16x16x32_bf16 v[68:71], v[208:211], v[216:219], v[68:71]
	v_mfma_f32_16x16x32_bf16 v[64:67], v[208:211], v[224:227], v[64:67]
	s_barrier
	s_setprio 0
	ds_read_b128 v[174:177], v137 offset:16384
	ds_read_b128 v[178:181], v137 offset:17408
	ds_read_b128 v[182:185], v136 offset:16384
	ds_read_b128 v[186:189], v136 offset:17408
	ds_read_b128 v[190:193], v135 offset:16384
	ds_read_b128 v[196:199], v135 offset:17408
	ds_read_b128 v[200:203], v133 offset:16384
	ds_read_b128 v[208:211], v133 offset:17408
	global_load_lds_dwordx4 v[230:231], off
	v_lshl_add_u64 v[230:231], v[204:205], 0, s[84:85]
	v_readfirstlane_b32 s84, v139
	s_mov_b32 m0, s84
	s_nop 0
	global_load_lds_dwordx4 v[230:231], off
	s_setprio 1
	s_barrier
	s_waitcnt lgkmcnt(0)
	v_mfma_f32_16x16x32_bf16 v[60:63], v[174:177], v[158:161], v[60:63]
	v_mfma_f32_16x16x32_bf16 v[56:59], v[174:177], v[166:169], v[56:59]
	v_mfma_f32_16x16x32_bf16 v[52:55], v[182:185], v[158:161], v[52:55]
	v_mfma_f32_16x16x32_bf16 v[48:51], v[182:185], v[166:169], v[48:51]
	v_mfma_f32_16x16x32_bf16 v[44:47], v[190:193], v[158:161], v[44:47]
	v_mfma_f32_16x16x32_bf16 v[40:43], v[190:193], v[166:169], v[40:43]
	v_mfma_f32_16x16x32_bf16 v[36:39], v[200:203], v[158:161], v[36:39]
	v_mfma_f32_16x16x32_bf16 v[32:35], v[200:203], v[166:169], v[32:35]
	v_mfma_f32_16x16x32_bf16 v[60:63], v[178:181], v[162:165], v[60:63]
	v_mfma_f32_16x16x32_bf16 v[56:59], v[178:181], v[170:173], v[56:59]
	v_mfma_f32_16x16x32_bf16 v[52:55], v[186:189], v[162:165], v[52:55]
	v_mfma_f32_16x16x32_bf16 v[48:51], v[186:189], v[170:173], v[48:51]
	v_mfma_f32_16x16x32_bf16 v[44:47], v[196:199], v[162:165], v[44:47]
	v_mfma_f32_16x16x32_bf16 v[40:43], v[196:199], v[170:173], v[40:43]
	v_mfma_f32_16x16x32_bf16 v[36:39], v[208:211], v[162:165], v[36:39]
	v_mfma_f32_16x16x32_bf16 v[32:35], v[208:211], v[170:173], v[32:35]
	s_barrier
; #define WAIT_V(n) asm volatile("s_waitcnt vmcnt(" #n ")" ::: "memory")
; #define WAIT_L(n) asm volatile("s_waitcnt lgkmcnt(" #n ")" ::: "memory")
; #define BAR __builtin_amdgcn_s_barrier()
; #define SCHED __builtin_amdgcn_sched_barrier(0)
; template <int EPI>
; __device__ __forceinline__ void gemm_tile(const Params& p, const bf16* __restrict__ A, const bf16* __restrict__ Bt, const int K,
;                                           const int nt, const int brow, const int bcol, int pm, int pn) {
;     ...
;     BAR; WAIT_L(0); MMA(1, 0, At, B0); BAR; SCHED;
;     STAGE(SB(0, 1), Bt, bcol + HALF, t + 2);
;     WAIT_V(6); BAR; MMA(1, 1, At, B1); BAR;
;     LDB(B0, 1, 0); SCHED; LDA(At, 1, 0); STAGE(SA(0, 1), A, brow + HALF, t + 2);
;     WAIT_L(8); BAR; WAIT_L(0); MMA(0, 0, At, B0); BAR; SCHED;
;     LDB(B1, 1, 1); STAGE(SB(1, 0), Bt, bcol, t + 3);
;     BAR; WAIT_L(0); MMA(0, 1, At, B1); BAR;
;     LDA(At, 1, 1); STAGE(SA(1, 0), A, brow, t + 3);
	s_setprio 0
	s_add_i32 s88, s88, 2
	s_add_u32 s68, s68, 0x100
	s_addc_u32 s69, s69, 0
	s_add_u32 s70, s70, 0x100
	s_addc_u32 s71, s71, 0
	s_mov_b64 s[84:85], 0x4d60100
	v_lshl_add_u64 v[158:159], v[228:229], 0, s[84:85]
	v_readfirstlane_b32 s84, v140
	s_mov_b32 m0, s84
	s_mov_b64 s[84:85], 0x4e10100
	global_load_lds_dwordx4 v[158:159], off
	v_lshl_add_u64 v[158:159], v[228:229], 0, s[84:85]
	v_readfirstlane_b32 s84, v141
	s_mov_b32 m0, s84
	s_nop 0
	global_load_lds_dwordx4 v[158:159], off
	s_mov_b64 s[84:85], 0x12662100
	v_lshl_add_u64 v[248:249], v[204:205], 0, s[84:85]
	s_mov_b64 s[84:85], 0x12712100
	v_lshl_add_u64 v[250:251], v[204:205], 0, s[84:85]
	s_waitcnt vmcnt(6)
	s_setprio 1
	s_barrier
	v_mfma_f32_16x16x32_bf16 v[28:31], v[174:177], v[212:215], v[28:31]
	v_mfma_f32_16x16x32_bf16 v[24:27], v[174:177], v[220:223], v[24:27]
	v_mfma_f32_16x16x32_bf16 v[20:23], v[182:185], v[212:215], v[20:23]
	v_mfma_f32_16x16x32_bf16 v[16:19], v[182:185], v[220:223], v[16:19]
	v_mfma_f32_16x16x32_bf16 v[12:15], v[190:193], v[212:215], v[12:15]
	v_mfma_f32_16x16x32_bf16 v[8:11], v[190:193], v[220:223], v[8:11]
	v_mfma_f32_16x16x32_bf16 v[4:7], v[200:203], v[212:215], v[4:7]
	v_mfma_f32_16x16x32_bf16 v[0:3], v[200:203], v[220:223], v[0:3]
	v_mfma_f32_16x16x32_bf16 v[28:31], v[178:181], v[216:219], v[28:31]
	v_mfma_f32_16x16x32_bf16 v[24:27], v[178:181], v[224:227], v[24:27]
	v_mfma_f32_16x16x32_bf16 v[20:23], v[186:189], v[216:219], v[20:23]
	v_mfma_f32_16x16x32_bf16 v[16:19], v[186:189], v[224:227], v[16:19]
	v_mfma_f32_16x16x32_bf16 v[12:15], v[196:199], v[216:219], v[12:15]
	v_mfma_f32_16x16x32_bf16 v[8:11], v[196:199], v[224:227], v[8:11]
	v_mfma_f32_16x16x32_bf16 v[4:7], v[208:211], v[216:219], v[4:7]
	v_mfma_f32_16x16x32_bf16 v[0:3], v[208:211], v[224:227], v[0:3]
	s_barrier
	s_setprio 0
	ds_read_b128 v[158:161], v145
	ds_read_b128 v[162:165], v145 offset:1024
	ds_read_b128 v[166:169], v145 offset:2048
	ds_read_b128 v[170:173], v145 offset:3072
	s_mov_b32 m0, s100
	ds_read_b128 v[174:177], v137 offset:32768
	ds_read_b128 v[178:181], v137 offset:33792
	ds_read_b128 v[182:185], v136 offset:32768
	ds_read_b128 v[186:189], v136 offset:33792
	ds_read_b128 v[190:193], v135 offset:32768
	ds_read_b128 v[196:199], v135 offset:33792
	ds_read_b128 v[200:203], v133 offset:32768
	ds_read_b128 v[208:211], v133 offset:33792
	global_load_lds_dwordx4 v[248:249], off
	s_mov_b32 m0, s101
	s_nop 0
	global_load_lds_dwordx4 v[250:251], off
	s_waitcnt lgkmcnt(8)
	s_setprio 1
	s_barrier
	s_waitcnt lgkmcnt(0)
	v_mfma_f32_16x16x32_bf16 v[124:127], v[174:177], v[158:161], v[124:127]
	v_mfma_f32_16x16x32_bf16 v[120:123], v[174:177], v[166:169], v[120:123]
	v_mfma_f32_16x16x32_bf16 v[116:119], v[182:185], v[158:161], v[116:119]
	v_mfma_f32_16x16x32_bf16 v[112:115], v[182:185], v[166:169], v[112:115]
	v_mfma_f32_16x16x32_bf16 v[108:111], v[190:193], v[158:161], v[108:111]
	v_mfma_f32_16x16x32_bf16 v[104:107], v[190:193], v[166:169], v[104:107]
	v_mfma_f32_16x16x32_bf16 v[100:103], v[200:203], v[158:161], v[100:103]
	v_mfma_f32_16x16x32_bf16 v[96:99], v[200:203], v[166:169], v[96:99]
	v_mfma_f32_16x16x32_bf16 v[124:127], v[178:181], v[162:165], v[124:127]
	v_mfma_f32_16x16x32_bf16 v[120:123], v[178:181], v[170:173], v[120:123]
	v_mfma_f32_16x16x32_bf16 v[116:119], v[186:189], v[162:165], v[116:119]
	v_mfma_f32_16x16x32_bf16 v[112:115], v[186:189], v[170:173], v[112:115]
	v_mfma_f32_16x16x32_bf16 v[108:111], v[196:199], v[162:165], v[108:111]
	v_mfma_f32_16x16x32_bf16 v[104:107], v[196:199], v[170:173], v[104:107]
	v_mfma_f32_16x16x32_bf16 v[100:103], v[208:211], v[162:165], v[100:103]
	v_mfma_f32_16x16x32_bf16 v[96:99], v[208:211], v[170:173], v[96:99]
	s_barrier
	s_setprio 0
	s_mov_b64 s[84:85], 0x4c00180
	v_lshl_add_u64 v[230:231], v[228:229], 0, s[84:85]
	v_readfirstlane_b32 s84, v146
	s_mov_b32 m0, s84
	v_readfirstlane_b32 s84, v147
	ds_read_b128 v[212:215], v142
	ds_read_b128 v[216:219], v142 offset:1024
	ds_read_b128 v[220:223], v142 offset:2048
	ds_read_b128 v[224:227], v142 offset:3072
	global_load_lds_dwordx4 v[230:231], off
	v_lshl_add_u64 v[230:231], v[228:229], 0, s[10:11]
	s_mov_b32 m0, s84
	s_nop 0
	global_load_lds_dwordx4 v[230:231], off
	v_readfirstlane_b32 s84, v148
	v_lshl_add_u64 v[230:231], v[204:205], 0, s[12:13]
	s_mov_b32 m0, s84
	v_readfirstlane_b32 s84, v149
	s_setprio 1
	s_barrier
	s_waitcnt lgkmcnt(0)
	v_mfma_f32_16x16x32_bf16 v[92:95], v[174:177], v[212:215], v[92:95]
	v_mfma_f32_16x16x32_bf16 v[88:91], v[174:177], v[220:223], v[88:91]
	v_mfma_f32_16x16x32_bf16 v[84:87], v[182:185], v[212:215], v[84:87]
	v_mfma_f32_16x16x32_bf16 v[80:83], v[182:185], v[220:223], v[80:83]
	v_mfma_f32_16x16x32_bf16 v[76:79], v[190:193], v[212:215], v[76:79]
	v_mfma_f32_16x16x32_bf16 v[72:75], v[190:193], v[220:223], v[72:75]
	v_mfma_f32_16x16x32_bf16 v[68:71], v[200:203], v[212:215], v[68:71]
	v_mfma_f32_16x16x32_bf16 v[64:67], v[200:203], v[220:223], v[64:67]
	v_mfma_f32_16x16x32_bf16 v[92:95], v[178:181], v[216:219], v[92:95]
	v_mfma_f32_16x16x32_bf16 v[88:91], v[178:181], v[224:227], v[88:91]
	v_mfma_f32_16x16x32_bf16 v[84:87], v[186:189], v[216:219], v[84:87]
	v_mfma_f32_16x16x32_bf16 v[80:83], v[186:189], v[224:227], v[80:83]
	v_mfma_f32_16x16x32_bf16 v[76:79], v[196:199], v[216:219], v[76:79]
	v_mfma_f32_16x16x32_bf16 v[72:75], v[196:199], v[224:227], v[72:75]
	v_mfma_f32_16x16x32_bf16 v[68:71], v[208:211], v[216:219], v[68:71]
	v_mfma_f32_16x16x32_bf16 v[64:67], v[208:211], v[224:227], v[64:67]
	s_barrier
; #define WAIT_V(n) asm volatile("s_waitcnt vmcnt(" #n ")" ::: "memory")
; #define WAIT_L(n) asm volatile("s_waitcnt lgkmcnt(" #n ")" ::: "memory")
; #define BAR __builtin_amdgcn_s_barrier()
; #define SCHED __builtin_amdgcn_sched_barrier(0)
; template <int EPI>
; __device__ __forceinline__ void gemm_tile(const Params& p, const bf16* __restrict__ A, const bf16* __restrict__ Bt, const int K,
;                                           const int nt, const int brow, const int bcol, int pm, int pn) {
;     ...
;     BAR; WAIT_L(0); MMA(1, 0, At, B0); BAR; SCHED;
;     STAGE(SB(1, 1), Bt, bcol + HALF, t + 3);
;     WAIT_V(6); BAR; MMA(1, 1, At, B1); BAR;
;   }
;   { LDB(B0, 0, 0); LDA(At, 0, 0); STAGE(SA(1, 1), A, brow + HALF, nt - 1);
;     BAR; WAIT_L(0); MMA(0, 0, At, B0); BAR;
	s_setprio 0
	ds_read_b128 v[174:177], v137 offset:49152
	ds_read_b128 v[178:181], v137 offset:50176
	ds_read_b128 v[182:185], v136 offset:49152
	ds_read_b128 v[186:189], v136 offset:50176
	ds_read_b128 v[190:193], v135 offset:49152
	ds_read_b128 v[196:199], v135 offset:50176
	ds_read_b128 v[200:203], v133 offset:49152
	ds_read_b128 v[208:211], v133 offset:50176
	global_load_lds_dwordx4 v[230:231], off
	v_lshl_add_u64 v[204:205], v[204:205], 0, s[14:15]
	s_mov_b32 m0, s84
	s_nop 0
	global_load_lds_dwordx4 v[204:205], off
	s_setprio 1
	s_barrier
	s_waitcnt lgkmcnt(0)
	v_mfma_f32_16x16x32_bf16 v[60:63], v[174:177], v[158:161], v[60:63]
	v_mfma_f32_16x16x32_bf16 v[56:59], v[174:177], v[166:169], v[56:59]
	v_mfma_f32_16x16x32_bf16 v[52:55], v[182:185], v[158:161], v[52:55]
	v_mfma_f32_16x16x32_bf16 v[48:51], v[182:185], v[166:169], v[48:51]
	v_mfma_f32_16x16x32_bf16 v[44:47], v[190:193], v[158:161], v[44:47]
	v_mfma_f32_16x16x32_bf16 v[40:43], v[190:193], v[166:169], v[40:43]
	v_mfma_f32_16x16x32_bf16 v[36:39], v[200:203], v[158:161], v[36:39]
	v_mfma_f32_16x16x32_bf16 v[32:35], v[200:203], v[166:169], v[32:35]
	v_mfma_f32_16x16x32_bf16 v[60:63], v[178:181], v[162:165], v[60:63]
	v_mfma_f32_16x16x32_bf16 v[56:59], v[178:181], v[170:173], v[56:59]
	v_mfma_f32_16x16x32_bf16 v[52:55], v[186:189], v[162:165], v[52:55]
	v_mfma_f32_16x16x32_bf16 v[48:51], v[186:189], v[170:173], v[48:51]
	v_mfma_f32_16x16x32_bf16 v[44:47], v[196:199], v[162:165], v[44:47]
	v_mfma_f32_16x16x32_bf16 v[40:43], v[196:199], v[170:173], v[40:43]
	v_mfma_f32_16x16x32_bf16 v[36:39], v[208:211], v[162:165], v[36:39]
	v_mfma_f32_16x16x32_bf16 v[32:35], v[208:211], v[170:173], v[32:35]
	s_barrier
	s_setprio 0
	v_readfirstlane_b32 s84, v150
	v_lshl_add_u64 v[158:159], v[228:229], 0, s[16:17]
	s_mov_b32 m0, s84
	v_readfirstlane_b32 s84, v152
	global_load_lds_dwordx4 v[158:159], off
	v_lshl_add_u64 v[158:159], v[228:229], 0, s[18:19]
	s_mov_b32 m0, s84
	s_nop 0
	global_load_lds_dwordx4 v[158:159], off
	v_lshl_add_u64 v[204:205], s[70:71], 0, v[130:131]
	s_mov_b64 s[84:85], 0x12662080
	v_lshl_add_u64 v[246:247], v[204:205], 0, s[84:85]
	s_mov_b64 s[84:85], 0x12712080
	v_lshl_add_u64 v[244:245], v[204:205], 0, s[84:85]
	s_waitcnt vmcnt(6)
	s_setprio 1
	s_barrier
	v_mfma_f32_16x16x32_bf16 v[28:31], v[174:177], v[212:215], v[28:31]
	v_mfma_f32_16x16x32_bf16 v[24:27], v[174:177], v[220:223], v[24:27]
	v_mfma_f32_16x16x32_bf16 v[20:23], v[182:185], v[212:215], v[20:23]
	v_mfma_f32_16x16x32_bf16 v[16:19], v[182:185], v[220:223], v[16:19]
	v_mfma_f32_16x16x32_bf16 v[12:15], v[190:193], v[212:215], v[12:15]
	v_mfma_f32_16x16x32_bf16 v[8:11], v[190:193], v[220:223], v[8:11]
	v_mfma_f32_16x16x32_bf16 v[4:7], v[200:203], v[212:215], v[4:7]
	v_mfma_f32_16x16x32_bf16 v[0:3], v[200:203], v[220:223], v[0:3]
	v_mfma_f32_16x16x32_bf16 v[28:31], v[178:181], v[216:219], v[28:31]
	v_mfma_f32_16x16x32_bf16 v[24:27], v[178:181], v[224:227], v[24:27]
	v_mfma_f32_16x16x32_bf16 v[20:23], v[186:189], v[216:219], v[20:23]
	v_mfma_f32_16x16x32_bf16 v[16:19], v[186:189], v[224:227], v[16:19]
	v_mfma_f32_16x16x32_bf16 v[12:15], v[196:199], v[216:219], v[12:15]
	v_mfma_f32_16x16x32_bf16 v[8:11], v[196:199], v[224:227], v[8:11]
	v_mfma_f32_16x16x32_bf16 v[4:7], v[208:211], v[216:219], v[4:7]
	v_mfma_f32_16x16x32_bf16 v[0:3], v[208:211], v[224:227], v[0:3]
	s_barrier
	s_setprio 0
	s_cmpk_lt_u32 s88, 0x54
	s_cbranch_scc1 .LBB0_1704
	s_add_u32 s68, s62, s87
	s_addc_u32 s69, s63, s86
	v_lshl_add_u64 v[130:131], s[68:69], 0, v[128:129]
	v_readfirstlane_b32 s68, v154
	s_mov_b32 m0, s68
	s_add_u32 s68, s62, s79
	v_lshl_add_u64 v[130:131], v[130:131], 0, s[20:21]
	s_addc_u32 s69, s63, s78
	ds_read_b128 v[138:141], v155
	ds_read_b128 v[146:149], v155 offset:1024
	ds_read_b128 v[158:161], v155 offset:2048
	ds_read_b128 v[162:165], v155 offset:3072
	ds_read_b128 v[166:169], v137
	ds_read_b128 v[170:173], v137 offset:1024
	ds_read_b128 v[174:177], v136
	ds_read_b128 v[178:181], v136 offset:1024
	ds_read_b128 v[182:185], v135
	ds_read_b128 v[186:189], v135 offset:1024
	ds_read_b128 v[190:193], v133
	ds_read_b128 v[196:199], v133 offset:1024
	global_load_lds_dwordx4 v[130:131], off
	v_lshl_add_u64 v[130:131], s[68:69], 0, v[128:129]
	v_readfirstlane_b32 s68, v153
	v_lshl_add_u64 v[130:131], v[130:131], 0, s[20:21]
	s_mov_b32 m0, s68
	s_nop 0
	global_load_lds_dwordx4 v[130:131], off
	s_setprio 1
	s_barrier
	s_waitcnt lgkmcnt(0)
	v_mfma_f32_16x16x32_bf16 v[124:127], v[166:169], v[138:141], v[124:127]
	v_mfma_f32_16x16x32_bf16 v[120:123], v[166:169], v[158:161], v[120:123]
	v_mfma_f32_16x16x32_bf16 v[116:119], v[174:177], v[138:141], v[116:119]
	v_mfma_f32_16x16x32_bf16 v[108:111], v[182:185], v[138:141], v[108:111]
	v_mfma_f32_16x16x32_bf16 v[124:127], v[170:173], v[146:149], v[124:127]
	v_mfma_f32_16x16x32_bf16 v[120:123], v[170:173], v[162:165], v[120:123]
	v_mfma_f32_16x16x32_bf16 v[116:119], v[178:181], v[146:149], v[116:119]
	v_mfma_f32_16x16x32_bf16 v[112:115], v[174:177], v[158:161], v[112:115]
	v_mfma_f32_16x16x32_bf16 v[108:111], v[186:189], v[146:149], v[108:111]
	v_mfma_f32_16x16x32_bf16 v[104:107], v[182:185], v[158:161], v[104:107]
	v_mfma_f32_16x16x32_bf16 v[100:103], v[190:193], v[138:141], v[100:103]
	v_mfma_f32_16x16x32_bf16 v[96:99], v[190:193], v[158:161], v[96:99]
	v_mfma_f32_16x16x32_bf16 v[152:155], v[178:181], v[162:165], v[112:115]
	v_mfma_f32_16x16x32_bf16 v[200:203], v[186:189], v[162:165], v[104:107]
	v_mfma_f32_16x16x32_bf16 v[208:211], v[196:199], v[146:149], v[100:103]
	v_mfma_f32_16x16x32_bf16 v[212:215], v[196:199], v[162:165], v[96:99]
	s_barrier
; #define WAIT_V(n) asm volatile("s_waitcnt vmcnt(" #n ")" ::: "memory")
; #define WAIT_L(n) asm volatile("s_waitcnt lgkmcnt(" #n ")" ::: "memory")
; #define BAR __builtin_amdgcn_s_barrier()
; template <int EPI>
; __device__ __forceinline__ void gemm_tile(const Params& p, const bf16* __restrict__ A, const bf16* __restrict__ Bt, const int K,
;                                           const int nt, const int brow, const int bcol, int pm, int pn) {
;     ...
;     LDB(B1, 0, 1); BAR; WAIT_L(0); MMA(0, 1, At, B1); BAR;
;     LDA(At, 0, 1); WAIT_V(4); BAR; WAIT_L(0); MMA(1, 0, At, B0); MMA(1, 1, At, B1); BAR; }
;   { LDB(B0, 1, 0); LDA(At, 1, 0); WAIT_V(2); BAR; WAIT_L(0); MMA(0, 0, At, B0); BAR;
;     LDB(B1, 1, 1); WAIT_V(0); BAR; WAIT_L(0); MMA(0, 1, At, B1); BAR;
	s_setprio 0
	s_nop 1
	ds_read_b128 v[96:99], v151
	ds_read_b128 v[100:103], v151 offset:1024
	ds_read_b128 v[104:107], v151 offset:2048
	ds_read_b128 v[112:115], v151 offset:3072
	s_setprio 1
	s_barrier
	s_waitcnt lgkmcnt(0)
	v_mfma_f32_16x16x32_bf16 v[92:95], v[166:169], v[96:99], v[92:95]
	v_mfma_f32_16x16x32_bf16 v[88:91], v[166:169], v[104:107], v[88:91]
	v_mfma_f32_16x16x32_bf16 v[84:87], v[174:177], v[96:99], v[84:87]
	v_mfma_f32_16x16x32_bf16 v[76:79], v[182:185], v[96:99], v[76:79]
	v_mfma_f32_16x16x32_bf16 v[92:95], v[170:173], v[100:103], v[92:95]
	v_mfma_f32_16x16x32_bf16 v[88:91], v[170:173], v[112:115], v[88:91]
	v_mfma_f32_16x16x32_bf16 v[84:87], v[178:181], v[100:103], v[84:87]
	v_mfma_f32_16x16x32_bf16 v[80:83], v[174:177], v[104:107], v[80:83]
	v_mfma_f32_16x16x32_bf16 v[76:79], v[186:189], v[100:103], v[76:79]
	v_mfma_f32_16x16x32_bf16 v[72:75], v[182:185], v[104:107], v[72:75]
	v_mfma_f32_16x16x32_bf16 v[68:71], v[190:193], v[96:99], v[68:71]
	v_mfma_f32_16x16x32_bf16 v[64:67], v[190:193], v[104:107], v[64:67]
	v_mfma_f32_16x16x32_bf16 v[166:169], v[178:181], v[112:115], v[80:83]
	v_mfma_f32_16x16x32_bf16 v[170:173], v[186:189], v[112:115], v[72:75]
	v_mfma_f32_16x16x32_bf16 v[174:177], v[196:199], v[100:103], v[68:71]
	v_mfma_f32_16x16x32_bf16 v[178:181], v[196:199], v[112:115], v[64:67]
	s_barrier
	s_setprio 0
	s_nop 1
	ds_read_b128 v[64:67], v137 offset:16384
	ds_read_b128 v[68:71], v137 offset:17408
	ds_read_b128 v[72:75], v136 offset:16384
	ds_read_b128 v[80:83], v136 offset:17408
	ds_read_b128 v[182:185], v135 offset:16384
	ds_read_b128 v[186:189], v135 offset:17408
	ds_read_b128 v[190:193], v133 offset:16384
	ds_read_b128 v[196:199], v133 offset:17408
	s_waitcnt vmcnt(4)
	s_setprio 1
	s_barrier
	s_waitcnt lgkmcnt(0)
	v_mfma_f32_16x16x32_bf16 v[60:63], v[64:67], v[138:141], v[60:63]
	v_mfma_f32_16x16x32_bf16 v[56:59], v[64:67], v[158:161], v[56:59]
	v_mfma_f32_16x16x32_bf16 v[52:55], v[72:75], v[138:141], v[52:55]
	v_mfma_f32_16x16x32_bf16 v[44:47], v[182:185], v[138:141], v[44:47]
	v_mfma_f32_16x16x32_bf16 v[60:63], v[68:71], v[146:149], v[60:63]
	v_mfma_f32_16x16x32_bf16 v[56:59], v[68:71], v[162:165], v[56:59]
	v_mfma_f32_16x16x32_bf16 v[52:55], v[80:83], v[146:149], v[52:55]
	v_mfma_f32_16x16x32_bf16 v[48:51], v[72:75], v[158:161], v[48:51]
	v_mfma_f32_16x16x32_bf16 v[44:47], v[186:189], v[146:149], v[44:47]
	v_mfma_f32_16x16x32_bf16 v[40:43], v[182:185], v[158:161], v[40:43]
	v_mfma_f32_16x16x32_bf16 v[36:39], v[190:193], v[138:141], v[36:39]
	v_mfma_f32_16x16x32_bf16 v[32:35], v[190:193], v[158:161], v[32:35]
	v_mfma_f32_16x16x32_bf16 v[216:219], v[80:83], v[162:165], v[48:51]
	v_mfma_f32_16x16x32_bf16 v[220:223], v[186:189], v[162:165], v[40:43]
	v_mfma_f32_16x16x32_bf16 v[138:141], v[196:199], v[146:149], v[36:39]
	v_mfma_f32_16x16x32_bf16 v[146:149], v[196:199], v[162:165], v[32:35]
	s_setprio 0
	s_setprio 1
	v_mfma_f32_16x16x32_bf16 v[28:31], v[64:67], v[96:99], v[28:31]
	v_mfma_f32_16x16x32_bf16 v[24:27], v[64:67], v[104:107], v[24:27]
	v_mfma_f32_16x16x32_bf16 v[20:23], v[72:75], v[96:99], v[20:23]
	v_mfma_f32_16x16x32_bf16 v[12:15], v[182:185], v[96:99], v[12:15]
	v_mfma_f32_16x16x32_bf16 v[28:31], v[68:71], v[100:103], v[28:31]
	v_mfma_f32_16x16x32_bf16 v[24:27], v[68:71], v[112:115], v[24:27]
	v_mfma_f32_16x16x32_bf16 v[20:23], v[80:83], v[100:103], v[20:23]
	v_mfma_f32_16x16x32_bf16 v[16:19], v[72:75], v[104:107], v[16:19]
	v_mfma_f32_16x16x32_bf16 v[12:15], v[186:189], v[100:103], v[12:15]
	v_mfma_f32_16x16x32_bf16 v[8:11], v[182:185], v[104:107], v[8:11]
	v_mfma_f32_16x16x32_bf16 v[4:7], v[190:193], v[96:99], v[4:7]
	v_mfma_f32_16x16x32_bf16 v[0:3], v[190:193], v[104:107], v[0:3]
	v_mfma_f32_16x16x32_bf16 v[158:161], v[80:83], v[112:115], v[16:19]
	v_mfma_f32_16x16x32_bf16 v[162:165], v[186:189], v[112:115], v[8:11]
	v_mfma_f32_16x16x32_bf16 v[182:185], v[196:199], v[100:103], v[4:7]
	v_mfma_f32_16x16x32_bf16 v[186:189], v[196:199], v[112:115], v[0:3]
	s_barrier
	s_setprio 0
	s_nop 1
	ds_read_b128 v[0:3], v145
	ds_read_b128 v[4:7], v145 offset:1024
	ds_read_b128 v[8:11], v145 offset:2048
	ds_read_b128 v[16:19], v145 offset:3072
	ds_read_b128 v[32:35], v137 offset:32768
	ds_read_b128 v[36:39], v137 offset:33792
	ds_read_b128 v[40:43], v136 offset:32768
	ds_read_b128 v[48:51], v136 offset:33792
	ds_read_b128 v[190:193], v135 offset:32768
	ds_read_b128 v[196:199], v135 offset:33792
	ds_read_b128 v[224:227], v133 offset:32768
	ds_read_b128 v[228:231], v133 offset:33792
	s_waitcnt vmcnt(2)
	s_setprio 1
	s_barrier
; #define WAIT_V(n) asm volatile("s_waitcnt vmcnt(" #n ")" ::: "memory")
; #define WAIT_L(n) asm volatile("s_waitcnt lgkmcnt(" #n ")" ::: "memory")
; #define BAR __builtin_amdgcn_s_barrier()
; template <int EPI>
; __device__ __forceinline__ void gemm_tile(const Params& p, const bf16* __restrict__ A, const bf16* __restrict__ Bt, const int K,
;                                           const int nt, const int brow, const int bcol, int pm, int pn) {
;     ...
;   { LDB(B0, 1, 0); LDA(At, 1, 0); WAIT_V(2); BAR; WAIT_L(0); MMA(0, 0, At, B0); BAR;
;     LDB(B1, 1, 1); WAIT_V(0); BAR; WAIT_L(0); MMA(0, 1, At, B1); BAR;
;     LDA(At, 1, 1); BAR; WAIT_L(0); MMA(1, 0, At, B0); MMA(1, 1, At, B1); BAR; }
;   if (wr == 0) BAR;
; template <int EPI>
; __device__ __forceinline__ void gemm_phase(const Params& p, const bf16* A, const bf16* Bt, int K, int nM, int nN) {
;     ...
;   for (int t = blockIdx.x; t < ntile; t += gridDim.x) {
;     int pm, pn;
;     tile_map(t, nM, nN, pm, pn);
;     int brow;
;     if constexpr (EPI == EPI_GU) brow = (pm == 65) ? SEQ : 254 * pm - 2;
;     else brow = pm * BM;
;     gemm_tile<EPI>(p, A, Bt, K, K / BK, brow, pn * BM, pm, pn);
	s_waitcnt lgkmcnt(0)
	v_mfma_f32_16x16x32_bf16 v[64:67], v[32:35], v[0:3], v[124:127]
	v_mfma_f32_16x16x32_bf16 v[96:99], v[36:39], v[4:7], v[64:67]
	v_mfma_f32_16x16x32_bf16 v[64:67], v[32:35], v[8:11], v[120:123]
	v_mfma_f32_16x16x32_bf16 v[112:115], v[36:39], v[16:19], v[64:67]
	v_mfma_f32_16x16x32_bf16 v[64:67], v[40:43], v[0:3], v[116:119]
	v_mfma_f32_16x16x32_bf16 v[100:103], v[48:51], v[4:7], v[64:67]
	v_mfma_f32_16x16x32_bf16 v[64:67], v[40:43], v[8:11], v[152:155]
	v_mfma_f32_16x16x32_bf16 v[116:119], v[48:51], v[16:19], v[64:67]
	v_mfma_f32_16x16x32_bf16 v[64:67], v[190:193], v[0:3], v[108:111]
	v_mfma_f32_16x16x32_bf16 v[104:107], v[196:199], v[4:7], v[64:67]
	v_mfma_f32_16x16x32_bf16 v[64:67], v[190:193], v[8:11], v[200:203]
	v_mfma_f32_16x16x32_bf16 v[120:123], v[196:199], v[16:19], v[64:67]
	v_mfma_f32_16x16x32_bf16 v[64:67], v[224:227], v[0:3], v[208:211]
	v_mfma_f32_16x16x32_bf16 v[108:111], v[228:231], v[4:7], v[64:67]
	v_mfma_f32_16x16x32_bf16 v[64:67], v[224:227], v[8:11], v[212:215]
	v_mfma_f32_16x16x32_bf16 v[124:127], v[228:231], v[16:19], v[64:67]
	s_barrier
	s_setprio 0
	ds_read_b128 v[150:153], v142
	ds_read_b128 v[200:203], v142 offset:1024
	ds_read_b128 v[208:211], v142 offset:2048
	ds_read_b128 v[142:145], v142 offset:3072
	s_waitcnt vmcnt(0)
	s_setprio 1
	s_barrier
	s_waitcnt lgkmcnt(0)
	v_mfma_f32_16x16x32_bf16 v[64:67], v[32:35], v[150:153], v[92:95]
	v_mfma_f32_16x16x32_bf16 v[32:35], v[32:35], v[208:211], v[88:91]
	v_mfma_f32_16x16x32_bf16 v[80:83], v[36:39], v[142:145], v[32:35]
	v_mfma_f32_16x16x32_bf16 v[32:35], v[40:43], v[150:153], v[84:87]
	v_mfma_f32_16x16x32_bf16 v[68:71], v[48:51], v[200:203], v[32:35]
	v_mfma_f32_16x16x32_bf16 v[32:35], v[40:43], v[208:211], v[166:169]
	v_mfma_f32_16x16x32_bf16 v[84:87], v[48:51], v[142:145], v[32:35]
	v_mfma_f32_16x16x32_bf16 v[32:35], v[190:193], v[150:153], v[76:79]
	v_mfma_f32_16x16x32_bf16 v[72:75], v[196:199], v[200:203], v[32:35]
	v_mfma_f32_16x16x32_bf16 v[32:35], v[190:193], v[208:211], v[170:173]
	v_mfma_f32_16x16x32_bf16 v[88:91], v[196:199], v[142:145], v[32:35]
	v_mfma_f32_16x16x32_bf16 v[32:35], v[224:227], v[150:153], v[174:177]
	v_mfma_f32_16x16x32_bf16 v[76:79], v[228:231], v[200:203], v[32:35]
	v_mfma_f32_16x16x32_bf16 v[32:35], v[224:227], v[208:211], v[178:181]
	v_mfma_f32_16x16x32_bf16 v[64:67], v[36:39], v[200:203], v[64:67]
	v_mfma_f32_16x16x32_bf16 v[92:95], v[228:231], v[142:145], v[32:35]
	s_barrier
	s_setprio 0
	ds_read_b128 v[166:169], v137 offset:49152
	ds_read_b128 v[170:173], v137 offset:50176
	ds_read_b128 v[174:177], v136 offset:49152
	ds_read_b128 v[178:181], v136 offset:50176
	ds_read_b128 v[190:193], v135 offset:49152
	ds_read_b128 v[134:137], v135 offset:50176
	ds_read_b128 v[196:199], v133 offset:49152
	ds_read_b128 v[130:133], v133 offset:50176
	s_setprio 1
	s_barrier
	s_waitcnt lgkmcnt(0)
	v_mfma_f32_16x16x32_bf16 v[36:39], v[166:169], v[8:11], v[56:59]
	v_mfma_f32_16x16x32_bf16 v[40:43], v[174:177], v[8:11], v[216:219]
	v_mfma_f32_16x16x32_bf16 v[32:35], v[166:169], v[0:3], v[60:63]
	v_mfma_f32_16x16x32_bf16 v[48:51], v[170:173], v[16:19], v[36:39]
	v_mfma_f32_16x16x32_bf16 v[36:39], v[174:177], v[0:3], v[52:55]
	v_mfma_f32_16x16x32_bf16 v[52:55], v[178:181], v[16:19], v[40:43]
	v_mfma_f32_16x16x32_bf16 v[40:43], v[190:193], v[0:3], v[44:47]
	v_mfma_f32_16x16x32_bf16 v[44:47], v[190:193], v[8:11], v[220:223]
	v_mfma_f32_16x16x32_bf16 v[0:3], v[196:199], v[0:3], v[138:141]
	v_mfma_f32_16x16x32_bf16 v[56:59], v[134:137], v[16:19], v[44:47]
	v_mfma_f32_16x16x32_bf16 v[44:47], v[130:133], v[4:7], v[0:3]
	v_mfma_f32_16x16x32_bf16 v[0:3], v[196:199], v[8:11], v[146:149]
	v_mfma_f32_16x16x32_bf16 v[32:35], v[170:173], v[4:7], v[32:35]
	v_mfma_f32_16x16x32_bf16 v[36:39], v[178:181], v[4:7], v[36:39]
	v_mfma_f32_16x16x32_bf16 v[40:43], v[134:137], v[4:7], v[40:43]
	v_mfma_f32_16x16x32_bf16 v[60:63], v[130:133], v[16:19], v[0:3]
	s_setprio 0
	s_setprio 1
	v_mfma_f32_16x16x32_bf16 v[4:7], v[166:169], v[208:211], v[24:27]
	v_mfma_f32_16x16x32_bf16 v[8:11], v[174:177], v[208:211], v[158:161]
	v_mfma_f32_16x16x32_bf16 v[16:19], v[170:173], v[142:145], v[4:7]
	v_mfma_f32_16x16x32_bf16 v[4:7], v[174:177], v[150:153], v[20:23]
	v_mfma_f32_16x16x32_bf16 v[20:23], v[178:181], v[142:145], v[8:11]
	v_mfma_f32_16x16x32_bf16 v[8:11], v[190:193], v[150:153], v[12:15]
	v_mfma_f32_16x16x32_bf16 v[12:15], v[190:193], v[208:211], v[162:165]
	v_mfma_f32_16x16x32_bf16 v[0:3], v[166:169], v[150:153], v[28:31]
	v_mfma_f32_16x16x32_bf16 v[24:27], v[134:137], v[142:145], v[12:15]
	v_mfma_f32_16x16x32_bf16 v[12:15], v[196:199], v[150:153], v[182:185]
	v_mfma_f32_16x16x32_bf16 v[28:31], v[196:199], v[208:211], v[186:189]
	v_mfma_f32_16x16x32_bf16 v[0:3], v[170:173], v[200:203], v[0:3]
	v_mfma_f32_16x16x32_bf16 v[4:7], v[178:181], v[200:203], v[4:7]
	v_mfma_f32_16x16x32_bf16 v[8:11], v[134:137], v[200:203], v[8:11]
	v_mfma_f32_16x16x32_bf16 v[12:15], v[130:133], v[200:203], v[12:15]
	v_mfma_f32_16x16x32_bf16 v[28:31], v[130:133], v[142:145], v[28:31]
	s_barrier
	s_setprio 0
	s_cmpk_gt_u32 s77, 0xff
	s_cbranch_scc1 .LBB0_1696
	s_barrier
	s_branch .LBB0_1696

; __global__ void __launch_bounds__(512, 2) fwd_megakernel(Params p) {
;   if (p.use_cg) cg::this_grid().sync();
;     ...
;   phase_prep(p);
;   xcd_barrier(xb);
;   if (blockIdx.x >= 24 && (blockIdx.x & 1)) convert_w_o_gu(p, 24, gridDim.x - 24);
;   if (blockIdx.x < 24) gemm_tile<EPI_PROJ>(p, P_HBUF(p), P_WINT(p), DM, DM / BK, SEQ, blockIdx.x * BM, 64, blockIdx.x);
;   gemm_phase<EPI_PROJ>(p, P_HBUF(p), P_WINT(p), DM, 64, 24);
;   if (blockIdx.x >= 24 && !(blockIdx.x & 1)) convert_w_o_gu(p, 24, gridDim.x - 24);
;   xcd_barrier(xb);
;   phase_mixer(p);
;   xcd_barrier(xb);
;   gemm_phase<EPI_WO>(p, P_MIX(p), P_WOT(p), DM, 65, 8);
;   if (blockIdx.x >= 8) convert_w_down(p, 8, gridDim.x - 8);
;   xcd_barrier(xb);
;   gemm_phase<EPI_GU>(p, P_HBUF(p), P_WGUT(p), DM, 66, 44);
;   xcd_barrier(xb);
;   if (blockIdx.x < 8 * DSK) {
;     const int pn = blockIdx.x / DSK, ks = blockIdx.x % DSK;
;     gemm_tile<EPI_DOWN_ATOMIC>(p, P_ACT(p) + ks * 512, P_WDT(p) + ks * 512, DFF, 512 / BK, SEQ, pn * BM, 64 + ks, pn);
;   }
;   gemm_phase<EPI_DOWN>(p, P_ACT(p), P_WDT(p), DFF, 64, 8);
;   xcd_barrier(xb);
;   phase_final(p);
; }
	.amdhsa_kernel _Z14fwd_megakernel6Params
		.amdhsa_group_segment_fixed_size 16
		.amdhsa_private_segment_fixed_size 0
		.amdhsa_kernarg_size 416
		.amdhsa_user_sgpr_count 2
		.amdhsa_user_sgpr_dispatch_ptr 0
		.amdhsa_user_sgpr_queue_ptr 0
		.amdhsa_user_sgpr_kernarg_segment_ptr 1
		.amdhsa_user_sgpr_dispatch_id 0
		.amdhsa_user_sgpr_kernarg_preload_length 0
		.amdhsa_user_sgpr_kernarg_preload_offset 0
		.amdhsa_user_sgpr_private_segment_size 0
		.amdhsa_uses_dynamic_stack 0
		.amdhsa_enable_private_segment 0
		.amdhsa_system_sgpr_workgroup_id_x 1
		.amdhsa_system_sgpr_workgroup_id_y 0
		.amdhsa_system_sgpr_workgroup_id_z 0
		.amdhsa_system_sgpr_workgroup_info 0
		.amdhsa_system_vgpr_workitem_id 2
		.amdhsa_next_free_vgpr 252
		.amdhsa_next_free_sgpr 102
		.amdhsa_accum_offset 252
		.amdhsa_reserve_vcc 1
		.amdhsa_float_round_mode_32 0
		.amdhsa_float_round_mode_16_64 0
		.amdhsa_float_denorm_mode_32 3
		.amdhsa_float_denorm_mode_16_64 3
		.amdhsa_dx10_clamp 1
		.amdhsa_ieee_mode 1
		.amdhsa_fp16_overflow 0
		.amdhsa_tg_split 0
		.amdhsa_exception_fp_ieee_invalid_op 0
		.amdhsa_exception_fp_denorm_src 0
		.amdhsa_exception_fp_ieee_div_zero 0
		.amdhsa_exception_fp_ieee_overflow 0
		.amdhsa_exception_fp_ieee_underflow 0
		.amdhsa_exception_fp_ieee_inexact 0
		.amdhsa_exception_int_div_zero 0
	.end_amdhsa_kernel

; __global__ void __launch_bounds__(512, 2) fwd_megakernel(Params p) {
;   if (p.use_cg) cg::this_grid().sync();
;     ...
;   phase_prep(p);
;   xcd_barrier(xb);
;   if (blockIdx.x >= 24 && (blockIdx.x & 1)) convert_w_o_gu(p, 24, gridDim.x - 24);
;   if (blockIdx.x < 24) gemm_tile<EPI_PROJ>(p, P_HBUF(p), P_WINT(p), DM, DM / BK, SEQ, blockIdx.x * BM, 64, blockIdx.x);
;   gemm_phase<EPI_PROJ>(p, P_HBUF(p), P_WINT(p), DM, 64, 24);
;   if (blockIdx.x >= 24 && !(blockIdx.x & 1)) convert_w_o_gu(p, 24, gridDim.x - 24);
;   xcd_barrier(xb);
;   phase_mixer(p);
;   xcd_barrier(xb);
;   gemm_phase<EPI_WO>(p, P_MIX(p), P_WOT(p), DM, 65, 8);
;   if (blockIdx.x >= 8) convert_w_down(p, 8, gridDim.x - 8);
;   xcd_barrier(xb);
;   gemm_phase<EPI_GU>(p, P_HBUF(p), P_WGUT(p), DM, 66, 44);
;   xcd_barrier(xb);
;   if (blockIdx.x < 8 * DSK) {
;     const int pn = blockIdx.x / DSK, ks = blockIdx.x % DSK;
;     gemm_tile<EPI_DOWN_ATOMIC>(p, P_ACT(p) + ks * 512, P_WDT(p) + ks * 512, DFF, 512 / BK, SEQ, pn * BM, 64 + ks, pn);
;   }
;   gemm_phase<EPI_DOWN>(p, P_ACT(p), P_WDT(p), DFF, 64, 8);
;   xcd_barrier(xb);
;   phase_final(p);
; }
amdhsa.kernels:
  - .agpr_count:     0
    .args:
      - .offset:         0
        .size:           160
        .value_kind:     by_value
      - .offset:         160
        .size:           4
        .value_kind:     hidden_block_count_x
      - .offset:         164
        .size:           4
        .value_kind:     hidden_block_count_y
      - .offset:         168
        .size:           4
        .value_kind:     hidden_block_count_z
      - .offset:         172
        .size:           2
        .value_kind:     hidden_group_size_x
      - .offset:         174
        .size:           2
        .value_kind:     hidden_group_size_y
      - .offset:         176
        .size:           2
        .value_kind:     hidden_group_size_z
      - .offset:         178
        .size:           2
        .value_kind:     hidden_remainder_x
      - .offset:         180
        .size:           2
        .value_kind:     hidden_remainder_y
      - .offset:         182
        .size:           2
        .value_kind:     hidden_remainder_z
      - .offset:         200
        .size:           8
        .value_kind:     hidden_global_offset_x
      - .offset:         208
        .size:           8
        .value_kind:     hidden_global_offset_y
      - .offset:         216
        .size:           8
        .value_kind:     hidden_global_offset_z
      - .offset:         224
        .size:           2
        .value_kind:     hidden_grid_dims
      - .offset:         248
        .size:           8
        .value_kind:     hidden_multigrid_sync_arg
      - .offset:         280
        .size:           4
        .value_kind:     hidden_dynamic_lds_size
    .group_segment_fixed_size: 16
    .kernarg_segment_align: 8
    .kernarg_segment_size: 416
    .language:       OpenCL C
    .language_version:
      - 2
      - 0
    .max_flat_workgroup_size: 512
    .name:           _Z14fwd_megakernel6Params
    .private_segment_fixed_size: 0
    .sgpr_count:     108
    .sgpr_spill_count: 8
    .symbol:         _Z14fwd_megakernel6Params.kd
    .uniform_work_group_size: 1
    .uses_dynamic_stack: false
    .vgpr_count:     252
    .vgpr_spill_count: 0
    .wavefront_size: 64
